# rotated GEMM k-loops: ds_reads issued first after each barrier, prefetch global loads moved into the first MFMA group's shadow, on top of v_rot
# baseline (speedup 1.0000x reference)
.LBB0_208:
	ds_read_b128 v[204:207], v178 offset:32768
	ds_read_b128 v[208:211], v178 offset:33792
	ds_read_b128 v[212:215], v178 offset:34816
	ds_read_b128 v[216:219], v178 offset:35840
	ds_read_b128 v[222:225], v176
	ds_read_b128 v[226:229], v176 offset:1024
	ds_read_b128 v[230:233], v176 offset:2048
	ds_read_b128 v[234:237], v176 offset:3072
	ds_read_b128 v[238:241], v176 offset:4096
	ds_read_b128 v[242:245], v176 offset:5120
	ds_read_b128 v[246:249], v176 offset:6144
	ds_read_b128 v[250:253], v176 offset:7168
	s_setprio 1
	s_waitcnt lgkmcnt(7)
	v_mfma_f32_16x16x32_bf16 v[124:127], v[222:225], v[204:207], v[124:127]
	v_mfma_f32_16x16x32_bf16 v[120:123], v[222:225], v[208:211], v[120:123]
	v_mfma_f32_16x16x32_bf16 v[60:63], v[222:225], v[212:215], v[60:63]
	v_mfma_f32_16x16x32_bf16 v[56:59], v[222:225], v[216:219], v[56:59]
	global_load_dwordx4 v[180:183], v[180:181], off
	global_load_dwordx4 v[184:187], v[184:185], off
	global_load_dwordx4 v[188:191], v[188:189], off
	global_load_dwordx4 v[192:195], v[192:193], off
	global_load_dwordx4 v[196:199], v[196:197], off
	global_load_dwordx4 v[200:203], v[200:201], off
	s_waitcnt vmcnt(11)
	ds_write_b128 v152, v[128:131] offset:16384
	s_waitcnt lgkmcnt(7)
	v_mfma_f32_16x16x32_bf16 v[116:119], v[226:229], v[204:207], v[116:119]
	v_mfma_f32_16x16x32_bf16 v[112:115], v[226:229], v[208:211], v[112:115]
	v_mfma_f32_16x16x32_bf16 v[52:55], v[226:229], v[212:215], v[52:55]
	v_mfma_f32_16x16x32_bf16 v[48:51], v[226:229], v[216:219], v[48:51]
	s_waitcnt vmcnt(9)
	ds_write_b128 v152, v[136:139] offset:20480
	s_waitcnt lgkmcnt(7)
	v_mfma_f32_16x16x32_bf16 v[108:111], v[230:233], v[204:207], v[108:111]
	v_mfma_f32_16x16x32_bf16 v[104:107], v[230:233], v[208:211], v[104:107]
	v_mfma_f32_16x16x32_bf16 v[44:47], v[230:233], v[212:215], v[44:47]
	v_mfma_f32_16x16x32_bf16 v[40:43], v[230:233], v[216:219], v[40:43]
	s_waitcnt vmcnt(8)
	ds_write_b128 v152, v[140:143] offset:24576
	s_waitcnt lgkmcnt(7)
	v_mfma_f32_16x16x32_bf16 v[100:103], v[234:237], v[204:207], v[100:103]
	v_mfma_f32_16x16x32_bf16 v[96:99], v[234:237], v[208:211], v[96:99]
	v_mfma_f32_16x16x32_bf16 v[36:39], v[234:237], v[212:215], v[36:39]
	v_mfma_f32_16x16x32_bf16 v[32:35], v[234:237], v[216:219], v[32:35]
	s_waitcnt vmcnt(7)
	ds_write_b128 v152, v[144:147] offset:28672
	s_waitcnt lgkmcnt(7)
	v_mfma_f32_16x16x32_bf16 v[92:95], v[238:241], v[204:207], v[92:95]
	v_mfma_f32_16x16x32_bf16 v[88:91], v[238:241], v[208:211], v[88:91]
	v_mfma_f32_16x16x32_bf16 v[28:31], v[238:241], v[212:215], v[28:31]
	v_mfma_f32_16x16x32_bf16 v[24:27], v[238:241], v[216:219], v[24:27]
	s_waitcnt vmcnt(7)
	ds_write_b128 v152, v[132:135] offset:40960
	s_waitcnt lgkmcnt(7)
	v_mfma_f32_16x16x32_bf16 v[84:87], v[242:245], v[204:207], v[84:87]
	v_mfma_f32_16x16x32_bf16 v[80:83], v[242:245], v[208:211], v[80:83]
	v_mfma_f32_16x16x32_bf16 v[20:23], v[242:245], v[212:215], v[20:23]
	v_mfma_f32_16x16x32_bf16 v[16:19], v[242:245], v[216:219], v[16:19]
	s_waitcnt vmcnt(6)
	ds_write_b128 v152, v[148:151] offset:45056
	s_waitcnt lgkmcnt(7)
	v_mfma_f32_16x16x32_bf16 v[76:79], v[246:249], v[204:207], v[76:79]
	v_mfma_f32_16x16x32_bf16 v[72:75], v[246:249], v[208:211], v[72:75]
	v_mfma_f32_16x16x32_bf16 v[12:15], v[246:249], v[212:215], v[12:15]
	v_mfma_f32_16x16x32_bf16 v[8:11], v[246:249], v[216:219], v[8:11]
	s_waitcnt lgkmcnt(6)
	v_mfma_f32_16x16x32_bf16 v[68:71], v[250:253], v[204:207], v[68:71]
	v_mfma_f32_16x16x32_bf16 v[64:67], v[250:253], v[208:211], v[64:67]
	v_mfma_f32_16x16x32_bf16 v[4:7], v[250:253], v[212:215], v[4:7]
	v_mfma_f32_16x16x32_bf16 v[0:3], v[250:253], v[216:219], v[0:3]
	s_setprio 0
	s_min_u32 s5, s5, 0x380
	s_lshl_b32 s30, s5, 1
	s_mov_b32 s53, s31
	s_add_i32 s52, s30, 0xc0
	v_lshl_add_u64 v[128:129], v[154:155], 0, s[30:31]
	v_lshl_add_u64 v[132:133], v[156:157], 0, s[30:31]
	v_lshl_add_u64 v[136:137], v[158:159], 0, s[52:53]
	v_lshl_add_u64 v[140:141], v[160:161], 0, s[52:53]
	v_lshl_add_u64 v[144:145], v[162:163], 0, s[52:53]
	v_lshl_add_u64 v[148:149], v[164:165], 0, s[52:53]
	s_waitcnt lgkmcnt(0)
	s_barrier
	ds_read_b128 v[204:207], v175 offset:40960
	ds_read_b128 v[208:211], v175 offset:41984
	ds_read_b128 v[212:215], v175 offset:43008
	ds_read_b128 v[216:219], v175 offset:44032
	ds_read_b128 v[222:225], v177
	ds_read_b128 v[226:229], v177 offset:1024
	ds_read_b128 v[230:233], v177 offset:2048
	ds_read_b128 v[234:237], v177 offset:3072
	ds_read_b128 v[238:241], v177 offset:4096
	ds_read_b128 v[242:245], v177 offset:5120
	ds_read_b128 v[246:249], v177 offset:6144
	ds_read_b128 v[250:253], v177 offset:7168
	s_setprio 1
	s_waitcnt lgkmcnt(7)
	v_mfma_f32_16x16x32_bf16 v[124:127], v[222:225], v[204:207], v[124:127]
	v_mfma_f32_16x16x32_bf16 v[120:123], v[222:225], v[208:211], v[120:123]
	v_mfma_f32_16x16x32_bf16 v[60:63], v[222:225], v[212:215], v[60:63]
	v_mfma_f32_16x16x32_bf16 v[56:59], v[222:225], v[216:219], v[56:59]
	global_load_dwordx4 v[128:131], v[128:129], off offset:192
	global_load_dwordx4 v[132:135], v[132:133], off offset:192
	global_load_dwordx4 v[136:139], v[136:137], off
	global_load_dwordx4 v[140:143], v[140:141], off
	global_load_dwordx4 v[144:147], v[144:145], off
	global_load_dwordx4 v[148:151], v[148:149], off
	s_waitcnt vmcnt(11)
	ds_write_b128 v152, v[180:183]
	s_waitcnt lgkmcnt(7)
	v_mfma_f32_16x16x32_bf16 v[116:119], v[226:229], v[204:207], v[116:119]
	v_mfma_f32_16x16x32_bf16 v[112:115], v[226:229], v[208:211], v[112:115]
	v_mfma_f32_16x16x32_bf16 v[52:55], v[226:229], v[212:215], v[52:55]
	v_mfma_f32_16x16x32_bf16 v[48:51], v[226:229], v[216:219], v[48:51]
	s_waitcnt vmcnt(10)
	ds_write_b128 v152, v[184:187] offset:4096
	s_waitcnt lgkmcnt(7)
	v_mfma_f32_16x16x32_bf16 v[108:111], v[230:233], v[204:207], v[108:111]
	v_mfma_f32_16x16x32_bf16 v[104:107], v[230:233], v[208:211], v[104:107]
	v_mfma_f32_16x16x32_bf16 v[44:47], v[230:233], v[212:215], v[44:47]
	v_mfma_f32_16x16x32_bf16 v[40:43], v[230:233], v[216:219], v[40:43]
	s_waitcnt vmcnt(9)
	ds_write_b128 v152, v[188:191] offset:8192
	s_waitcnt lgkmcnt(7)
	v_mfma_f32_16x16x32_bf16 v[100:103], v[234:237], v[204:207], v[100:103]
	v_mfma_f32_16x16x32_bf16 v[96:99], v[234:237], v[208:211], v[96:99]
	v_mfma_f32_16x16x32_bf16 v[36:39], v[234:237], v[212:215], v[36:39]
	v_mfma_f32_16x16x32_bf16 v[32:35], v[234:237], v[216:219], v[32:35]
	s_waitcnt vmcnt(8)
	ds_write_b128 v152, v[192:195] offset:12288
	s_waitcnt lgkmcnt(7)
	v_mfma_f32_16x16x32_bf16 v[92:95], v[238:241], v[204:207], v[92:95]
	v_mfma_f32_16x16x32_bf16 v[88:91], v[238:241], v[208:211], v[88:91]
	v_mfma_f32_16x16x32_bf16 v[28:31], v[238:241], v[212:215], v[28:31]
	v_mfma_f32_16x16x32_bf16 v[24:27], v[238:241], v[216:219], v[24:27]
	s_waitcnt vmcnt(7)
	ds_write_b128 v152, v[196:199] offset:32768
	s_waitcnt lgkmcnt(7)
	v_mfma_f32_16x16x32_bf16 v[84:87], v[242:245], v[204:207], v[84:87]
	v_mfma_f32_16x16x32_bf16 v[80:83], v[242:245], v[208:211], v[80:83]
	v_mfma_f32_16x16x32_bf16 v[20:23], v[242:245], v[212:215], v[20:23]
	v_mfma_f32_16x16x32_bf16 v[16:19], v[242:245], v[216:219], v[16:19]
	s_waitcnt vmcnt(6)
	ds_write_b128 v152, v[200:203] offset:36864
	s_waitcnt lgkmcnt(7)
	v_mfma_f32_16x16x32_bf16 v[76:79], v[246:249], v[204:207], v[76:79]
	v_mfma_f32_16x16x32_bf16 v[72:75], v[246:249], v[208:211], v[72:75]
	v_mfma_f32_16x16x32_bf16 v[12:15], v[246:249], v[212:215], v[12:15]
	v_mfma_f32_16x16x32_bf16 v[8:11], v[246:249], v[216:219], v[8:11]
	s_waitcnt lgkmcnt(6)
	v_mfma_f32_16x16x32_bf16 v[68:71], v[250:253], v[204:207], v[68:71]
	v_mfma_f32_16x16x32_bf16 v[64:67], v[250:253], v[208:211], v[64:67]
	v_mfma_f32_16x16x32_bf16 v[4:7], v[250:253], v[212:215], v[4:7]
	v_mfma_f32_16x16x32_bf16 v[0:3], v[250:253], v[216:219], v[0:3]
	s_setprio 0
	s_add_i32 s1, s1, 2
	s_mov_b32 s5, s27
	s_add_i32 s27, s5, 64
	s_min_u32 s30, s27, 0x3e0
	s_lshl_b32 s30, s30, 1
	v_lshl_add_u64 v[180:181], v[154:155], 0, s[30:31]
	v_lshl_add_u64 v[184:185], v[158:159], 0, s[30:31]
	v_lshl_add_u64 v[188:189], v[160:161], 0, s[30:31]
	v_lshl_add_u64 v[192:193], v[162:163], 0, s[30:31]
	v_lshl_add_u64 v[196:197], v[156:157], 0, s[30:31]
	v_lshl_add_u64 v[200:201], v[164:165], 0, s[30:31]
	s_cmp_lt_u32 s1, 30
	s_waitcnt lgkmcnt(0)
	s_cbranch_scc1 .Lrot_5
	s_barrier
	s_waitcnt vmcnt(5)
	v_mov_b32_e32 v128, v220
	s_cmp_gt_i32 s26, 15
	v_and_b32_e32 v158, 15, v128
	v_and_b32_e32 v160, 64, v128
	v_and_b32_e32 v129, 0xffffff80, v128
	v_lshrrev_b32_e32 v128, 2, v128
	v_add_u32_e32 v130, s4, v129
	v_and_b32_e32 v159, 12, v128
	s_waitcnt vmcnt(3)
	v_or_b32_e32 v136, v130, v159
	v_ashrrev_i32_e32 v128, 14, v130
	s_waitcnt vmcnt(0)
	v_or_b32_e32 v150, 16, v136
	v_or_b32_e32 v148, 32, v136
	v_or_b32_e32 v146, 48, v136
	v_or_b32_e32 v142, 64, v136
	v_or_b32_e32 v140, 0x50, v136
	v_or_b32_e32 v138, 0x60, v136
	v_or_b32_e32 v134, 0x70, v136
	s_mov_b64 s[4:5], -1
	v_ashrrev_i32_e32 v137, 31, v136
	v_lshlrev_b32_e32 v132, 1, v159
	v_mov_b32_e32 v250, s0
	v_and_b32_e32 v250, 0x80, v250
	v_add_u32_e32 v250, v250, v160
	v_mul_u32_u24_e32 v250, 30, v250
	v_lshrrev_b32_e32 v251, 3, v158
	v_mul_u32_u24_e32 v251, 0xf0, v251
	v_add_u32_e32 v250, v250, v251
	v_lshrrev_b32_e32 v251, 2, v159
	v_mul_u32_u24_e32 v251, 0x7c0, v251
	v_sub_u32_e32 v250, v250, v251
	v_ashrrev_i32_e32 v251, 31, v250
	v_and_b32_e32 v252, 8, v159
	v_lshlrev_b32_e32 v252, 5, v252
	v_and_b32_e32 v253, 4, v159
	v_lshl_or_b32 v252, v253, 1, v252
	v_lshl_or_b32 v252, v158, 4, v252
	v_mov_b32_e32 v253, 0
	v_ashrrev_i32_e32 v129, 31, v128
	v_ashrrev_i32_e32 v151, 31, v150
	v_ashrrev_i32_e32 v149, 31, v148
	v_ashrrev_i32_e32 v147, 31, v146
	v_ashrrev_i32_e32 v143, 31, v142
	v_ashrrev_i32_e32 v141, 31, v140
	v_ashrrev_i32_e32 v139, 31, v138
	v_ashrrev_i32_e32 v135, 31, v134
	s_cbranch_scc0 .LBB0_211
	v_lshl_add_u64 v[144:145], v[136:137], 2, s[8:9]
	global_load_dwordx4 v[162:165], v[144:145], off
	s_add_i32 s1, s0, 0xfffff800
	s_and_b32 s5, s0, 0x180
	s_ashr_i32 s4, s1, 9
	v_or_b32_e32 v154, s5, v160
	s_ashr_i32 s5, s4, 31
	v_lshlrev_b64 v[144:145], 9, v[128:129]
	s_lshl_b64 s[4:5], s[4:5], 7
	v_lshrrev_b32_e32 v152, 7, v130
	v_lshl_add_u64 v[130:131], v[144:145], 0, s[4:5]
	v_and_or_b32 v130, v152, s38, v130
	v_lshlrev_b64 v[130:131], 16, v[130:131]
	v_mov_b32_e32 v133, v153
	v_lshl_or_b32 v130, v154, 7, v130
	v_lshl_add_u64 v[178:179], s[12:13], 0, v[252:253]
	v_mov_b32_e32 v145, v131
	v_mov_b32_e32 v181, v131
	v_lshlrev_b64 v[156:157], 1, v[130:131]
	v_or_b32_e32 v144, 0x800, v130
	v_or_b32_e32 v180, 0x1000, v130
	v_or_b32_e32 v130, 0x1800, v130
	v_lshl_add_u64 v[182:183], v[178:179], 0, v[156:157]
	v_lshlrev_b64 v[154:155], 1, v[144:145]
	v_lshlrev_b64 v[144:145], 1, v[180:181]
	v_lshlrev_b64 v[130:131], 1, v[130:131]
	v_lshl_add_u64 v[176:177], v[150:151], 2, s[8:9]
	v_lshl_add_u64 v[180:181], v[178:179], 0, v[154:155]
	v_lshl_add_u64 v[184:185], v[178:179], 0, v[144:145]
	v_lshl_add_u64 v[178:179], v[178:179], 0, v[130:131]
	s_waitcnt vmcnt(0)
	v_mul_f32_e32 v133, v124, v162
	v_mul_f32_e32 v152, v125, v163
	v_mul_f32_e32 v161, v126, v164
	v_mul_f32_e32 v175, v127, v165
	v_mul_f32_e32 v186, v120, v162
	v_mul_f32_e32 v187, v121, v163
	v_mul_f32_e32 v188, v122, v164
	v_mul_f32_e32 v189, v123, v165
	v_mul_f32_e32 v190, v60, v162
	v_mul_f32_e32 v191, v61, v163
	v_mul_f32_e32 v194, v56, v162
	v_mul_f32_e32 v195, v57, v163
	v_cvt_pk_bf16_f32 v162, v133, v152
	v_cvt_pk_bf16_f32 v163, v161, v175
	v_mul_f32_e32 v192, v62, v164
	v_mul_f32_e32 v193, v63, v165
	v_mul_f32_e32 v196, v58, v164
	v_mul_f32_e32 v197, v59, v165
	v_cvt_pk_bf16_f32 v164, v186, v187
	v_cvt_pk_bf16_f32 v165, v188, v189
	v_cvt_pk_bf16_f32 v186, v190, v191
	v_cvt_pk_bf16_f32 v187, v192, v193
	v_cvt_pk_bf16_f32 v188, v194, v195
	v_cvt_pk_bf16_f32 v189, v196, v197
	global_store_dwordx2 v[182:183], v[162:163], off
	global_store_dwordx2 v[180:181], v[164:165], off
	global_store_dwordx2 v[184:185], v[186:187], off
	global_store_dwordx2 v[178:179], v[188:189], off
	global_load_dwordx4 v[162:165], v[176:177], off
	v_bitop3_b32 v133, v136, 28, 16 bitop3:0xc8
	v_lshlrev_b32_e32 v152, 1, v133
	v_lshl_add_u64 v[178:179], s[12:13], 0, v[252:253]
	v_lshl_add_u64 v[180:181], v[178:179], 0, v[156:157]
	v_lshl_add_u64 v[176:177], v[148:149], 2, s[8:9]
	v_lshl_add_u64 v[182:183], v[178:179], 0, v[154:155]
	v_lshl_add_u64 v[184:185], v[178:179], 0, v[144:145]
	v_lshl_add_u64 v[178:179], v[178:179], 0, v[130:131]
	s_waitcnt vmcnt(0)
	v_mul_f32_e32 v133, v116, v162
	v_mul_f32_e32 v152, v117, v163
	v_mul_f32_e32 v161, v118, v164
	v_mul_f32_e32 v175, v119, v165
	v_mul_f32_e32 v186, v112, v162
	v_mul_f32_e32 v187, v113, v163
	v_mul_f32_e32 v188, v114, v164
	v_mul_f32_e32 v189, v115, v165
	global_load_dwordx4 v[116:119], v[176:177], off
	v_mul_f32_e32 v190, v52, v162
	v_mul_f32_e32 v191, v53, v163
	v_mul_f32_e32 v194, v48, v162
	v_mul_f32_e32 v195, v49, v163
	v_cvt_pk_bf16_f32 v162, v133, v152
	v_cvt_pk_bf16_f32 v163, v161, v175
	v_mul_f32_e32 v192, v54, v164
	v_mul_f32_e32 v193, v55, v165
	v_mul_f32_e32 v196, v50, v164
	v_mul_f32_e32 v197, v51, v165
	v_cvt_pk_bf16_f32 v164, v186, v187
	v_cvt_pk_bf16_f32 v165, v188, v189
	v_cvt_pk_bf16_f32 v186, v190, v191
	v_cvt_pk_bf16_f32 v187, v192, v193
	v_cvt_pk_bf16_f32 v188, v194, v195
	v_cvt_pk_bf16_f32 v189, v196, v197
	global_store_dwordx2 v[180:181], v[162:163], off offset:512
	global_store_dwordx2 v[182:183], v[164:165], off offset:512
	global_store_dwordx2 v[184:185], v[186:187], off offset:512
	global_store_dwordx2 v[178:179], v[188:189], off offset:512
	v_bitop3_b32 v133, v136, 44, 32 bitop3:0xc8
	v_lshlrev_b32_e32 v152, 1, v133
	v_lshl_add_u64 v[178:179], s[12:13], 0, v[252:253]
	v_lshl_add_u64 v[180:181], v[178:179], 0, v[156:157]
	v_lshl_add_u64 v[176:177], v[146:147], 2, s[8:9]
	global_load_dwordx4 v[112:115], v[176:177], off
	v_lshl_add_u64 v[182:183], v[178:179], 0, v[154:155]
	v_lshl_add_u64 v[184:185], v[178:179], 0, v[144:145]
	v_lshl_add_u64 v[178:179], v[178:179], 0, v[130:131]
	s_waitcnt vmcnt(5)
	v_mov_b32_e32 v162, v116
	v_mov_b32_e32 v163, v117
	v_mov_b32_e32 v164, v118
	v_mov_b32_e32 v165, v119
	v_mul_f32_e32 v133, v108, v162
	v_mul_f32_e32 v152, v109, v163
	v_mul_f32_e32 v161, v110, v164
	v_mul_f32_e32 v175, v111, v165
	v_mul_f32_e32 v186, v104, v162
	v_mul_f32_e32 v187, v105, v163
	v_mul_f32_e32 v188, v106, v164
	v_mul_f32_e32 v189, v107, v165
	v_mul_f32_e32 v190, v44, v162
	v_mul_f32_e32 v191, v45, v163
	v_mul_f32_e32 v194, v40, v162
	v_mul_f32_e32 v195, v41, v163
	v_cvt_pk_bf16_f32 v162, v133, v152
	v_cvt_pk_bf16_f32 v163, v161, v175
	v_mul_f32_e32 v192, v46, v164
	v_mul_f32_e32 v193, v47, v165
	v_mul_f32_e32 v196, v42, v164
	v_mul_f32_e32 v197, v43, v165
	v_cvt_pk_bf16_f32 v164, v186, v187
	v_cvt_pk_bf16_f32 v165, v188, v189
	v_cvt_pk_bf16_f32 v186, v190, v191
	v_cvt_pk_bf16_f32 v187, v192, v193
	v_cvt_pk_bf16_f32 v188, v194, v195
	v_cvt_pk_bf16_f32 v189, v196, v197
	global_store_dwordx2 v[180:181], v[162:163], off offset:1024
	global_store_dwordx2 v[182:183], v[164:165], off offset:1024
	global_store_dwordx2 v[184:185], v[186:187], off offset:1024
	global_store_dwordx2 v[178:179], v[188:189], off offset:1024
	v_bitop3_b32 v133, v136, 60, 48 bitop3:0xc8
	v_lshlrev_b32_e32 v152, 1, v133
	v_lshl_add_u64 v[178:179], s[12:13], 0, v[252:253]
	v_lshl_add_u64 v[180:181], v[178:179], 0, v[156:157]
	v_lshl_add_u64 v[176:177], v[142:143], 2, s[8:9]
	global_load_dwordx4 v[116:119], v[176:177], off
	v_lshl_add_u64 v[182:183], v[178:179], 0, v[154:155]
	v_lshl_add_u64 v[184:185], v[178:179], 0, v[144:145]
	v_lshl_add_u64 v[178:179], v[178:179], 0, v[130:131]
	s_waitcnt vmcnt(5)
	v_mov_b32_e32 v162, v112
	v_mov_b32_e32 v163, v113
	v_mov_b32_e32 v164, v114
	v_mov_b32_e32 v165, v115
	v_mul_f32_e32 v133, v100, v162
	v_mul_f32_e32 v152, v101, v163
	v_mul_f32_e32 v161, v102, v164
	v_mul_f32_e32 v175, v103, v165
	v_mul_f32_e32 v186, v96, v162
	v_mul_f32_e32 v187, v97, v163
	v_mul_f32_e32 v188, v98, v164
	v_mul_f32_e32 v189, v99, v165
	v_mul_f32_e32 v190, v36, v162
	v_mul_f32_e32 v191, v37, v163
	v_mul_f32_e32 v194, v32, v162
	v_mul_f32_e32 v195, v33, v163
	v_cvt_pk_bf16_f32 v162, v133, v152
	v_cvt_pk_bf16_f32 v163, v161, v175
	v_mul_f32_e32 v192, v38, v164
	v_mul_f32_e32 v193, v39, v165
	v_mul_f32_e32 v196, v34, v164
	v_mul_f32_e32 v197, v35, v165
	v_cvt_pk_bf16_f32 v164, v186, v187
	v_cvt_pk_bf16_f32 v165, v188, v189
	v_cvt_pk_bf16_f32 v186, v190, v191
	v_cvt_pk_bf16_f32 v187, v192, v193
	v_cvt_pk_bf16_f32 v188, v194, v195
	v_cvt_pk_bf16_f32 v189, v196, v197
	global_store_dwordx2 v[180:181], v[162:163], off offset:1536
	global_store_dwordx2 v[182:183], v[164:165], off offset:1536
	global_store_dwordx2 v[184:185], v[186:187], off offset:1536
	global_store_dwordx2 v[178:179], v[188:189], off offset:1536
	v_bitop3_b32 v133, v136, s39, 64 bitop3:0xc8
	v_lshlrev_b32_e32 v152, 1, v133
	v_lshl_add_u64 v[178:179], s[12:13], 0, v[252:253]
	v_lshl_add_u64 v[180:181], v[178:179], 0, v[156:157]
	v_lshl_add_u64 v[176:177], v[140:141], 2, s[8:9]
	global_load_dwordx4 v[112:115], v[176:177], off
	v_lshl_add_u64 v[182:183], v[178:179], 0, v[154:155]
	v_lshl_add_u64 v[184:185], v[178:179], 0, v[144:145]
	v_lshl_add_u64 v[178:179], v[178:179], 0, v[130:131]
	s_waitcnt vmcnt(5)
	v_mov_b32_e32 v162, v116
	v_mov_b32_e32 v163, v117
	v_mov_b32_e32 v164, v118
	v_mov_b32_e32 v165, v119
	v_mul_f32_e32 v133, v92, v162
	v_mul_f32_e32 v152, v93, v163
	v_mul_f32_e32 v161, v94, v164
	v_mul_f32_e32 v175, v95, v165
	v_mul_f32_e32 v186, v88, v162
	v_mul_f32_e32 v187, v89, v163
	v_mul_f32_e32 v188, v90, v164
	v_mul_f32_e32 v189, v91, v165
	v_mul_f32_e32 v190, v28, v162
	v_mul_f32_e32 v191, v29, v163
	v_mul_f32_e32 v194, v24, v162
	v_mul_f32_e32 v195, v25, v163
	v_cvt_pk_bf16_f32 v162, v133, v152
	v_cvt_pk_bf16_f32 v163, v161, v175
	v_mul_f32_e32 v192, v30, v164
	v_mul_f32_e32 v193, v31, v165
	v_mul_f32_e32 v196, v26, v164
	v_mul_f32_e32 v197, v27, v165
	v_cvt_pk_bf16_f32 v164, v186, v187
	v_cvt_pk_bf16_f32 v165, v188, v189
	v_cvt_pk_bf16_f32 v186, v190, v191
	v_cvt_pk_bf16_f32 v187, v192, v193
	v_cvt_pk_bf16_f32 v188, v194, v195
	v_cvt_pk_bf16_f32 v189, v196, v197
	global_store_dwordx2 v[180:181], v[162:163], off offset:2048
	global_store_dwordx2 v[182:183], v[164:165], off offset:2048
	global_store_dwordx2 v[184:185], v[186:187], off offset:2048
	global_store_dwordx2 v[178:179], v[188:189], off offset:2048
	v_bitop3_b32 v133, v136, s40, v166 bitop3:0xc8
	v_lshlrev_b32_e32 v152, 1, v133
	v_lshl_add_u64 v[178:179], s[12:13], 0, v[252:253]
	v_lshl_add_u64 v[180:181], v[178:179], 0, v[156:157]
	v_lshl_add_u64 v[176:177], v[138:139], 2, s[8:9]
	global_load_dwordx4 v[116:119], v[176:177], off
	v_lshl_add_u64 v[182:183], v[178:179], 0, v[154:155]
	v_lshl_add_u64 v[184:185], v[178:179], 0, v[144:145]
	v_lshl_add_u64 v[178:179], v[178:179], 0, v[130:131]
	s_waitcnt vmcnt(5)
	v_mov_b32_e32 v162, v112
	v_mov_b32_e32 v163, v113
	v_mov_b32_e32 v164, v114
	v_mov_b32_e32 v165, v115
	v_mul_f32_e32 v133, v84, v162
	v_mul_f32_e32 v152, v85, v163
	v_mul_f32_e32 v161, v86, v164
	v_mul_f32_e32 v175, v87, v165
	v_mul_f32_e32 v186, v80, v162
	v_mul_f32_e32 v187, v81, v163
	v_mul_f32_e32 v188, v82, v164
	v_mul_f32_e32 v189, v83, v165
	v_mul_f32_e32 v190, v20, v162
	v_mul_f32_e32 v191, v21, v163
	v_mul_f32_e32 v194, v16, v162
	v_mul_f32_e32 v195, v17, v163
	v_cvt_pk_bf16_f32 v162, v133, v152
	v_cvt_pk_bf16_f32 v163, v161, v175
	v_mul_f32_e32 v192, v22, v164
	v_mul_f32_e32 v193, v23, v165
	v_mul_f32_e32 v196, v18, v164
	v_mul_f32_e32 v197, v19, v165
	v_cvt_pk_bf16_f32 v164, v186, v187
	v_cvt_pk_bf16_f32 v165, v188, v189
	v_cvt_pk_bf16_f32 v186, v190, v191
	v_cvt_pk_bf16_f32 v187, v192, v193
	v_cvt_pk_bf16_f32 v188, v194, v195
	v_cvt_pk_bf16_f32 v189, v196, v197
	global_store_dwordx2 v[180:181], v[162:163], off offset:2560
	global_store_dwordx2 v[182:183], v[164:165], off offset:2560
	global_store_dwordx2 v[184:185], v[186:187], off offset:2560
	global_store_dwordx2 v[178:179], v[188:189], off offset:2560
	v_bitop3_b32 v133, v136, s41, v167 bitop3:0xc8
	v_lshlrev_b32_e32 v152, 1, v133
	v_lshl_add_u64 v[178:179], s[12:13], 0, v[252:253]
	v_lshl_add_u64 v[180:181], v[178:179], 0, v[156:157]
	v_lshl_add_u64 v[176:177], v[134:135], 2, s[8:9]
	global_load_dwordx4 v[112:115], v[176:177], off
	v_lshl_add_u64 v[182:183], v[178:179], 0, v[154:155]
	v_lshl_add_u64 v[184:185], v[178:179], 0, v[144:145]
	v_lshl_add_u64 v[178:179], v[178:179], 0, v[130:131]
	s_waitcnt vmcnt(5)
	v_mov_b32_e32 v162, v116
	v_mov_b32_e32 v163, v117
	v_mov_b32_e32 v164, v118
	v_mov_b32_e32 v165, v119
	v_mul_f32_e32 v133, v76, v162
	v_mul_f32_e32 v152, v77, v163
	v_mul_f32_e32 v161, v78, v164
	v_mul_f32_e32 v175, v79, v165
	v_mul_f32_e32 v186, v72, v162
	v_mul_f32_e32 v187, v73, v163
	v_mul_f32_e32 v188, v74, v164
	v_mul_f32_e32 v189, v75, v165
	v_mul_f32_e32 v190, v12, v162
	v_mul_f32_e32 v191, v13, v163
	v_mul_f32_e32 v194, v8, v162
	v_mul_f32_e32 v195, v9, v163
	v_cvt_pk_bf16_f32 v162, v133, v152
	v_cvt_pk_bf16_f32 v163, v161, v175
	v_mul_f32_e32 v192, v14, v164
	v_mul_f32_e32 v193, v15, v165
	v_mul_f32_e32 v196, v10, v164
	v_mul_f32_e32 v197, v11, v165
	v_cvt_pk_bf16_f32 v164, v186, v187
	v_cvt_pk_bf16_f32 v165, v188, v189
	v_cvt_pk_bf16_f32 v186, v190, v191
	v_cvt_pk_bf16_f32 v187, v192, v193
	v_cvt_pk_bf16_f32 v188, v194, v195
	v_cvt_pk_bf16_f32 v189, v196, v197
	global_store_dwordx2 v[180:181], v[162:163], off offset:3072
	global_store_dwordx2 v[182:183], v[164:165], off offset:3072
	global_store_dwordx2 v[184:185], v[186:187], off offset:3072
	global_store_dwordx2 v[178:179], v[188:189], off offset:3072
	v_bitop3_b32 v133, v136, s42, v168 bitop3:0xc8
	v_lshlrev_b32_e32 v152, 1, v133
	v_lshl_add_u64 v[176:177], s[12:13], 0, v[252:253]
	v_lshl_add_u64 v[156:157], v[176:177], 0, v[156:157]
	v_lshl_add_u64 v[154:155], v[176:177], 0, v[154:155]
	v_lshl_add_u64 v[144:145], v[176:177], 0, v[144:145]
	v_lshl_add_u64 v[130:131], v[176:177], 0, v[130:131]
	s_waitcnt vmcnt(4)
	v_mov_b32_e32 v162, v112
	v_mov_b32_e32 v163, v113
	v_mov_b32_e32 v164, v114
	v_mov_b32_e32 v165, v115
	v_mul_f32_e32 v133, v68, v162
	v_mul_f32_e32 v152, v69, v163
	v_mul_f32_e32 v161, v70, v164
	v_mul_f32_e32 v175, v71, v165
	v_mul_f32_e32 v176, v64, v162
	v_mul_f32_e32 v177, v65, v163
	v_mul_f32_e32 v178, v66, v164
	v_mul_f32_e32 v179, v67, v165
	v_mul_f32_e32 v180, v4, v162
	v_mul_f32_e32 v181, v5, v163
	v_mul_f32_e32 v184, v0, v162
	v_mul_f32_e32 v185, v1, v163
	v_cvt_pk_bf16_f32 v162, v133, v152
	v_cvt_pk_bf16_f32 v163, v161, v175
	v_mul_f32_e32 v182, v6, v164
	v_mul_f32_e32 v183, v7, v165
	v_mul_f32_e32 v186, v2, v164
	v_mul_f32_e32 v187, v3, v165
	v_cvt_pk_bf16_f32 v164, v176, v177
	v_cvt_pk_bf16_f32 v165, v178, v179
	v_cvt_pk_bf16_f32 v176, v180, v181
	v_cvt_pk_bf16_f32 v177, v182, v183
	v_cvt_pk_bf16_f32 v178, v184, v185
	v_cvt_pk_bf16_f32 v179, v186, v187
	global_store_dwordx2 v[156:157], v[162:163], off offset:3584
	global_store_dwordx2 v[154:155], v[164:165], off offset:3584
	global_store_dwordx2 v[144:145], v[176:177], off offset:3584
	global_store_dwordx2 v[130:131], v[178:179], off offset:3584
	s_cbranch_execnz .LBB0_206
	s_branch .LBB0_212

.LBB0_503:
	ds_read_b128 v[196:199], v169 offset:32768
	ds_read_b128 v[200:203], v169 offset:33792
	ds_read_b128 v[204:207], v169 offset:34816
	ds_read_b128 v[208:211], v169 offset:35840
	ds_read_b128 v[212:215], v167
	ds_read_b128 v[216:219], v167 offset:1024
	ds_read_b128 v[222:225], v167 offset:2048
	ds_read_b128 v[226:229], v167 offset:3072
	ds_read_b128 v[230:233], v167 offset:4096
	ds_read_b128 v[234:237], v167 offset:5120
	ds_read_b128 v[238:241], v167 offset:6144
	ds_read_b128 v[242:245], v167 offset:7168
	s_setprio 1
	s_waitcnt lgkmcnt(7)
	v_mfma_f32_16x16x32_bf16 v[148:151], v[196:199], v[212:215], v[148:151]
	v_mfma_f32_16x16x32_bf16 v[136:139], v[200:203], v[212:215], v[136:139]
	v_mfma_f32_16x16x32_bf16 v[132:135], v[204:207], v[212:215], v[132:135]
	v_mfma_f32_16x16x32_bf16 v[128:131], v[208:211], v[212:215], v[128:131]
	global_load_dwordx4 v[170:173], v[170:171], off
	global_load_dwordx4 v[174:177], v[174:175], off
	global_load_dwordx4 v[178:181], v[178:179], off
	global_load_dwordx4 v[182:185], v[182:183], off
	global_load_dwordx4 v[186:189], v[186:187], off
	global_load_dwordx4 v[190:193], v[190:191], off
	s_waitcnt vmcnt(11)
	ds_write_b128 v152, v[44:47] offset:16384
	s_waitcnt lgkmcnt(7)
	v_mfma_f32_16x16x32_bf16 v[124:127], v[196:199], v[216:219], v[124:127]
	v_mfma_f32_16x16x32_bf16 v[120:123], v[200:203], v[216:219], v[120:123]
	v_mfma_f32_16x16x32_bf16 v[116:119], v[204:207], v[216:219], v[116:119]
	v_mfma_f32_16x16x32_bf16 v[112:115], v[208:211], v[216:219], v[112:115]
	s_waitcnt vmcnt(9)
	ds_write_b128 v152, v[60:63] offset:20480
	s_waitcnt lgkmcnt(7)
	v_mfma_f32_16x16x32_bf16 v[108:111], v[196:199], v[222:225], v[108:111]
	v_mfma_f32_16x16x32_bf16 v[104:107], v[200:203], v[222:225], v[104:107]
	v_mfma_f32_16x16x32_bf16 v[100:103], v[204:207], v[222:225], v[100:103]
	v_mfma_f32_16x16x32_bf16 v[96:99], v[208:211], v[222:225], v[96:99]
	s_waitcnt vmcnt(8)
	ds_write_b128 v152, v[68:71] offset:24576
	s_waitcnt lgkmcnt(7)
	v_mfma_f32_16x16x32_bf16 v[92:95], v[196:199], v[226:229], v[92:95]
	v_mfma_f32_16x16x32_bf16 v[88:91], v[200:203], v[226:229], v[88:91]
	v_mfma_f32_16x16x32_bf16 v[84:87], v[204:207], v[226:229], v[84:87]
	v_mfma_f32_16x16x32_bf16 v[80:83], v[208:211], v[226:229], v[80:83]
	s_waitcnt vmcnt(7)
	ds_write_b128 v152, v[140:143] offset:28672
	s_waitcnt lgkmcnt(7)
	v_mfma_f32_16x16x32_bf16 v[76:79], v[196:199], v[230:233], v[76:79]
	v_mfma_f32_16x16x32_bf16 v[72:75], v[200:203], v[230:233], v[72:75]
	v_mfma_f32_16x16x32_bf16 v[64:67], v[204:207], v[230:233], v[64:67]
	v_mfma_f32_16x16x32_bf16 v[56:59], v[208:211], v[230:233], v[56:59]
	s_waitcnt vmcnt(7)
	ds_write_b128 v152, v[52:55] offset:40960
	s_waitcnt lgkmcnt(7)
	v_mfma_f32_16x16x32_bf16 v[48:51], v[196:199], v[234:237], v[48:51]
	v_mfma_f32_16x16x32_bf16 v[40:43], v[200:203], v[234:237], v[40:43]
	v_mfma_f32_16x16x32_bf16 v[36:39], v[204:207], v[234:237], v[36:39]
	v_mfma_f32_16x16x32_bf16 v[32:35], v[208:211], v[234:237], v[32:35]
	s_waitcnt vmcnt(6)
	ds_write_b128 v152, v[144:147] offset:45056
	s_waitcnt lgkmcnt(7)
	v_mfma_f32_16x16x32_bf16 v[28:31], v[196:199], v[238:241], v[28:31]
	v_mfma_f32_16x16x32_bf16 v[24:27], v[200:203], v[238:241], v[24:27]
	v_mfma_f32_16x16x32_bf16 v[20:23], v[204:207], v[238:241], v[20:23]
	v_mfma_f32_16x16x32_bf16 v[16:19], v[208:211], v[238:241], v[16:19]
	s_waitcnt lgkmcnt(6)
	v_mfma_f32_16x16x32_bf16 v[12:15], v[196:199], v[242:245], v[12:15]
	v_mfma_f32_16x16x32_bf16 v[8:11], v[200:203], v[242:245], v[8:11]
	v_mfma_f32_16x16x32_bf16 v[4:7], v[204:207], v[242:245], v[4:7]
	v_mfma_f32_16x16x32_bf16 v[0:3], v[208:211], v[242:245], v[0:3]
	s_setprio 0
	s_min_u32 s14, s36, 0x380
	s_lshl_b32 s14, s14, 1
	s_mov_b32 s39, s15
	s_add_i32 s38, s14, 0xc0
	v_lshl_add_u64 v[44:45], v[154:155], 0, s[14:15]
	v_lshl_add_u64 v[52:53], v[156:157], 0, s[14:15]
	v_lshl_add_u64 v[60:61], v[158:159], 0, s[38:39]
	v_lshl_add_u64 v[68:69], v[160:161], 0, s[38:39]
	v_lshl_add_u64 v[140:141], v[162:163], 0, s[38:39]
	v_lshl_add_u64 v[144:145], v[164:165], 0, s[38:39]
	s_waitcnt lgkmcnt(0)
	s_barrier
	ds_read_b128 v[196:199], v166 offset:40960
	ds_read_b128 v[200:203], v166 offset:41984
	ds_read_b128 v[204:207], v166 offset:43008
	ds_read_b128 v[208:211], v166 offset:44032
	ds_read_b128 v[212:215], v168
	ds_read_b128 v[216:219], v168 offset:1024
	ds_read_b128 v[222:225], v168 offset:2048
	ds_read_b128 v[226:229], v168 offset:3072
	ds_read_b128 v[230:233], v168 offset:4096
	ds_read_b128 v[234:237], v168 offset:5120
	ds_read_b128 v[238:241], v168 offset:6144
	ds_read_b128 v[242:245], v168 offset:7168
	s_setprio 1
	s_waitcnt lgkmcnt(7)
	v_mfma_f32_16x16x32_bf16 v[148:151], v[196:199], v[212:215], v[148:151]
	v_mfma_f32_16x16x32_bf16 v[136:139], v[200:203], v[212:215], v[136:139]
	v_mfma_f32_16x16x32_bf16 v[132:135], v[204:207], v[212:215], v[132:135]
	v_mfma_f32_16x16x32_bf16 v[128:131], v[208:211], v[212:215], v[128:131]
	global_load_dwordx4 v[44:47], v[44:45], off offset:192
	global_load_dwordx4 v[52:55], v[52:53], off offset:192
	global_load_dwordx4 v[60:63], v[60:61], off
	global_load_dwordx4 v[68:71], v[68:69], off
	global_load_dwordx4 v[140:143], v[140:141], off
	global_load_dwordx4 v[144:147], v[144:145], off
	s_waitcnt vmcnt(11)
	ds_write_b128 v152, v[170:173]
	s_waitcnt lgkmcnt(7)
	v_mfma_f32_16x16x32_bf16 v[124:127], v[196:199], v[216:219], v[124:127]
	v_mfma_f32_16x16x32_bf16 v[120:123], v[200:203], v[216:219], v[120:123]
	v_mfma_f32_16x16x32_bf16 v[116:119], v[204:207], v[216:219], v[116:119]
	v_mfma_f32_16x16x32_bf16 v[112:115], v[208:211], v[216:219], v[112:115]
	s_waitcnt vmcnt(10)
	ds_write_b128 v152, v[174:177] offset:4096
	s_waitcnt lgkmcnt(7)
	v_mfma_f32_16x16x32_bf16 v[108:111], v[196:199], v[222:225], v[108:111]
	v_mfma_f32_16x16x32_bf16 v[104:107], v[200:203], v[222:225], v[104:107]
	v_mfma_f32_16x16x32_bf16 v[100:103], v[204:207], v[222:225], v[100:103]
	v_mfma_f32_16x16x32_bf16 v[96:99], v[208:211], v[222:225], v[96:99]
	s_waitcnt vmcnt(9)
	ds_write_b128 v152, v[178:181] offset:8192
	s_waitcnt lgkmcnt(7)
	v_mfma_f32_16x16x32_bf16 v[92:95], v[196:199], v[226:229], v[92:95]
	v_mfma_f32_16x16x32_bf16 v[88:91], v[200:203], v[226:229], v[88:91]
	v_mfma_f32_16x16x32_bf16 v[84:87], v[204:207], v[226:229], v[84:87]
	v_mfma_f32_16x16x32_bf16 v[80:83], v[208:211], v[226:229], v[80:83]
	s_waitcnt vmcnt(8)
	ds_write_b128 v152, v[182:185] offset:12288
	s_waitcnt lgkmcnt(7)
	v_mfma_f32_16x16x32_bf16 v[76:79], v[196:199], v[230:233], v[76:79]
	v_mfma_f32_16x16x32_bf16 v[72:75], v[200:203], v[230:233], v[72:75]
	v_mfma_f32_16x16x32_bf16 v[64:67], v[204:207], v[230:233], v[64:67]
	v_mfma_f32_16x16x32_bf16 v[56:59], v[208:211], v[230:233], v[56:59]
	s_waitcnt vmcnt(7)
	ds_write_b128 v152, v[186:189] offset:32768
	s_waitcnt lgkmcnt(7)
	v_mfma_f32_16x16x32_bf16 v[48:51], v[196:199], v[234:237], v[48:51]
	v_mfma_f32_16x16x32_bf16 v[40:43], v[200:203], v[234:237], v[40:43]
	v_mfma_f32_16x16x32_bf16 v[36:39], v[204:207], v[234:237], v[36:39]
	v_mfma_f32_16x16x32_bf16 v[32:35], v[208:211], v[234:237], v[32:35]
	s_waitcnt vmcnt(6)
	ds_write_b128 v152, v[190:193] offset:36864
	s_waitcnt lgkmcnt(7)
	v_mfma_f32_16x16x32_bf16 v[28:31], v[196:199], v[238:241], v[28:31]
	v_mfma_f32_16x16x32_bf16 v[24:27], v[200:203], v[238:241], v[24:27]
	v_mfma_f32_16x16x32_bf16 v[20:23], v[204:207], v[238:241], v[20:23]
	v_mfma_f32_16x16x32_bf16 v[16:19], v[208:211], v[238:241], v[16:19]
	s_waitcnt lgkmcnt(6)
	v_mfma_f32_16x16x32_bf16 v[12:15], v[196:199], v[242:245], v[12:15]
	v_mfma_f32_16x16x32_bf16 v[8:11], v[200:203], v[242:245], v[8:11]
	v_mfma_f32_16x16x32_bf16 v[4:7], v[204:207], v[242:245], v[4:7]
	v_mfma_f32_16x16x32_bf16 v[0:3], v[208:211], v[242:245], v[0:3]
	s_setprio 0
	s_add_i32 s29, s29, 2
	s_mov_b32 s36, s37
	s_add_i32 s37, s36, 64
	s_min_u32 s14, s37, 0x3e0
	s_lshl_b32 s14, s14, 1
	v_lshl_add_u64 v[170:171], v[154:155], 0, s[14:15]
	v_lshl_add_u64 v[174:175], v[158:159], 0, s[14:15]
	v_lshl_add_u64 v[178:179], v[160:161], 0, s[14:15]
	v_lshl_add_u64 v[182:183], v[162:163], 0, s[14:15]
	v_lshl_add_u64 v[186:187], v[156:157], 0, s[14:15]
	v_lshl_add_u64 v[190:191], v[164:165], 0, s[14:15]
	s_cmp_lt_u32 s29, 30
	s_waitcnt lgkmcnt(0)
	s_cbranch_scc1 .Lrot_4
	s_barrier
	s_waitcnt vmcnt(1)
	v_mov_b32_e32 v142, v220
	v_readlane_b32 s36, v254, 6
	v_and_b32_e32 v45, 0xffffff80, v142
	v_add_u32_e32 v143, s28, v45
	v_lshrrev_b32_e32 v45, 2, v142
	v_and_b32_e32 v44, 64, v142
	v_and_b32_e32 v45, 12, v45
	s_ashr_i32 s28, s33, 2
	v_or3_b32 v140, v44, v45, s35
	s_ashr_i32 s29, s28, 31
	v_ashrrev_i32_e32 v141, 31, v140
	v_readlane_b32 s44, v254, 14
	v_readlane_b32 s45, v254, 15
	s_waitcnt vmcnt(0)
	v_and_or_b32 v144, v142, 15, v143
	s_lshl_b64 s[28:29], s[28:29], 3
	v_lshl_add_u64 v[44:45], v[140:141], 2, s[44:45]
	s_add_u32 s28, s5, s28
	v_lshlrev_b64 v[140:141], 1, v[140:141]
	v_ashrrev_i32_e32 v145, 31, v144
	s_addc_u32 s29, s26, s29
	v_lshl_add_u64 v[142:143], s[70:71], 0, v[140:141]
	v_lshl_add_u64 v[146:147], v[144:145], 2, s[6:7]
	v_lshlrev_b64 v[154:155], 5, v[144:145]
	v_lshlrev_b64 v[190:191], 12, v[144:145]
	global_load_dwordx4 v[68:71], v[44:45], off
	global_load_dwordx4 v[60:63], v[44:45], off offset:64
	global_load_dwordx4 v[52:55], v[44:45], off offset:128
	s_nop 0
	global_load_dwordx4 v[44:47], v[44:45], off offset:192
	v_lshl_add_u64 v[154:155], s[28:29], 0, v[154:155]
	global_load_dword v202, v[146:147], off
	global_load_dwordx2 v[184:185], v[154:155], off
	v_lshl_add_u64 v[146:147], v[142:143], 0, v[190:191]
	global_load_dwordx2 v[196:197], v[146:147], off
	global_load_dwordx2 v[198:199], v[146:147], off offset:32
	global_load_dwordx2 v[200:201], v[146:147], off offset:64
	global_load_dwordx2 v[192:193], v[146:147], off offset:96
	v_or_b32_e32 v146, 16, v144
	v_ashrrev_i32_e32 v147, 31, v146
	v_lshlrev_b64 v[188:189], 12, v[146:147]
	v_lshl_add_u64 v[154:155], v[146:147], 2, s[6:7]
	v_lshlrev_b64 v[156:157], 5, v[146:147]
	v_lshl_add_u64 v[146:147], v[142:143], 0, v[188:189]
	v_lshl_add_u64 v[156:157], s[28:29], 0, v[156:157]
	global_load_dword v195, v[154:155], off
	global_load_dwordx2 v[172:173], v[156:157], off
	global_load_dwordx2 v[186:187], v[146:147], off
	global_load_dwordx2 v[182:183], v[146:147], off offset:32
	global_load_dwordx2 v[180:181], v[146:147], off offset:64
	global_load_dwordx2 v[178:179], v[146:147], off offset:96
	v_or_b32_e32 v146, 32, v144
	v_ashrrev_i32_e32 v147, 31, v146
	v_lshl_add_u64 v[154:155], v[146:147], 2, s[6:7]
	v_lshlrev_b64 v[156:157], 5, v[146:147]
	v_lshl_add_u64 v[156:157], s[28:29], 0, v[156:157]
	global_load_dword v152, v[154:155], off
	global_load_dwordx2 v[160:161], v[156:157], off
	v_or_b32_e32 v154, 48, v144
	v_lshlrev_b64 v[176:177], 12, v[146:147]
	v_ashrrev_i32_e32 v155, 31, v154
	v_lshl_add_u64 v[146:147], v[142:143], 0, v[176:177]
	v_lshlrev_b64 v[156:157], 5, v[154:155]
	v_lshlrev_b64 v[164:165], 12, v[154:155]
	global_load_dwordx2 v[174:175], v[146:147], off
	global_load_dwordx2 v[170:171], v[146:147], off offset:32
	global_load_dwordx2 v[168:169], v[146:147], off offset:64
	global_load_dwordx2 v[166:167], v[146:147], off offset:96
	v_lshl_add_u64 v[146:147], v[154:155], 2, s[6:7]
	v_lshl_add_u64 v[156:157], s[28:29], 0, v[156:157]
	v_lshl_add_u64 v[154:155], v[142:143], 0, v[164:165]
	global_load_dword v145, v[146:147], off
	s_nop 0
	global_load_dwordx2 v[146:147], v[156:157], off
	global_load_dwordx2 v[162:163], v[154:155], off
	global_load_dwordx2 v[158:159], v[154:155], off offset:32
	s_nop 0
	global_load_dwordx2 v[156:157], v[154:155], off offset:64
	s_nop 0
	global_load_dwordx2 v[154:155], v[154:155], off offset:96
	v_readlane_b32 s37, v254, 7
	v_readlane_b32 s38, v254, 8
	v_readlane_b32 s39, v254, 9
	v_readlane_b32 s40, v254, 10
	v_readlane_b32 s41, v254, 11
	v_readlane_b32 s42, v254, 12
	v_readlane_b32 s43, v254, 13
	v_readlane_b32 s46, v254, 16
	v_readlane_b32 s47, v254, 17
	v_readlane_b32 s48, v254, 18
	v_readlane_b32 s49, v254, 19
	v_readlane_b32 s50, v254, 20
	v_readlane_b32 s51, v254, 21
	v_lshl_add_u64 v[140:141], s[8:9], 0, v[140:141]
	s_waitcnt vmcnt(23)
	v_mul_f32_e32 v148, v148, v202
	v_mul_f32_e32 v205, 0xbfb8aa3b, v148
	v_exp_f32_e32 v205, v205
	v_mul_f32_e32 v149, v149, v202
	v_mul_f32_e32 v206, 0xbfb8aa3b, v149
	v_exp_f32_e32 v206, v206
	v_add_f32_e32 v205, 1.0, v205
	v_rcp_f32_e32 v205, v205
	s_waitcnt vmcnt(21)
	v_lshlrev_b32_e32 v203, 16, v196
	v_mul_f32_e32 v150, v150, v202
	v_sub_f32_e32 v203, v203, v184
	v_mul_f32_e32 v148, v148, v205
	v_add_f32_e32 v205, 1.0, v206
	v_rcp_f32_e32 v205, v205
	v_mul_f32_e32 v148, v148, v203
	v_mul_f32_e32 v203, 0xbfb8aa3b, v150
	v_exp_f32_e32 v203, v203
	v_and_b32_e32 v196, 0xffff0000, v196
	v_mul_f32_e32 v151, v151, v202
	v_mul_f32_e32 v149, v149, v205
	v_sub_f32_e32 v196, v196, v184
	v_mul_f32_e32 v149, v149, v196
	v_add_f32_e32 v196, 1.0, v203
	v_mul_f32_e32 v203, 0xbfb8aa3b, v151
	v_exp_f32_e32 v203, v203
	v_rcp_f32_e32 v196, v196
	v_lshlrev_b32_e32 v204, 16, v197
	v_and_b32_e32 v197, 0xffff0000, v197
	v_add_f32_e32 v203, 1.0, v203
	v_rcp_f32_e32 v203, v203
	v_mul_f32_e32 v150, v150, v196
	v_sub_f32_e32 v196, v204, v184
	v_mul_f32_e32 v150, v150, v196
	v_mul_f32_e32 v151, v151, v203
	v_sub_f32_e32 v196, v197, v184
	v_mul_f32_e32 v151, v151, v196
	v_mul_f32_e32 v148, v185, v148
	v_mul_f32_e32 v149, v185, v149
	v_mul_f32_e32 v151, v185, v151
	v_mul_f32_e32 v148, v68, v148
	v_mul_f32_e32 v149, v69, v149
	v_mul_f32_e32 v150, v185, v150
	v_mul_f32_e32 v151, v71, v151
	v_mul_f32_e32 v136, v136, v202
	v_mul_f32_e32 v150, v70, v150
	v_cvt_pk_bf16_f32 v148, v148, v149
	v_cvt_pk_bf16_f32 v149, v150, v151
	v_mul_f32_e32 v151, 0xbfb8aa3b, v136
	v_exp_f32_e32 v151, v151
	v_mul_f32_e32 v137, v137, v202
	v_mul_f32_e32 v197, 0xbfb8aa3b, v137
	v_exp_f32_e32 v197, v197
	v_add_f32_e32 v151, 1.0, v151
	v_rcp_f32_e32 v151, v151
	v_lshl_add_u64 v[190:191], v[140:141], 0, v[190:191]
	global_store_dwordx2 v[190:191], v[148:149], off
	s_waitcnt vmcnt(21)
	v_lshlrev_b32_e32 v148, 16, v198
	v_mul_f32_e32 v136, v136, v151
	v_add_f32_e32 v151, 1.0, v197
	v_rcp_f32_e32 v151, v151
	v_and_b32_e32 v149, 0xffff0000, v198
	v_mul_f32_e32 v138, v138, v202
	v_sub_f32_e32 v148, v148, v184
	v_mul_f32_e32 v139, v139, v202
	v_mul_f32_e32 v136, v136, v148
	v_mul_f32_e32 v137, v137, v151
	v_mul_f32_e32 v148, 0xbfb8aa3b, v138
	v_sub_f32_e32 v149, v149, v184
	v_exp_f32_e32 v148, v148
	v_mul_f32_e32 v137, v137, v149
	v_mul_f32_e32 v149, 0xbfb8aa3b, v139
	v_exp_f32_e32 v149, v149
	v_add_f32_e32 v148, 1.0, v148
	v_rcp_f32_e32 v148, v148
	v_lshlrev_b32_e32 v150, 16, v199
	v_add_f32_e32 v149, 1.0, v149
	v_rcp_f32_e32 v149, v149
	v_and_b32_e32 v196, 0xffff0000, v199
	v_mul_f32_e32 v138, v138, v148
	v_sub_f32_e32 v148, v150, v184
	v_mul_f32_e32 v138, v138, v148
	v_mul_f32_e32 v139, v139, v149
	v_sub_f32_e32 v148, v196, v184
	v_mul_f32_e32 v139, v139, v148
	v_mul_f32_e32 v136, v185, v136
	v_mul_f32_e32 v137, v185, v137
	v_mul_f32_e32 v139, v185, v139
	v_mul_f32_e32 v136, v60, v136
	v_mul_f32_e32 v137, v61, v137
	v_mul_f32_e32 v138, v185, v138
	v_mul_f32_e32 v139, v63, v139
	v_mul_f32_e32 v132, v132, v202
	v_mul_f32_e32 v138, v62, v138
	v_cvt_pk_bf16_f32 v136, v136, v137
	v_cvt_pk_bf16_f32 v137, v138, v139
	v_mul_f32_e32 v139, 0xbfb8aa3b, v132
	v_exp_f32_e32 v139, v139
	v_mul_f32_e32 v133, v133, v202
	v_mul_f32_e32 v149, 0xbfb8aa3b, v133
	v_exp_f32_e32 v149, v149
	v_add_f32_e32 v139, 1.0, v139
	v_rcp_f32_e32 v139, v139
	global_store_dwordx2 v[190:191], v[136:137], off offset:32
	s_waitcnt vmcnt(21)
	v_lshlrev_b32_e32 v136, 16, v200
	v_and_b32_e32 v137, 0xffff0000, v200
	v_mul_f32_e32 v132, v132, v139
	v_add_f32_e32 v139, 1.0, v149
	v_rcp_f32_e32 v139, v139
	v_mul_f32_e32 v134, v134, v202
	v_sub_f32_e32 v136, v136, v184
	v_mul_f32_e32 v135, v135, v202
	v_mul_f32_e32 v132, v132, v136
	v_mul_f32_e32 v133, v133, v139
	v_mul_f32_e32 v136, 0xbfb8aa3b, v134
	v_sub_f32_e32 v137, v137, v184
	v_exp_f32_e32 v136, v136
	v_mul_f32_e32 v133, v133, v137
	v_mul_f32_e32 v137, 0xbfb8aa3b, v135
	v_exp_f32_e32 v137, v137
	v_add_f32_e32 v136, 1.0, v136
	v_rcp_f32_e32 v136, v136
	v_lshlrev_b32_e32 v138, 16, v201
	v_add_f32_e32 v137, 1.0, v137
	v_rcp_f32_e32 v137, v137
	v_and_b32_e32 v148, 0xffff0000, v201
	v_mul_f32_e32 v134, v134, v136
	v_sub_f32_e32 v136, v138, v184
	v_mul_f32_e32 v134, v134, v136
	v_mul_f32_e32 v135, v135, v137
	v_sub_f32_e32 v136, v148, v184
	v_mul_f32_e32 v135, v135, v136
	v_mul_f32_e32 v132, v185, v132
	v_mul_f32_e32 v133, v185, v133
	v_mul_f32_e32 v135, v185, v135
	v_mul_f32_e32 v132, v52, v132
	v_mul_f32_e32 v133, v53, v133
	v_mul_f32_e32 v134, v185, v134
	v_mul_f32_e32 v135, v55, v135
	v_mul_f32_e32 v128, v128, v202
	v_mul_f32_e32 v134, v54, v134
	v_cvt_pk_bf16_f32 v132, v132, v133
	v_cvt_pk_bf16_f32 v133, v134, v135
	v_mul_f32_e32 v135, 0xbfb8aa3b, v128
	v_exp_f32_e32 v135, v135
	v_mul_f32_e32 v129, v129, v202
	v_mul_f32_e32 v137, 0xbfb8aa3b, v129
	v_exp_f32_e32 v137, v137
	v_add_f32_e32 v135, 1.0, v135
	v_rcp_f32_e32 v135, v135
	global_store_dwordx2 v[190:191], v[132:133], off offset:64
	s_waitcnt vmcnt(21)
	v_and_b32_e32 v133, 0xffff0000, v192
	v_mul_f32_e32 v131, v131, v202
	v_mul_f32_e32 v128, v128, v135
	v_add_f32_e32 v135, 1.0, v137
	v_rcp_f32_e32 v135, v135
	v_sub_f32_e32 v133, v133, v184
	v_lshlrev_b32_e32 v132, 16, v192
	v_mul_f32_e32 v130, v130, v202
	v_mul_f32_e32 v129, v129, v135
	v_mul_f32_e32 v129, v129, v133
	v_mul_f32_e32 v133, 0xbfb8aa3b, v131
	v_exp_f32_e32 v133, v133
	v_sub_f32_e32 v132, v132, v184
	v_mul_f32_e32 v128, v128, v132
	v_mul_f32_e32 v132, 0xbfb8aa3b, v130
	v_add_f32_e32 v133, 1.0, v133
	v_rcp_f32_e32 v133, v133
	s_waitcnt vmcnt(20)
	v_mul_f32_e32 v124, v124, v195
	v_exp_f32_e32 v132, v132
	v_mul_f32_e32 v125, v125, v195
	v_mul_f32_e32 v131, v131, v133
	v_mul_f32_e32 v133, 0xbfb8aa3b, v124
	v_exp_f32_e32 v133, v133
	v_add_f32_e32 v132, 1.0, v132
	v_rcp_f32_e32 v132, v132
	v_mul_f32_e32 v135, 0xbfb8aa3b, v125
	v_add_f32_e32 v133, 1.0, v133
	v_rcp_f32_e32 v133, v133
	v_exp_f32_e32 v135, v135
	v_lshlrev_b32_e32 v134, 16, v193
	v_and_b32_e32 v136, 0xffff0000, v193
	v_mul_f32_e32 v130, v130, v132
	v_sub_f32_e32 v132, v134, v184
	v_mul_f32_e32 v130, v130, v132
	v_sub_f32_e32 v132, v136, v184
	v_mul_f32_e32 v124, v124, v133
	v_add_f32_e32 v133, 1.0, v135
	v_mul_f32_e32 v128, v185, v128
	v_mul_f32_e32 v129, v185, v129
	v_mul_f32_e32 v130, v185, v130
	v_mul_f32_e32 v131, v131, v132
	v_rcp_f32_e32 v133, v133
	v_mul_f32_e32 v128, v44, v128
	v_mul_f32_e32 v129, v45, v129
	v_mul_f32_e32 v130, v46, v130
	v_mul_f32_e32 v131, v185, v131
	v_mul_f32_e32 v131, v47, v131
	v_cvt_pk_bf16_f32 v128, v128, v129
	v_cvt_pk_bf16_f32 v129, v130, v131
	s_waitcnt vmcnt(18)
	v_lshlrev_b32_e32 v130, 16, v186
	v_and_b32_e32 v131, 0xffff0000, v186
	v_mul_f32_e32 v126, v126, v195
	v_sub_f32_e32 v130, v130, v172
	v_mul_f32_e32 v127, v127, v195
	v_mul_f32_e32 v124, v124, v130
	v_mul_f32_e32 v125, v125, v133
	v_mul_f32_e32 v130, 0xbfb8aa3b, v126
	v_sub_f32_e32 v131, v131, v172
	v_exp_f32_e32 v130, v130
	v_mul_f32_e32 v125, v125, v131
	v_mul_f32_e32 v131, 0xbfb8aa3b, v127
	v_exp_f32_e32 v131, v131
	v_add_f32_e32 v130, 1.0, v130
	v_rcp_f32_e32 v130, v130
	v_lshlrev_b32_e32 v132, 16, v187
	v_add_f32_e32 v131, 1.0, v131
	v_rcp_f32_e32 v131, v131
	v_and_b32_e32 v134, 0xffff0000, v187
	v_mul_f32_e32 v126, v126, v130
	v_sub_f32_e32 v130, v132, v172
	v_mul_f32_e32 v126, v126, v130
	v_mul_f32_e32 v127, v127, v131
	v_sub_f32_e32 v130, v134, v172
	v_mul_f32_e32 v127, v127, v130
	v_mul_f32_e32 v124, v173, v124
	v_mul_f32_e32 v125, v173, v125
	v_mul_f32_e32 v127, v173, v127
	v_mul_f32_e32 v124, v68, v124
	v_mul_f32_e32 v125, v69, v125
	v_mul_f32_e32 v126, v173, v126
	v_mul_f32_e32 v127, v71, v127
	v_mul_f32_e32 v120, v120, v195
	v_mul_f32_e32 v126, v70, v126
	v_cvt_pk_bf16_f32 v124, v124, v125
	v_cvt_pk_bf16_f32 v125, v126, v127
	v_mul_f32_e32 v127, 0xbfb8aa3b, v120
	v_exp_f32_e32 v127, v127
	v_mul_f32_e32 v121, v121, v195
	v_mul_f32_e32 v131, 0xbfb8aa3b, v121
	v_exp_f32_e32 v131, v131
	v_add_f32_e32 v127, 1.0, v127
	v_rcp_f32_e32 v127, v127
	global_store_dwordx2 v[190:191], v[128:129], off offset:96
	v_lshl_add_u64 v[128:129], v[140:141], 0, v[188:189]
	global_store_dwordx2 v[128:129], v[124:125], off
	v_mul_f32_e32 v120, v120, v127
	v_add_f32_e32 v127, 1.0, v131
	v_rcp_f32_e32 v127, v127
	s_waitcnt vmcnt(19)
	v_lshlrev_b32_e32 v124, 16, v182
	v_and_b32_e32 v125, 0xffff0000, v182
	v_mul_f32_e32 v122, v122, v195
	v_sub_f32_e32 v124, v124, v172
	v_mul_f32_e32 v123, v123, v195
	v_mul_f32_e32 v120, v120, v124
	v_mul_f32_e32 v121, v121, v127
	v_mul_f32_e32 v124, 0xbfb8aa3b, v122
	v_sub_f32_e32 v125, v125, v172
	v_exp_f32_e32 v124, v124
	v_mul_f32_e32 v121, v121, v125
	v_mul_f32_e32 v125, 0xbfb8aa3b, v123
	v_exp_f32_e32 v125, v125
	v_add_f32_e32 v124, 1.0, v124
	v_rcp_f32_e32 v124, v124
	v_lshlrev_b32_e32 v126, 16, v183
	v_add_f32_e32 v125, 1.0, v125
	v_rcp_f32_e32 v125, v125
	v_and_b32_e32 v130, 0xffff0000, v183
	v_mul_f32_e32 v122, v122, v124
	v_sub_f32_e32 v124, v126, v172
	v_mul_f32_e32 v122, v122, v124
	v_mul_f32_e32 v123, v123, v125
	v_sub_f32_e32 v124, v130, v172
	v_mul_f32_e32 v123, v123, v124
	v_mul_f32_e32 v120, v173, v120
	v_mul_f32_e32 v121, v173, v121
	v_mul_f32_e32 v123, v173, v123
	v_mul_f32_e32 v120, v60, v120
	v_mul_f32_e32 v121, v61, v121
	v_mul_f32_e32 v122, v173, v122
	v_mul_f32_e32 v123, v63, v123
	v_mul_f32_e32 v116, v116, v195
	v_mul_f32_e32 v122, v62, v122
	v_cvt_pk_bf16_f32 v120, v120, v121
	v_cvt_pk_bf16_f32 v121, v122, v123
	v_mul_f32_e32 v123, 0xbfb8aa3b, v116
	v_exp_f32_e32 v123, v123
	v_mul_f32_e32 v117, v117, v195
	v_mul_f32_e32 v125, 0xbfb8aa3b, v117
	v_exp_f32_e32 v125, v125
	v_add_f32_e32 v123, 1.0, v123
	v_rcp_f32_e32 v123, v123
	global_store_dwordx2 v[128:129], v[120:121], off offset:32
	s_waitcnt vmcnt(19)
	v_lshlrev_b32_e32 v120, 16, v180
	v_and_b32_e32 v121, 0xffff0000, v180
	v_mul_f32_e32 v116, v116, v123
	v_add_f32_e32 v123, 1.0, v125
	v_rcp_f32_e32 v123, v123
	v_mul_f32_e32 v118, v118, v195
	v_sub_f32_e32 v120, v120, v172
	v_mul_f32_e32 v119, v119, v195
	v_mul_f32_e32 v116, v116, v120
	v_mul_f32_e32 v117, v117, v123
	v_mul_f32_e32 v120, 0xbfb8aa3b, v118
	v_sub_f32_e32 v121, v121, v172
	v_exp_f32_e32 v120, v120
	v_mul_f32_e32 v117, v117, v121
	v_mul_f32_e32 v121, 0xbfb8aa3b, v119
	v_exp_f32_e32 v121, v121
	v_add_f32_e32 v120, 1.0, v120
	v_rcp_f32_e32 v120, v120
	v_lshlrev_b32_e32 v122, 16, v181
	v_add_f32_e32 v121, 1.0, v121
	v_rcp_f32_e32 v121, v121
	v_and_b32_e32 v124, 0xffff0000, v181
	v_mul_f32_e32 v118, v118, v120
	v_sub_f32_e32 v120, v122, v172
	v_mul_f32_e32 v118, v118, v120
	v_mul_f32_e32 v119, v119, v121
	v_sub_f32_e32 v120, v124, v172
	v_mul_f32_e32 v119, v119, v120
	v_mul_f32_e32 v116, v173, v116
	v_mul_f32_e32 v117, v173, v117
	v_mul_f32_e32 v119, v173, v119
	v_mul_f32_e32 v116, v52, v116
	v_mul_f32_e32 v117, v53, v117
	v_mul_f32_e32 v118, v173, v118
	v_mul_f32_e32 v119, v55, v119
	v_mul_f32_e32 v112, v112, v195
	v_mul_f32_e32 v118, v54, v118
	v_cvt_pk_bf16_f32 v116, v116, v117
	v_cvt_pk_bf16_f32 v117, v118, v119
	v_mul_f32_e32 v119, 0xbfb8aa3b, v112
	v_exp_f32_e32 v119, v119
	v_mul_f32_e32 v113, v113, v195
	v_mul_f32_e32 v121, 0xbfb8aa3b, v113
	v_exp_f32_e32 v121, v121
	v_add_f32_e32 v119, 1.0, v119
	v_rcp_f32_e32 v119, v119
	global_store_dwordx2 v[128:129], v[116:117], off offset:64
	s_waitcnt vmcnt(19)
	v_and_b32_e32 v117, 0xffff0000, v178
	v_mul_f32_e32 v115, v115, v195
	v_mul_f32_e32 v112, v112, v119
	v_add_f32_e32 v119, 1.0, v121
	v_rcp_f32_e32 v119, v119
	v_sub_f32_e32 v117, v117, v172
	v_lshlrev_b32_e32 v116, 16, v178
	v_mul_f32_e32 v114, v114, v195
	v_mul_f32_e32 v113, v113, v119
	v_mul_f32_e32 v113, v113, v117
	v_mul_f32_e32 v117, 0xbfb8aa3b, v115
	v_exp_f32_e32 v117, v117
	v_sub_f32_e32 v116, v116, v172
	v_mul_f32_e32 v112, v112, v116
	v_mul_f32_e32 v116, 0xbfb8aa3b, v114
	v_add_f32_e32 v117, 1.0, v117
	v_rcp_f32_e32 v117, v117
	s_waitcnt vmcnt(18)
	v_mul_f32_e32 v108, v108, v152
	v_exp_f32_e32 v116, v116
	v_mul_f32_e32 v109, v109, v152
	v_mul_f32_e32 v115, v115, v117
	v_mul_f32_e32 v117, 0xbfb8aa3b, v108
	v_exp_f32_e32 v117, v117
	v_add_f32_e32 v116, 1.0, v116
	v_rcp_f32_e32 v116, v116
	v_mul_f32_e32 v119, 0xbfb8aa3b, v109
	v_add_f32_e32 v117, 1.0, v117
	v_rcp_f32_e32 v117, v117
	v_exp_f32_e32 v119, v119
	v_lshlrev_b32_e32 v118, 16, v179
	v_and_b32_e32 v120, 0xffff0000, v179
	v_mul_f32_e32 v114, v114, v116
	v_sub_f32_e32 v116, v118, v172
	v_mul_f32_e32 v114, v114, v116
	v_sub_f32_e32 v116, v120, v172
	v_mul_f32_e32 v108, v108, v117
	v_add_f32_e32 v117, 1.0, v119
	v_mul_f32_e32 v112, v173, v112
	v_mul_f32_e32 v113, v173, v113
	v_mul_f32_e32 v114, v173, v114
	v_mul_f32_e32 v115, v115, v116
	v_rcp_f32_e32 v117, v117
	v_mul_f32_e32 v112, v44, v112
	v_mul_f32_e32 v113, v45, v113
	v_mul_f32_e32 v114, v46, v114
	v_mul_f32_e32 v115, v173, v115
	v_mul_f32_e32 v115, v47, v115
	v_cvt_pk_bf16_f32 v112, v112, v113
	v_cvt_pk_bf16_f32 v113, v114, v115
	s_waitcnt vmcnt(16)
	v_lshlrev_b32_e32 v114, 16, v174
	v_and_b32_e32 v115, 0xffff0000, v174
	v_mul_f32_e32 v110, v110, v152
	v_sub_f32_e32 v114, v114, v160
	v_mul_f32_e32 v111, v111, v152
	v_mul_f32_e32 v108, v108, v114
	v_mul_f32_e32 v109, v109, v117
	v_mul_f32_e32 v114, 0xbfb8aa3b, v110
	v_sub_f32_e32 v115, v115, v160
	v_exp_f32_e32 v114, v114
	v_mul_f32_e32 v109, v109, v115
	v_mul_f32_e32 v115, 0xbfb8aa3b, v111
	v_exp_f32_e32 v115, v115
	v_add_f32_e32 v114, 1.0, v114
	v_rcp_f32_e32 v114, v114
	v_lshlrev_b32_e32 v116, 16, v175
	v_add_f32_e32 v115, 1.0, v115
	v_rcp_f32_e32 v115, v115
	v_and_b32_e32 v118, 0xffff0000, v175
	v_mul_f32_e32 v110, v110, v114
	v_sub_f32_e32 v114, v116, v160
	v_mul_f32_e32 v110, v110, v114
	v_mul_f32_e32 v111, v111, v115
	v_sub_f32_e32 v114, v118, v160
	v_mul_f32_e32 v111, v111, v114
	v_mul_f32_e32 v108, v161, v108
	v_mul_f32_e32 v109, v161, v109
	v_mul_f32_e32 v111, v161, v111
	v_mul_f32_e32 v108, v68, v108
	v_mul_f32_e32 v109, v69, v109
	v_mul_f32_e32 v110, v161, v110
	v_mul_f32_e32 v111, v71, v111
	v_mul_f32_e32 v104, v104, v152
	v_mul_f32_e32 v110, v70, v110
	v_cvt_pk_bf16_f32 v108, v108, v109
	v_cvt_pk_bf16_f32 v109, v110, v111
	v_mul_f32_e32 v111, 0xbfb8aa3b, v104
	v_exp_f32_e32 v111, v111
	v_mul_f32_e32 v105, v105, v152
	v_mul_f32_e32 v115, 0xbfb8aa3b, v105
	v_exp_f32_e32 v115, v115
	v_add_f32_e32 v111, 1.0, v111
	v_rcp_f32_e32 v111, v111
	global_store_dwordx2 v[128:129], v[112:113], off offset:96
	v_lshl_add_u64 v[112:113], v[140:141], 0, v[176:177]
	global_store_dwordx2 v[112:113], v[108:109], off
	v_mul_f32_e32 v104, v104, v111
	v_add_f32_e32 v111, 1.0, v115
	v_rcp_f32_e32 v111, v111
	s_waitcnt vmcnt(17)
	v_lshlrev_b32_e32 v108, 16, v170
	v_and_b32_e32 v109, 0xffff0000, v170
	v_mul_f32_e32 v106, v106, v152
	v_sub_f32_e32 v108, v108, v160
	v_mul_f32_e32 v107, v107, v152
	v_mul_f32_e32 v104, v104, v108
	v_mul_f32_e32 v105, v105, v111
	v_mul_f32_e32 v108, 0xbfb8aa3b, v106
	v_sub_f32_e32 v109, v109, v160
	v_exp_f32_e32 v108, v108
	v_mul_f32_e32 v105, v105, v109
	v_mul_f32_e32 v109, 0xbfb8aa3b, v107
	v_exp_f32_e32 v109, v109
	v_add_f32_e32 v108, 1.0, v108
	v_rcp_f32_e32 v108, v108
	v_lshlrev_b32_e32 v110, 16, v171
	v_add_f32_e32 v109, 1.0, v109
	v_rcp_f32_e32 v109, v109
	v_and_b32_e32 v114, 0xffff0000, v171
	v_mul_f32_e32 v106, v106, v108
	v_sub_f32_e32 v108, v110, v160
	v_mul_f32_e32 v106, v106, v108
	v_mul_f32_e32 v107, v107, v109
	v_sub_f32_e32 v108, v114, v160
	v_mul_f32_e32 v107, v107, v108
	v_mul_f32_e32 v104, v161, v104
	v_mul_f32_e32 v105, v161, v105
	v_mul_f32_e32 v107, v161, v107
	v_mul_f32_e32 v104, v60, v104
	v_mul_f32_e32 v105, v61, v105
	v_mul_f32_e32 v106, v161, v106
	v_mul_f32_e32 v107, v63, v107
	v_mul_f32_e32 v100, v100, v152
	v_mul_f32_e32 v106, v62, v106
	v_cvt_pk_bf16_f32 v104, v104, v105
	v_cvt_pk_bf16_f32 v105, v106, v107
	v_mul_f32_e32 v107, 0xbfb8aa3b, v100
	v_exp_f32_e32 v107, v107
	v_mul_f32_e32 v101, v101, v152
	v_mul_f32_e32 v109, 0xbfb8aa3b, v101
	v_exp_f32_e32 v109, v109
	v_add_f32_e32 v107, 1.0, v107
	v_rcp_f32_e32 v107, v107
	global_store_dwordx2 v[112:113], v[104:105], off offset:32
	s_waitcnt vmcnt(17)
	v_lshlrev_b32_e32 v104, 16, v168
	v_and_b32_e32 v105, 0xffff0000, v168
	v_mul_f32_e32 v100, v100, v107
	v_add_f32_e32 v107, 1.0, v109
	v_rcp_f32_e32 v107, v107
	v_mul_f32_e32 v102, v102, v152
	v_sub_f32_e32 v104, v104, v160
	v_mul_f32_e32 v103, v103, v152
	v_mul_f32_e32 v100, v100, v104
	v_mul_f32_e32 v101, v101, v107
	v_mul_f32_e32 v104, 0xbfb8aa3b, v102
	v_sub_f32_e32 v105, v105, v160
	v_exp_f32_e32 v104, v104
	v_mul_f32_e32 v101, v101, v105
	v_mul_f32_e32 v105, 0xbfb8aa3b, v103
	v_exp_f32_e32 v105, v105
	v_add_f32_e32 v104, 1.0, v104
	v_rcp_f32_e32 v104, v104
	v_lshlrev_b32_e32 v106, 16, v169
	v_add_f32_e32 v105, 1.0, v105
	v_rcp_f32_e32 v105, v105
	v_and_b32_e32 v108, 0xffff0000, v169
	v_mul_f32_e32 v102, v102, v104
	v_sub_f32_e32 v104, v106, v160
	v_mul_f32_e32 v102, v102, v104
	v_mul_f32_e32 v103, v103, v105
	v_sub_f32_e32 v104, v108, v160
	v_mul_f32_e32 v103, v103, v104
	v_mul_f32_e32 v100, v161, v100
	v_mul_f32_e32 v101, v161, v101
	v_mul_f32_e32 v103, v161, v103
	v_mul_f32_e32 v100, v52, v100
	v_mul_f32_e32 v101, v53, v101
	v_mul_f32_e32 v102, v161, v102
	v_mul_f32_e32 v103, v55, v103
	v_mul_f32_e32 v96, v96, v152
	v_mul_f32_e32 v102, v54, v102
	v_cvt_pk_bf16_f32 v100, v100, v101
	v_cvt_pk_bf16_f32 v101, v102, v103
	v_mul_f32_e32 v103, 0xbfb8aa3b, v96
	v_exp_f32_e32 v103, v103
	v_mul_f32_e32 v97, v97, v152
	v_mul_f32_e32 v105, 0xbfb8aa3b, v97
	v_exp_f32_e32 v105, v105
	v_add_f32_e32 v103, 1.0, v103
	v_rcp_f32_e32 v103, v103
	global_store_dwordx2 v[112:113], v[100:101], off offset:64
	s_waitcnt vmcnt(17)
	v_and_b32_e32 v101, 0xffff0000, v166
	v_mul_f32_e32 v99, v99, v152
	v_mul_f32_e32 v96, v96, v103
	v_add_f32_e32 v103, 1.0, v105
	v_rcp_f32_e32 v103, v103
	v_sub_f32_e32 v101, v101, v160
	v_lshlrev_b32_e32 v100, 16, v166
	v_mul_f32_e32 v98, v98, v152
	v_mul_f32_e32 v97, v97, v103
	v_mul_f32_e32 v97, v97, v101
	v_mul_f32_e32 v101, 0xbfb8aa3b, v99
	v_exp_f32_e32 v101, v101
	v_sub_f32_e32 v100, v100, v160
	v_mul_f32_e32 v96, v96, v100
	v_mul_f32_e32 v100, 0xbfb8aa3b, v98
	v_add_f32_e32 v101, 1.0, v101
	v_rcp_f32_e32 v101, v101
	s_waitcnt vmcnt(16)
	v_mul_f32_e32 v92, v92, v145
	v_exp_f32_e32 v100, v100
	v_mul_f32_e32 v93, v93, v145
	v_mul_f32_e32 v99, v99, v101
	v_mul_f32_e32 v101, 0xbfb8aa3b, v92
	v_exp_f32_e32 v101, v101
	v_add_f32_e32 v100, 1.0, v100
	v_rcp_f32_e32 v100, v100
	v_mul_f32_e32 v103, 0xbfb8aa3b, v93
	v_add_f32_e32 v101, 1.0, v101
	v_rcp_f32_e32 v101, v101
	v_exp_f32_e32 v103, v103
	v_lshlrev_b32_e32 v102, 16, v167
	v_and_b32_e32 v104, 0xffff0000, v167
	v_mul_f32_e32 v98, v98, v100
	v_sub_f32_e32 v100, v102, v160
	v_mul_f32_e32 v98, v98, v100
	v_sub_f32_e32 v100, v104, v160
	v_mul_f32_e32 v92, v92, v101
	v_add_f32_e32 v101, 1.0, v103
	v_mul_f32_e32 v96, v161, v96
	v_mul_f32_e32 v97, v161, v97
	v_mul_f32_e32 v98, v161, v98
	v_mul_f32_e32 v99, v99, v100
	v_rcp_f32_e32 v101, v101
	v_mul_f32_e32 v96, v44, v96
	v_mul_f32_e32 v97, v45, v97
	v_mul_f32_e32 v98, v46, v98
	v_mul_f32_e32 v99, v161, v99
	v_mul_f32_e32 v99, v47, v99
	v_cvt_pk_bf16_f32 v96, v96, v97
	v_cvt_pk_bf16_f32 v97, v98, v99
	s_waitcnt vmcnt(14)
	v_lshlrev_b32_e32 v98, 16, v162
	v_and_b32_e32 v99, 0xffff0000, v162
	v_mul_f32_e32 v94, v94, v145
	v_sub_f32_e32 v98, v98, v146
	v_mul_f32_e32 v95, v95, v145
	v_mul_f32_e32 v92, v92, v98
	v_mul_f32_e32 v93, v93, v101
	v_mul_f32_e32 v98, 0xbfb8aa3b, v94
	v_sub_f32_e32 v99, v99, v146
	v_exp_f32_e32 v98, v98
	v_mul_f32_e32 v93, v93, v99
	v_mul_f32_e32 v99, 0xbfb8aa3b, v95
	v_exp_f32_e32 v99, v99
	v_add_f32_e32 v98, 1.0, v98
	v_rcp_f32_e32 v98, v98
	v_lshlrev_b32_e32 v100, 16, v163
	v_add_f32_e32 v99, 1.0, v99
	v_rcp_f32_e32 v99, v99
	v_and_b32_e32 v102, 0xffff0000, v163
	v_mul_f32_e32 v94, v94, v98
	v_sub_f32_e32 v98, v100, v146
	v_mul_f32_e32 v94, v94, v98
	v_mul_f32_e32 v95, v95, v99
	v_sub_f32_e32 v98, v102, v146
	v_mul_f32_e32 v95, v95, v98
	v_mul_f32_e32 v92, v147, v92
	v_mul_f32_e32 v93, v147, v93
	v_mul_f32_e32 v95, v147, v95
	v_mul_f32_e32 v92, v68, v92
	v_mul_f32_e32 v93, v69, v93
	v_mul_f32_e32 v94, v147, v94
	v_mul_f32_e32 v95, v71, v95
	v_mul_f32_e32 v88, v88, v145
	v_mul_f32_e32 v94, v70, v94
	v_cvt_pk_bf16_f32 v92, v92, v93
	v_cvt_pk_bf16_f32 v93, v94, v95
	v_mul_f32_e32 v95, 0xbfb8aa3b, v88
	v_exp_f32_e32 v95, v95
	v_mul_f32_e32 v89, v89, v145
	v_mul_f32_e32 v99, 0xbfb8aa3b, v89
	v_exp_f32_e32 v99, v99
	v_add_f32_e32 v95, 1.0, v95
	v_rcp_f32_e32 v95, v95
	global_store_dwordx2 v[112:113], v[96:97], off offset:96
	v_lshl_add_u64 v[96:97], v[140:141], 0, v[164:165]
	global_store_dwordx2 v[96:97], v[92:93], off
	v_mul_f32_e32 v88, v88, v95
	v_add_f32_e32 v95, 1.0, v99
	v_rcp_f32_e32 v95, v95
	s_waitcnt vmcnt(15)
	v_lshlrev_b32_e32 v92, 16, v158
	v_and_b32_e32 v93, 0xffff0000, v158
	v_mul_f32_e32 v90, v90, v145
	v_sub_f32_e32 v92, v92, v146
	v_mul_f32_e32 v91, v91, v145
	v_mul_f32_e32 v88, v88, v92
	v_mul_f32_e32 v89, v89, v95
	v_mul_f32_e32 v92, 0xbfb8aa3b, v90
	v_sub_f32_e32 v93, v93, v146
	v_exp_f32_e32 v92, v92
	v_mul_f32_e32 v89, v89, v93
	v_mul_f32_e32 v93, 0xbfb8aa3b, v91
	v_exp_f32_e32 v93, v93
	v_add_f32_e32 v92, 1.0, v92
	v_rcp_f32_e32 v92, v92
	v_lshlrev_b32_e32 v94, 16, v159
	v_add_f32_e32 v93, 1.0, v93
	v_rcp_f32_e32 v93, v93
	v_and_b32_e32 v98, 0xffff0000, v159
	v_mul_f32_e32 v90, v90, v92
	v_sub_f32_e32 v92, v94, v146
	v_mul_f32_e32 v90, v90, v92
	v_mul_f32_e32 v91, v91, v93
	v_sub_f32_e32 v92, v98, v146
	v_mul_f32_e32 v91, v91, v92
	v_mul_f32_e32 v88, v147, v88
	v_mul_f32_e32 v89, v147, v89
	v_mul_f32_e32 v91, v147, v91
	v_mul_f32_e32 v88, v60, v88
	v_mul_f32_e32 v89, v61, v89
	v_mul_f32_e32 v90, v147, v90
	v_mul_f32_e32 v91, v63, v91
	v_mul_f32_e32 v84, v84, v145
	v_mul_f32_e32 v90, v62, v90
	v_cvt_pk_bf16_f32 v88, v88, v89
	v_cvt_pk_bf16_f32 v89, v90, v91
	v_mul_f32_e32 v91, 0xbfb8aa3b, v84
	v_exp_f32_e32 v91, v91
	v_mul_f32_e32 v85, v85, v145
	v_mul_f32_e32 v93, 0xbfb8aa3b, v85
	v_exp_f32_e32 v93, v93
	v_add_f32_e32 v91, 1.0, v91
	v_rcp_f32_e32 v91, v91
	global_store_dwordx2 v[96:97], v[88:89], off offset:32
	s_waitcnt vmcnt(15)
	v_lshlrev_b32_e32 v88, 16, v156
	v_and_b32_e32 v89, 0xffff0000, v156
	v_mul_f32_e32 v84, v84, v91
	v_add_f32_e32 v91, 1.0, v93
	v_rcp_f32_e32 v91, v91
	v_mul_f32_e32 v86, v86, v145
	v_sub_f32_e32 v88, v88, v146
	v_mul_f32_e32 v87, v87, v145
	v_mul_f32_e32 v84, v84, v88
	v_mul_f32_e32 v85, v85, v91
	v_mul_f32_e32 v88, 0xbfb8aa3b, v86
	v_sub_f32_e32 v89, v89, v146
	v_exp_f32_e32 v88, v88
	v_mul_f32_e32 v85, v85, v89
	v_mul_f32_e32 v89, 0xbfb8aa3b, v87
	v_exp_f32_e32 v89, v89
	v_add_f32_e32 v88, 1.0, v88
	v_rcp_f32_e32 v88, v88
	v_lshlrev_b32_e32 v90, 16, v157
	v_add_f32_e32 v89, 1.0, v89
	v_rcp_f32_e32 v89, v89
	v_and_b32_e32 v92, 0xffff0000, v157
	v_mul_f32_e32 v86, v86, v88
	v_sub_f32_e32 v88, v90, v146
	v_mul_f32_e32 v86, v86, v88
	v_mul_f32_e32 v87, v87, v89
	v_sub_f32_e32 v88, v92, v146
	v_mul_f32_e32 v87, v87, v88
	v_mul_f32_e32 v84, v147, v84
	v_mul_f32_e32 v85, v147, v85
	v_mul_f32_e32 v87, v147, v87
	v_mul_f32_e32 v84, v52, v84
	v_mul_f32_e32 v85, v53, v85
	v_mul_f32_e32 v86, v147, v86
	v_mul_f32_e32 v87, v55, v87
	v_mul_f32_e32 v80, v80, v145
	v_mul_f32_e32 v86, v54, v86
	v_cvt_pk_bf16_f32 v84, v84, v85
	v_cvt_pk_bf16_f32 v85, v86, v87
	v_mul_f32_e32 v87, 0xbfb8aa3b, v80
	v_exp_f32_e32 v87, v87
	v_mul_f32_e32 v81, v81, v145
	v_mul_f32_e32 v89, 0xbfb8aa3b, v81
	v_exp_f32_e32 v89, v89
	v_add_f32_e32 v87, 1.0, v87
	v_rcp_f32_e32 v87, v87
	global_store_dwordx2 v[96:97], v[84:85], off offset:64
	s_waitcnt vmcnt(15)
	v_lshlrev_b32_e32 v84, 16, v154
	v_and_b32_e32 v85, 0xffff0000, v154
	v_mul_f32_e32 v80, v80, v87
	v_add_f32_e32 v87, 1.0, v89
	v_rcp_f32_e32 v87, v87
	v_mul_f32_e32 v82, v82, v145
	v_sub_f32_e32 v84, v84, v146
	v_mul_f32_e32 v83, v83, v145
	v_mul_f32_e32 v80, v80, v84
	v_mul_f32_e32 v81, v81, v87
	v_mul_f32_e32 v84, 0xbfb8aa3b, v82
	v_sub_f32_e32 v85, v85, v146
	v_exp_f32_e32 v84, v84
	v_mul_f32_e32 v81, v81, v85
	v_mul_f32_e32 v85, 0xbfb8aa3b, v83
	v_exp_f32_e32 v85, v85
	v_add_f32_e32 v84, 1.0, v84
	v_rcp_f32_e32 v84, v84
	v_lshlrev_b32_e32 v86, 16, v155
	v_add_f32_e32 v85, 1.0, v85
	v_rcp_f32_e32 v85, v85
	v_and_b32_e32 v88, 0xffff0000, v155
	v_mul_f32_e32 v82, v82, v84
	v_sub_f32_e32 v84, v86, v146
	v_mul_f32_e32 v82, v82, v84
	v_mul_f32_e32 v83, v83, v85
	v_sub_f32_e32 v84, v88, v146
	v_mul_f32_e32 v80, v147, v80
	v_mul_f32_e32 v81, v147, v81
	v_mul_f32_e32 v83, v83, v84
	v_mul_f32_e32 v80, v44, v80
	v_mul_f32_e32 v81, v45, v81
	v_mul_f32_e32 v82, v147, v82
	v_mul_f32_e32 v83, v147, v83
	v_mul_f32_e32 v82, v46, v82
	v_mul_f32_e32 v83, v47, v83
	v_cvt_pk_bf16_f32 v80, v80, v81
	v_cvt_pk_bf16_f32 v81, v82, v83
	global_store_dwordx2 v[96:97], v[80:81], off offset:96
	v_or_b32_e32 v80, 64, v144
	v_ashrrev_i32_e32 v81, 31, v80
	v_lshlrev_b64 v[118:119], 12, v[80:81]
	v_lshl_add_u64 v[82:83], v[80:81], 2, s[6:7]
	v_lshlrev_b64 v[84:85], 5, v[80:81]
	v_lshl_add_u64 v[80:81], v[142:143], 0, v[118:119]
	v_lshl_add_u64 v[84:85], s[28:29], 0, v[84:85]
	global_load_dword v125, v[82:83], off
	global_load_dwordx2 v[112:113], v[84:85], off
	global_load_dwordx2 v[126:127], v[80:81], off
	global_load_dwordx2 v[128:129], v[80:81], off offset:32
	global_load_dwordx2 v[130:131], v[80:81], off offset:64
	global_load_dwordx2 v[120:121], v[80:81], off offset:96
	v_or_b32_e32 v80, 0x50, v144
	v_ashrrev_i32_e32 v81, 31, v80
	v_lshlrev_b64 v[116:117], 12, v[80:81]
	v_lshl_add_u64 v[82:83], v[80:81], 2, s[6:7]
	v_lshlrev_b64 v[84:85], 5, v[80:81]
	v_lshl_add_u64 v[80:81], v[142:143], 0, v[116:117]
	v_lshl_add_u64 v[84:85], s[28:29], 0, v[84:85]
	global_load_dword v124, v[82:83], off
	global_load_dwordx2 v[100:101], v[84:85], off
	global_load_dwordx2 v[114:115], v[80:81], off
	global_load_dwordx2 v[110:111], v[80:81], off offset:32
	global_load_dwordx2 v[108:109], v[80:81], off offset:64
	global_load_dwordx2 v[106:107], v[80:81], off offset:96
	v_or_b32_e32 v80, 0x60, v144
	v_ashrrev_i32_e32 v81, 31, v80
	v_lshl_add_u64 v[82:83], v[80:81], 2, s[6:7]
	v_lshlrev_b64 v[84:85], 5, v[80:81]
	v_lshl_add_u64 v[84:85], s[28:29], 0, v[84:85]
	global_load_dword v123, v[82:83], off
	global_load_dwordx2 v[88:89], v[84:85], off
	v_or_b32_e32 v82, 0x70, v144
	v_lshlrev_b64 v[104:105], 12, v[80:81]
	v_ashrrev_i32_e32 v83, 31, v82
	v_lshl_add_u64 v[80:81], v[142:143], 0, v[104:105]
	v_lshlrev_b64 v[84:85], 5, v[82:83]
	v_lshlrev_b64 v[92:93], 12, v[82:83]
	global_load_dwordx2 v[102:103], v[80:81], off
	global_load_dwordx2 v[98:99], v[80:81], off offset:32
	global_load_dwordx2 v[96:97], v[80:81], off offset:64
	global_load_dwordx2 v[94:95], v[80:81], off offset:96
	v_lshl_add_u64 v[80:81], v[82:83], 2, s[6:7]
	v_lshl_add_u64 v[84:85], s[28:29], 0, v[84:85]
	v_lshl_add_u64 v[82:83], v[142:143], 0, v[92:93]
	global_load_dword v122, v[80:81], off
	s_nop 0
	global_load_dwordx2 v[80:81], v[84:85], off
	global_load_dwordx2 v[90:91], v[82:83], off
	global_load_dwordx2 v[86:87], v[82:83], off offset:32
	s_nop 0
	global_load_dwordx2 v[84:85], v[82:83], off offset:64
	s_nop 0
	global_load_dwordx2 v[82:83], v[82:83], off offset:96
	s_waitcnt vmcnt(23)
	v_mul_f32_e32 v76, v76, v125
	v_mul_f32_e32 v134, 0xbfb8aa3b, v76
	v_exp_f32_e32 v134, v134
	v_mul_f32_e32 v77, v77, v125
	v_mul_f32_e32 v135, 0xbfb8aa3b, v77
	v_exp_f32_e32 v135, v135
	v_add_f32_e32 v134, 1.0, v134
	v_rcp_f32_e32 v134, v134
	s_waitcnt vmcnt(21)
	v_lshlrev_b32_e32 v132, 16, v126
	v_mul_f32_e32 v78, v78, v125
	v_sub_f32_e32 v132, v132, v112
	v_mul_f32_e32 v76, v76, v134
	v_add_f32_e32 v134, 1.0, v135
	v_rcp_f32_e32 v134, v134
	v_mul_f32_e32 v76, v76, v132
	v_mul_f32_e32 v132, 0xbfb8aa3b, v78
	v_exp_f32_e32 v132, v132
	v_and_b32_e32 v126, 0xffff0000, v126
	v_mul_f32_e32 v79, v79, v125
	v_mul_f32_e32 v77, v77, v134
	v_sub_f32_e32 v126, v126, v112
	v_mul_f32_e32 v77, v77, v126
	v_add_f32_e32 v126, 1.0, v132
	v_mul_f32_e32 v132, 0xbfb8aa3b, v79
	v_exp_f32_e32 v132, v132
	v_rcp_f32_e32 v126, v126
	v_lshlrev_b32_e32 v133, 16, v127
	v_and_b32_e32 v127, 0xffff0000, v127
	v_add_f32_e32 v132, 1.0, v132
	v_rcp_f32_e32 v132, v132
	v_mul_f32_e32 v78, v78, v126
	v_sub_f32_e32 v126, v133, v112
	v_mul_f32_e32 v78, v78, v126
	v_mul_f32_e32 v79, v79, v132
	v_sub_f32_e32 v126, v127, v112
	v_mul_f32_e32 v79, v79, v126
	v_mul_f32_e32 v76, v113, v76
	v_mul_f32_e32 v77, v113, v77
	v_mul_f32_e32 v79, v113, v79
	v_mul_f32_e32 v76, v68, v76
	v_mul_f32_e32 v77, v69, v77
	v_mul_f32_e32 v78, v113, v78
	v_mul_f32_e32 v79, v71, v79
	v_mul_f32_e32 v72, v72, v125
	v_mul_f32_e32 v78, v70, v78
	v_cvt_pk_bf16_f32 v76, v76, v77
	v_cvt_pk_bf16_f32 v77, v78, v79
	v_mul_f32_e32 v79, 0xbfb8aa3b, v72
	v_exp_f32_e32 v79, v79
	v_mul_f32_e32 v73, v73, v125
	v_mul_f32_e32 v127, 0xbfb8aa3b, v73
	v_exp_f32_e32 v127, v127
	v_add_f32_e32 v79, 1.0, v79
	v_rcp_f32_e32 v79, v79
	v_lshl_add_u64 v[118:119], v[140:141], 0, v[118:119]
	global_store_dwordx2 v[118:119], v[76:77], off
	s_waitcnt vmcnt(21)
	v_lshlrev_b32_e32 v76, 16, v128
	v_mul_f32_e32 v72, v72, v79
	v_add_f32_e32 v79, 1.0, v127
	v_rcp_f32_e32 v79, v79
	v_and_b32_e32 v77, 0xffff0000, v128
	v_mul_f32_e32 v74, v74, v125
	v_sub_f32_e32 v76, v76, v112
	v_mul_f32_e32 v75, v75, v125
	v_mul_f32_e32 v72, v72, v76
	v_mul_f32_e32 v73, v73, v79
	v_mul_f32_e32 v76, 0xbfb8aa3b, v74
	v_sub_f32_e32 v77, v77, v112
	v_exp_f32_e32 v76, v76
	v_mul_f32_e32 v73, v73, v77
	v_mul_f32_e32 v77, 0xbfb8aa3b, v75
	v_exp_f32_e32 v77, v77
	v_add_f32_e32 v76, 1.0, v76
	v_rcp_f32_e32 v76, v76
	v_lshlrev_b32_e32 v78, 16, v129
	v_add_f32_e32 v77, 1.0, v77
	v_rcp_f32_e32 v77, v77
	v_and_b32_e32 v126, 0xffff0000, v129
	v_mul_f32_e32 v74, v74, v76
	v_sub_f32_e32 v76, v78, v112
	v_mul_f32_e32 v74, v74, v76
	v_mul_f32_e32 v75, v75, v77
	v_sub_f32_e32 v76, v126, v112
	v_mul_f32_e32 v75, v75, v76
	v_mul_f32_e32 v72, v113, v72
	v_mul_f32_e32 v73, v113, v73
	v_mul_f32_e32 v75, v113, v75
	v_mul_f32_e32 v72, v60, v72
	v_mul_f32_e32 v73, v61, v73
	v_mul_f32_e32 v74, v113, v74
	v_mul_f32_e32 v75, v63, v75
	v_mul_f32_e32 v64, v64, v125
	v_mul_f32_e32 v74, v62, v74
	v_cvt_pk_bf16_f32 v72, v72, v73
	v_cvt_pk_bf16_f32 v73, v74, v75
	v_mul_f32_e32 v75, 0xbfb8aa3b, v64
	v_exp_f32_e32 v75, v75
	v_mul_f32_e32 v65, v65, v125
	v_mul_f32_e32 v77, 0xbfb8aa3b, v65
	v_exp_f32_e32 v77, v77
	v_add_f32_e32 v75, 1.0, v75
	v_rcp_f32_e32 v75, v75
	global_store_dwordx2 v[118:119], v[72:73], off offset:32
	s_waitcnt vmcnt(21)
	v_lshlrev_b32_e32 v72, 16, v130
	v_and_b32_e32 v73, 0xffff0000, v130
	v_mul_f32_e32 v64, v64, v75
	v_add_f32_e32 v75, 1.0, v77
	v_rcp_f32_e32 v75, v75
	v_mul_f32_e32 v66, v66, v125
	v_sub_f32_e32 v72, v72, v112
	v_mul_f32_e32 v67, v67, v125
	v_mul_f32_e32 v64, v64, v72
	v_mul_f32_e32 v65, v65, v75
	v_mul_f32_e32 v72, 0xbfb8aa3b, v66
	v_sub_f32_e32 v73, v73, v112
	v_exp_f32_e32 v72, v72
	v_mul_f32_e32 v65, v65, v73
	v_mul_f32_e32 v73, 0xbfb8aa3b, v67
	v_exp_f32_e32 v73, v73
	v_add_f32_e32 v72, 1.0, v72
	v_rcp_f32_e32 v72, v72
	v_lshlrev_b32_e32 v74, 16, v131
	v_add_f32_e32 v73, 1.0, v73
	v_rcp_f32_e32 v73, v73
	v_and_b32_e32 v76, 0xffff0000, v131
	v_mul_f32_e32 v66, v66, v72
	v_sub_f32_e32 v72, v74, v112
	v_mul_f32_e32 v66, v66, v72
	v_mul_f32_e32 v67, v67, v73
	v_sub_f32_e32 v72, v76, v112
	v_mul_f32_e32 v67, v67, v72
	v_mul_f32_e32 v64, v113, v64
	v_mul_f32_e32 v65, v113, v65
	v_mul_f32_e32 v67, v113, v67
	v_mul_f32_e32 v64, v52, v64
	v_mul_f32_e32 v65, v53, v65
	v_mul_f32_e32 v66, v113, v66
	v_mul_f32_e32 v67, v55, v67
	v_mul_f32_e32 v56, v56, v125
	v_mul_f32_e32 v66, v54, v66
	v_cvt_pk_bf16_f32 v64, v64, v65
	v_cvt_pk_bf16_f32 v65, v66, v67
	v_mul_f32_e32 v67, 0xbfb8aa3b, v56
	v_exp_f32_e32 v67, v67
	v_mul_f32_e32 v57, v57, v125
	v_mul_f32_e32 v73, 0xbfb8aa3b, v57
	v_exp_f32_e32 v73, v73
	v_add_f32_e32 v67, 1.0, v67
	v_rcp_f32_e32 v67, v67
	global_store_dwordx2 v[118:119], v[64:65], off offset:64
	s_waitcnt vmcnt(21)
	v_and_b32_e32 v65, 0xffff0000, v120
	v_mul_f32_e32 v59, v59, v125
	v_mul_f32_e32 v56, v56, v67
	v_add_f32_e32 v67, 1.0, v73
	v_rcp_f32_e32 v67, v67
	v_sub_f32_e32 v65, v65, v112
	v_lshlrev_b32_e32 v64, 16, v120
	v_mul_f32_e32 v58, v58, v125
	v_mul_f32_e32 v57, v57, v67
	v_mul_f32_e32 v57, v57, v65
	v_mul_f32_e32 v65, 0xbfb8aa3b, v59
	v_exp_f32_e32 v65, v65
	v_sub_f32_e32 v64, v64, v112
	v_mul_f32_e32 v56, v56, v64
	v_mul_f32_e32 v64, 0xbfb8aa3b, v58
	v_add_f32_e32 v65, 1.0, v65
	v_rcp_f32_e32 v65, v65
	s_waitcnt vmcnt(20)
	v_mul_f32_e32 v48, v48, v124
	v_exp_f32_e32 v64, v64
	v_mul_f32_e32 v49, v49, v124
	v_mul_f32_e32 v59, v59, v65
	v_mul_f32_e32 v65, 0xbfb8aa3b, v48
	v_exp_f32_e32 v65, v65
	v_add_f32_e32 v64, 1.0, v64
	v_rcp_f32_e32 v64, v64
	v_mul_f32_e32 v67, 0xbfb8aa3b, v49
	v_add_f32_e32 v65, 1.0, v65
	v_rcp_f32_e32 v65, v65
	v_exp_f32_e32 v67, v67
	v_lshlrev_b32_e32 v66, 16, v121
	v_and_b32_e32 v72, 0xffff0000, v121
	v_mul_f32_e32 v58, v58, v64
	v_sub_f32_e32 v64, v66, v112
	v_mul_f32_e32 v58, v58, v64
	v_sub_f32_e32 v64, v72, v112
	v_mul_f32_e32 v48, v48, v65
	v_add_f32_e32 v65, 1.0, v67
	v_mul_f32_e32 v56, v113, v56
	v_mul_f32_e32 v57, v113, v57
	v_mul_f32_e32 v58, v113, v58
	v_mul_f32_e32 v59, v59, v64
	v_rcp_f32_e32 v65, v65
	v_mul_f32_e32 v56, v44, v56
	v_mul_f32_e32 v57, v45, v57
	v_mul_f32_e32 v58, v46, v58
	v_mul_f32_e32 v59, v113, v59
	v_mul_f32_e32 v59, v47, v59
	v_cvt_pk_bf16_f32 v56, v56, v57
	v_cvt_pk_bf16_f32 v57, v58, v59
	s_waitcnt vmcnt(18)
	v_lshlrev_b32_e32 v58, 16, v114
	v_and_b32_e32 v59, 0xffff0000, v114
	v_mul_f32_e32 v50, v50, v124
	v_sub_f32_e32 v58, v58, v100
	v_mul_f32_e32 v51, v51, v124
	v_mul_f32_e32 v48, v48, v58
	v_mul_f32_e32 v49, v49, v65
	v_mul_f32_e32 v58, 0xbfb8aa3b, v50
	v_sub_f32_e32 v59, v59, v100
	v_exp_f32_e32 v58, v58
	v_mul_f32_e32 v49, v49, v59
	v_mul_f32_e32 v59, 0xbfb8aa3b, v51
	v_exp_f32_e32 v59, v59
	v_add_f32_e32 v58, 1.0, v58
	v_rcp_f32_e32 v58, v58
	v_lshlrev_b32_e32 v64, 16, v115
	v_add_f32_e32 v59, 1.0, v59
	v_rcp_f32_e32 v59, v59
	v_and_b32_e32 v66, 0xffff0000, v115
	v_mul_f32_e32 v50, v50, v58
	v_sub_f32_e32 v58, v64, v100
	v_mul_f32_e32 v50, v50, v58
	v_mul_f32_e32 v51, v51, v59
	v_sub_f32_e32 v58, v66, v100
	v_mul_f32_e32 v51, v51, v58
	v_mul_f32_e32 v48, v101, v48
	v_mul_f32_e32 v49, v101, v49
	v_mul_f32_e32 v51, v101, v51
	v_mul_f32_e32 v48, v68, v48
	v_mul_f32_e32 v49, v69, v49
	v_mul_f32_e32 v50, v101, v50
	v_mul_f32_e32 v51, v71, v51
	v_mul_f32_e32 v40, v40, v124
	v_mul_f32_e32 v50, v70, v50
	v_cvt_pk_bf16_f32 v48, v48, v49
	v_cvt_pk_bf16_f32 v49, v50, v51
	v_mul_f32_e32 v51, 0xbfb8aa3b, v40
	v_exp_f32_e32 v51, v51
	v_mul_f32_e32 v41, v41, v124
	v_mul_f32_e32 v59, 0xbfb8aa3b, v41
	v_exp_f32_e32 v59, v59
	v_add_f32_e32 v51, 1.0, v51
	v_rcp_f32_e32 v51, v51
	global_store_dwordx2 v[118:119], v[56:57], off offset:96
	v_lshl_add_u64 v[56:57], v[140:141], 0, v[116:117]
	global_store_dwordx2 v[56:57], v[48:49], off
	v_mul_f32_e32 v40, v40, v51
	v_add_f32_e32 v51, 1.0, v59
	v_rcp_f32_e32 v51, v51
	s_waitcnt vmcnt(19)
	v_lshlrev_b32_e32 v48, 16, v110
	v_and_b32_e32 v49, 0xffff0000, v110
	v_mul_f32_e32 v42, v42, v124
	v_sub_f32_e32 v48, v48, v100
	v_mul_f32_e32 v43, v43, v124
	v_mul_f32_e32 v40, v40, v48
	v_mul_f32_e32 v41, v41, v51
	v_mul_f32_e32 v48, 0xbfb8aa3b, v42
	v_sub_f32_e32 v49, v49, v100
	v_exp_f32_e32 v48, v48
	v_mul_f32_e32 v41, v41, v49
	v_mul_f32_e32 v49, 0xbfb8aa3b, v43
	v_exp_f32_e32 v49, v49
	v_add_f32_e32 v48, 1.0, v48
	v_rcp_f32_e32 v48, v48
	v_lshlrev_b32_e32 v50, 16, v111
	v_add_f32_e32 v49, 1.0, v49
	v_rcp_f32_e32 v49, v49
	v_and_b32_e32 v58, 0xffff0000, v111
	v_mul_f32_e32 v42, v42, v48
	v_sub_f32_e32 v48, v50, v100
	v_mul_f32_e32 v42, v42, v48
	v_mul_f32_e32 v43, v43, v49
	v_sub_f32_e32 v48, v58, v100
	v_mul_f32_e32 v43, v43, v48
	v_mul_f32_e32 v40, v101, v40
	v_mul_f32_e32 v41, v101, v41
	v_mul_f32_e32 v43, v101, v43
	v_mul_f32_e32 v40, v60, v40
	v_mul_f32_e32 v41, v61, v41
	v_mul_f32_e32 v42, v101, v42
	v_mul_f32_e32 v43, v63, v43
	v_mul_f32_e32 v36, v36, v124
	v_mul_f32_e32 v42, v62, v42
	v_cvt_pk_bf16_f32 v40, v40, v41
	v_cvt_pk_bf16_f32 v41, v42, v43
	v_mul_f32_e32 v43, 0xbfb8aa3b, v36
	v_exp_f32_e32 v43, v43
	v_mul_f32_e32 v37, v37, v124
	v_mul_f32_e32 v49, 0xbfb8aa3b, v37
	v_exp_f32_e32 v49, v49
	v_add_f32_e32 v43, 1.0, v43
	v_rcp_f32_e32 v43, v43
	global_store_dwordx2 v[56:57], v[40:41], off offset:32
	s_waitcnt vmcnt(19)
	v_lshlrev_b32_e32 v40, 16, v108
	v_and_b32_e32 v41, 0xffff0000, v108
	v_mul_f32_e32 v36, v36, v43
	v_add_f32_e32 v43, 1.0, v49
	v_rcp_f32_e32 v43, v43
	v_mul_f32_e32 v38, v38, v124
	v_sub_f32_e32 v40, v40, v100
	v_mul_f32_e32 v39, v39, v124
	v_mul_f32_e32 v36, v36, v40
	v_mul_f32_e32 v37, v37, v43
	v_mul_f32_e32 v40, 0xbfb8aa3b, v38
	v_sub_f32_e32 v41, v41, v100
	v_exp_f32_e32 v40, v40
	v_mul_f32_e32 v37, v37, v41
	v_mul_f32_e32 v41, 0xbfb8aa3b, v39
	v_exp_f32_e32 v41, v41
	v_add_f32_e32 v40, 1.0, v40
	v_rcp_f32_e32 v40, v40
	v_lshlrev_b32_e32 v42, 16, v109
	v_add_f32_e32 v41, 1.0, v41
	v_rcp_f32_e32 v41, v41
	v_and_b32_e32 v48, 0xffff0000, v109
	v_mul_f32_e32 v38, v38, v40
	v_sub_f32_e32 v40, v42, v100
	v_mul_f32_e32 v38, v38, v40
	v_mul_f32_e32 v39, v39, v41
	v_sub_f32_e32 v40, v48, v100
	v_mul_f32_e32 v39, v39, v40
	v_mul_f32_e32 v36, v101, v36
	v_mul_f32_e32 v37, v101, v37
	v_mul_f32_e32 v39, v101, v39
	v_mul_f32_e32 v36, v52, v36
	v_mul_f32_e32 v37, v53, v37
	v_mul_f32_e32 v38, v101, v38
	v_mul_f32_e32 v39, v55, v39
	v_mul_f32_e32 v32, v32, v124
	v_mul_f32_e32 v38, v54, v38
	v_cvt_pk_bf16_f32 v36, v36, v37
	v_cvt_pk_bf16_f32 v37, v38, v39
	v_mul_f32_e32 v39, 0xbfb8aa3b, v32
	v_exp_f32_e32 v39, v39
	v_mul_f32_e32 v33, v33, v124
	v_mul_f32_e32 v41, 0xbfb8aa3b, v33
	v_exp_f32_e32 v41, v41
	v_add_f32_e32 v39, 1.0, v39
	v_rcp_f32_e32 v39, v39
	global_store_dwordx2 v[56:57], v[36:37], off offset:64
	s_waitcnt vmcnt(19)
	v_and_b32_e32 v37, 0xffff0000, v106
	v_mul_f32_e32 v35, v35, v124
	v_mul_f32_e32 v32, v32, v39
	v_add_f32_e32 v39, 1.0, v41
	v_rcp_f32_e32 v39, v39
	v_sub_f32_e32 v37, v37, v100
	v_lshlrev_b32_e32 v36, 16, v106
	v_mul_f32_e32 v34, v34, v124
	v_mul_f32_e32 v33, v33, v39
	v_mul_f32_e32 v33, v33, v37
	v_mul_f32_e32 v37, 0xbfb8aa3b, v35
	v_exp_f32_e32 v37, v37
	v_sub_f32_e32 v36, v36, v100
	v_mul_f32_e32 v32, v32, v36
	v_mul_f32_e32 v36, 0xbfb8aa3b, v34
	v_add_f32_e32 v37, 1.0, v37
	v_rcp_f32_e32 v37, v37
	s_waitcnt vmcnt(18)
	v_mul_f32_e32 v28, v28, v123
	v_exp_f32_e32 v36, v36
	v_mul_f32_e32 v29, v29, v123
	v_mul_f32_e32 v35, v35, v37
	v_mul_f32_e32 v37, 0xbfb8aa3b, v28
	v_exp_f32_e32 v37, v37
	v_add_f32_e32 v36, 1.0, v36
	v_rcp_f32_e32 v36, v36
	v_mul_f32_e32 v39, 0xbfb8aa3b, v29
	v_add_f32_e32 v37, 1.0, v37
	v_rcp_f32_e32 v37, v37
	v_exp_f32_e32 v39, v39
	v_lshlrev_b32_e32 v38, 16, v107
	v_and_b32_e32 v40, 0xffff0000, v107
	v_mul_f32_e32 v34, v34, v36
	v_sub_f32_e32 v36, v38, v100
	v_mul_f32_e32 v34, v34, v36
	v_sub_f32_e32 v36, v40, v100
	v_mul_f32_e32 v28, v28, v37
	v_add_f32_e32 v37, 1.0, v39
	v_mul_f32_e32 v32, v101, v32
	v_mul_f32_e32 v33, v101, v33
	v_mul_f32_e32 v34, v101, v34
	v_mul_f32_e32 v35, v35, v36
	v_rcp_f32_e32 v37, v37
	v_mul_f32_e32 v32, v44, v32
	v_mul_f32_e32 v33, v45, v33
	v_mul_f32_e32 v34, v46, v34
	v_mul_f32_e32 v35, v101, v35
	v_mul_f32_e32 v35, v47, v35
	v_cvt_pk_bf16_f32 v32, v32, v33
	v_cvt_pk_bf16_f32 v33, v34, v35
	s_waitcnt vmcnt(16)
	v_lshlrev_b32_e32 v34, 16, v102
	v_and_b32_e32 v35, 0xffff0000, v102
	v_mul_f32_e32 v30, v30, v123
	v_sub_f32_e32 v34, v34, v88
	v_mul_f32_e32 v31, v31, v123
	v_mul_f32_e32 v28, v28, v34
	v_mul_f32_e32 v29, v29, v37
	v_mul_f32_e32 v34, 0xbfb8aa3b, v30
	v_sub_f32_e32 v35, v35, v88
	v_exp_f32_e32 v34, v34
	v_mul_f32_e32 v29, v29, v35
	v_mul_f32_e32 v35, 0xbfb8aa3b, v31
	v_exp_f32_e32 v35, v35
	v_add_f32_e32 v34, 1.0, v34
	v_rcp_f32_e32 v34, v34
	v_lshlrev_b32_e32 v36, 16, v103
	v_add_f32_e32 v35, 1.0, v35
	v_rcp_f32_e32 v35, v35
	v_and_b32_e32 v38, 0xffff0000, v103
	v_mul_f32_e32 v30, v30, v34
	v_sub_f32_e32 v34, v36, v88
	v_mul_f32_e32 v30, v30, v34
	v_mul_f32_e32 v31, v31, v35
	v_sub_f32_e32 v34, v38, v88
	v_mul_f32_e32 v31, v31, v34
	v_mul_f32_e32 v28, v89, v28
	v_mul_f32_e32 v29, v89, v29
	v_mul_f32_e32 v31, v89, v31
	v_mul_f32_e32 v28, v68, v28
	v_mul_f32_e32 v29, v69, v29
	v_mul_f32_e32 v30, v89, v30
	v_mul_f32_e32 v31, v71, v31
	v_mul_f32_e32 v24, v24, v123
	v_mul_f32_e32 v30, v70, v30
	v_cvt_pk_bf16_f32 v28, v28, v29
	v_cvt_pk_bf16_f32 v29, v30, v31
	v_mul_f32_e32 v31, 0xbfb8aa3b, v24
	v_exp_f32_e32 v31, v31
	v_mul_f32_e32 v25, v25, v123
	v_mul_f32_e32 v35, 0xbfb8aa3b, v25
	v_exp_f32_e32 v35, v35
	v_add_f32_e32 v31, 1.0, v31
	v_rcp_f32_e32 v31, v31
	global_store_dwordx2 v[56:57], v[32:33], off offset:96
	v_lshl_add_u64 v[32:33], v[140:141], 0, v[104:105]
	global_store_dwordx2 v[32:33], v[28:29], off
	v_mul_f32_e32 v24, v24, v31
	v_add_f32_e32 v31, 1.0, v35
	v_rcp_f32_e32 v31, v31
	s_waitcnt vmcnt(17)
	v_lshlrev_b32_e32 v28, 16, v98
	v_and_b32_e32 v29, 0xffff0000, v98
	v_mul_f32_e32 v26, v26, v123
	v_sub_f32_e32 v28, v28, v88
	v_mul_f32_e32 v27, v27, v123
	v_mul_f32_e32 v24, v24, v28
	v_mul_f32_e32 v25, v25, v31
	v_mul_f32_e32 v28, 0xbfb8aa3b, v26
	v_sub_f32_e32 v29, v29, v88
	v_exp_f32_e32 v28, v28
	v_mul_f32_e32 v25, v25, v29
	v_mul_f32_e32 v29, 0xbfb8aa3b, v27
	v_exp_f32_e32 v29, v29
	v_add_f32_e32 v28, 1.0, v28
	v_rcp_f32_e32 v28, v28
	v_lshlrev_b32_e32 v30, 16, v99
	v_add_f32_e32 v29, 1.0, v29
	v_rcp_f32_e32 v29, v29
	v_and_b32_e32 v34, 0xffff0000, v99
	v_mul_f32_e32 v26, v26, v28
	v_sub_f32_e32 v28, v30, v88
	v_mul_f32_e32 v26, v26, v28
	v_mul_f32_e32 v27, v27, v29
	v_sub_f32_e32 v28, v34, v88
	v_mul_f32_e32 v27, v27, v28
	v_mul_f32_e32 v24, v89, v24
	v_mul_f32_e32 v25, v89, v25
	v_mul_f32_e32 v27, v89, v27
	v_mul_f32_e32 v24, v60, v24
	v_mul_f32_e32 v25, v61, v25
	v_mul_f32_e32 v26, v89, v26
	v_mul_f32_e32 v27, v63, v27
	v_mul_f32_e32 v20, v20, v123
	v_mul_f32_e32 v26, v62, v26
	v_cvt_pk_bf16_f32 v24, v24, v25
	v_cvt_pk_bf16_f32 v25, v26, v27
	v_mul_f32_e32 v27, 0xbfb8aa3b, v20
	v_exp_f32_e32 v27, v27
	v_mul_f32_e32 v21, v21, v123
	v_mul_f32_e32 v29, 0xbfb8aa3b, v21
	v_exp_f32_e32 v29, v29
	v_add_f32_e32 v27, 1.0, v27
	v_rcp_f32_e32 v27, v27
	global_store_dwordx2 v[32:33], v[24:25], off offset:32
	s_waitcnt vmcnt(17)
	v_lshlrev_b32_e32 v24, 16, v96
	v_and_b32_e32 v25, 0xffff0000, v96
	v_mul_f32_e32 v20, v20, v27
	v_add_f32_e32 v27, 1.0, v29
	v_rcp_f32_e32 v27, v27
	v_mul_f32_e32 v22, v22, v123
	v_sub_f32_e32 v24, v24, v88
	v_mul_f32_e32 v23, v23, v123
	v_mul_f32_e32 v20, v20, v24
	v_mul_f32_e32 v21, v21, v27
	v_mul_f32_e32 v24, 0xbfb8aa3b, v22
	v_sub_f32_e32 v25, v25, v88
	v_exp_f32_e32 v24, v24
	v_mul_f32_e32 v21, v21, v25
	v_mul_f32_e32 v25, 0xbfb8aa3b, v23
	v_exp_f32_e32 v25, v25
	v_add_f32_e32 v24, 1.0, v24
	v_rcp_f32_e32 v24, v24
	v_lshlrev_b32_e32 v26, 16, v97
	v_add_f32_e32 v25, 1.0, v25
	v_rcp_f32_e32 v25, v25
	v_and_b32_e32 v28, 0xffff0000, v97
	v_mul_f32_e32 v22, v22, v24
	v_sub_f32_e32 v24, v26, v88
	v_mul_f32_e32 v22, v22, v24
	v_mul_f32_e32 v23, v23, v25
	v_sub_f32_e32 v24, v28, v88
	v_mul_f32_e32 v23, v23, v24
	v_mul_f32_e32 v20, v89, v20
	v_mul_f32_e32 v21, v89, v21
	v_mul_f32_e32 v23, v89, v23
	v_mul_f32_e32 v20, v52, v20
	v_mul_f32_e32 v21, v53, v21
	v_mul_f32_e32 v22, v89, v22
	v_mul_f32_e32 v23, v55, v23
	v_mul_f32_e32 v16, v16, v123
	v_mul_f32_e32 v22, v54, v22
	v_cvt_pk_bf16_f32 v20, v20, v21
	v_cvt_pk_bf16_f32 v21, v22, v23
	v_mul_f32_e32 v23, 0xbfb8aa3b, v16
	v_exp_f32_e32 v23, v23
	v_mul_f32_e32 v17, v17, v123
	v_mul_f32_e32 v25, 0xbfb8aa3b, v17
	v_exp_f32_e32 v25, v25
	v_add_f32_e32 v23, 1.0, v23
	v_rcp_f32_e32 v23, v23
	global_store_dwordx2 v[32:33], v[20:21], off offset:64
	s_waitcnt vmcnt(17)
	v_and_b32_e32 v21, 0xffff0000, v94
	v_mul_f32_e32 v19, v19, v123
	v_mul_f32_e32 v16, v16, v23
	v_add_f32_e32 v23, 1.0, v25
	v_rcp_f32_e32 v23, v23
	v_sub_f32_e32 v21, v21, v88
	v_lshlrev_b32_e32 v20, 16, v94
	v_mul_f32_e32 v18, v18, v123
	v_mul_f32_e32 v17, v17, v23
	v_mul_f32_e32 v17, v17, v21
	v_mul_f32_e32 v21, 0xbfb8aa3b, v19
	v_exp_f32_e32 v21, v21
	v_sub_f32_e32 v20, v20, v88
	v_mul_f32_e32 v16, v16, v20
	v_mul_f32_e32 v20, 0xbfb8aa3b, v18
	v_add_f32_e32 v21, 1.0, v21
	v_rcp_f32_e32 v21, v21
	s_waitcnt vmcnt(16)
	v_mul_f32_e32 v12, v12, v122
	v_exp_f32_e32 v20, v20
	v_mul_f32_e32 v13, v13, v122
	v_mul_f32_e32 v19, v19, v21
	v_mul_f32_e32 v21, 0xbfb8aa3b, v12
	v_exp_f32_e32 v21, v21
	v_add_f32_e32 v20, 1.0, v20
	v_rcp_f32_e32 v20, v20
	v_mul_f32_e32 v23, 0xbfb8aa3b, v13
	v_add_f32_e32 v21, 1.0, v21
	v_rcp_f32_e32 v21, v21
	v_exp_f32_e32 v23, v23
	v_lshlrev_b32_e32 v22, 16, v95
	v_and_b32_e32 v24, 0xffff0000, v95
	v_mul_f32_e32 v18, v18, v20
	v_sub_f32_e32 v20, v22, v88
	v_mul_f32_e32 v18, v18, v20
	v_sub_f32_e32 v20, v24, v88
	v_mul_f32_e32 v12, v12, v21
	v_add_f32_e32 v21, 1.0, v23
	v_mul_f32_e32 v16, v89, v16
	v_mul_f32_e32 v17, v89, v17
	v_mul_f32_e32 v18, v89, v18
	v_mul_f32_e32 v19, v19, v20
	v_rcp_f32_e32 v21, v21
	v_mul_f32_e32 v16, v44, v16
	v_mul_f32_e32 v17, v45, v17
	v_mul_f32_e32 v18, v46, v18
	v_mul_f32_e32 v19, v89, v19
	v_mul_f32_e32 v19, v47, v19
	v_cvt_pk_bf16_f32 v16, v16, v17
	v_cvt_pk_bf16_f32 v17, v18, v19
	s_waitcnt vmcnt(14)
	v_lshlrev_b32_e32 v18, 16, v90
	v_and_b32_e32 v19, 0xffff0000, v90
	v_mul_f32_e32 v14, v14, v122
	v_sub_f32_e32 v18, v18, v80
	v_mul_f32_e32 v15, v15, v122
	v_mul_f32_e32 v12, v12, v18
	v_mul_f32_e32 v13, v13, v21
	v_mul_f32_e32 v18, 0xbfb8aa3b, v14
	v_sub_f32_e32 v19, v19, v80
	v_exp_f32_e32 v18, v18
	v_mul_f32_e32 v13, v13, v19
	v_mul_f32_e32 v19, 0xbfb8aa3b, v15
	v_exp_f32_e32 v19, v19
	v_add_f32_e32 v18, 1.0, v18
	v_rcp_f32_e32 v18, v18
	v_lshlrev_b32_e32 v20, 16, v91
	v_add_f32_e32 v19, 1.0, v19
	v_rcp_f32_e32 v19, v19
	v_and_b32_e32 v22, 0xffff0000, v91
	v_mul_f32_e32 v14, v14, v18
	v_sub_f32_e32 v18, v20, v80
	v_mul_f32_e32 v14, v14, v18
	v_mul_f32_e32 v15, v15, v19
	v_sub_f32_e32 v18, v22, v80
	v_mul_f32_e32 v15, v15, v18
	v_mul_f32_e32 v12, v81, v12
	v_mul_f32_e32 v13, v81, v13
	v_mul_f32_e32 v15, v81, v15
	v_mul_f32_e32 v12, v68, v12
	v_mul_f32_e32 v13, v69, v13
	v_mul_f32_e32 v14, v81, v14
	v_mul_f32_e32 v15, v71, v15
	v_mul_f32_e32 v8, v8, v122
	v_mul_f32_e32 v14, v70, v14
	v_cvt_pk_bf16_f32 v12, v12, v13
	v_cvt_pk_bf16_f32 v13, v14, v15
	v_mul_f32_e32 v15, 0xbfb8aa3b, v8
	v_exp_f32_e32 v15, v15
	v_mul_f32_e32 v9, v9, v122
	v_mul_f32_e32 v19, 0xbfb8aa3b, v9
	v_exp_f32_e32 v19, v19
	v_add_f32_e32 v15, 1.0, v15
	v_rcp_f32_e32 v15, v15
	global_store_dwordx2 v[32:33], v[16:17], off offset:96
	v_lshl_add_u64 v[16:17], v[140:141], 0, v[92:93]
	global_store_dwordx2 v[16:17], v[12:13], off
	v_mul_f32_e32 v8, v8, v15
	v_add_f32_e32 v15, 1.0, v19
	v_rcp_f32_e32 v15, v15
	s_waitcnt vmcnt(15)
	v_lshlrev_b32_e32 v12, 16, v86
	v_and_b32_e32 v13, 0xffff0000, v86
	v_mul_f32_e32 v10, v10, v122
	v_sub_f32_e32 v12, v12, v80
	v_mul_f32_e32 v11, v11, v122
	v_mul_f32_e32 v8, v8, v12
	v_mul_f32_e32 v9, v9, v15
	v_mul_f32_e32 v12, 0xbfb8aa3b, v10
	v_sub_f32_e32 v13, v13, v80
	v_exp_f32_e32 v12, v12
	v_mul_f32_e32 v9, v9, v13
	v_mul_f32_e32 v13, 0xbfb8aa3b, v11
	v_exp_f32_e32 v13, v13
	v_add_f32_e32 v12, 1.0, v12
	v_rcp_f32_e32 v12, v12
	v_lshlrev_b32_e32 v14, 16, v87
	v_add_f32_e32 v13, 1.0, v13
	v_rcp_f32_e32 v13, v13
	v_and_b32_e32 v18, 0xffff0000, v87
	v_mul_f32_e32 v10, v10, v12
	v_sub_f32_e32 v12, v14, v80
	v_mul_f32_e32 v10, v10, v12
	v_mul_f32_e32 v11, v11, v13
	v_sub_f32_e32 v12, v18, v80
	v_mul_f32_e32 v11, v11, v12
	v_mul_f32_e32 v8, v81, v8
	v_mul_f32_e32 v9, v81, v9
	v_mul_f32_e32 v11, v81, v11
	v_mul_f32_e32 v8, v60, v8
	v_mul_f32_e32 v9, v61, v9
	v_mul_f32_e32 v10, v81, v10
	v_mul_f32_e32 v11, v63, v11
	v_mul_f32_e32 v4, v4, v122
	v_mul_f32_e32 v10, v62, v10
	v_cvt_pk_bf16_f32 v8, v8, v9
	v_cvt_pk_bf16_f32 v9, v10, v11
	v_mul_f32_e32 v11, 0xbfb8aa3b, v4
	v_exp_f32_e32 v11, v11
	v_mul_f32_e32 v5, v5, v122
	v_mul_f32_e32 v13, 0xbfb8aa3b, v5
	v_exp_f32_e32 v13, v13
	v_add_f32_e32 v11, 1.0, v11
	v_rcp_f32_e32 v11, v11
	global_store_dwordx2 v[16:17], v[8:9], off offset:32
	s_waitcnt vmcnt(15)
	v_lshlrev_b32_e32 v8, 16, v84
	v_and_b32_e32 v9, 0xffff0000, v84
	v_mul_f32_e32 v4, v4, v11
	v_add_f32_e32 v11, 1.0, v13
	v_rcp_f32_e32 v11, v11
	v_mul_f32_e32 v6, v6, v122
	v_sub_f32_e32 v8, v8, v80
	v_mul_f32_e32 v7, v7, v122
	v_mul_f32_e32 v4, v4, v8
	v_mul_f32_e32 v5, v5, v11
	v_mul_f32_e32 v8, 0xbfb8aa3b, v6
	v_sub_f32_e32 v9, v9, v80
	v_exp_f32_e32 v8, v8
	v_mul_f32_e32 v5, v5, v9
	v_mul_f32_e32 v9, 0xbfb8aa3b, v7
	v_exp_f32_e32 v9, v9
	v_add_f32_e32 v8, 1.0, v8
	v_rcp_f32_e32 v8, v8
	v_lshlrev_b32_e32 v10, 16, v85
	v_add_f32_e32 v9, 1.0, v9
	v_rcp_f32_e32 v9, v9
	v_and_b32_e32 v12, 0xffff0000, v85
	v_mul_f32_e32 v6, v6, v8
	v_sub_f32_e32 v8, v10, v80
	v_mul_f32_e32 v6, v6, v8
	v_mul_f32_e32 v7, v7, v9
	v_sub_f32_e32 v8, v12, v80
	v_mul_f32_e32 v7, v7, v8
	v_mul_f32_e32 v4, v81, v4
	v_mul_f32_e32 v5, v81, v5
	v_mul_f32_e32 v7, v81, v7
	v_mul_f32_e32 v4, v52, v4
	v_mul_f32_e32 v5, v53, v5
	v_mul_f32_e32 v6, v81, v6
	v_mul_f32_e32 v7, v55, v7
	v_mul_f32_e32 v0, v0, v122
	v_mul_f32_e32 v6, v54, v6
	v_cvt_pk_bf16_f32 v4, v4, v5
	v_cvt_pk_bf16_f32 v5, v6, v7
	v_mul_f32_e32 v7, 0xbfb8aa3b, v0
	v_exp_f32_e32 v7, v7
	v_mul_f32_e32 v1, v1, v122
	v_mul_f32_e32 v9, 0xbfb8aa3b, v1
	v_exp_f32_e32 v9, v9
	v_add_f32_e32 v7, 1.0, v7
	v_rcp_f32_e32 v7, v7
	global_store_dwordx2 v[16:17], v[4:5], off offset:64
	s_waitcnt vmcnt(15)
	v_lshlrev_b32_e32 v4, 16, v82
	v_and_b32_e32 v5, 0xffff0000, v82
	v_mul_f32_e32 v0, v0, v7
	v_add_f32_e32 v7, 1.0, v9
	v_rcp_f32_e32 v7, v7
	v_mul_f32_e32 v2, v2, v122
	v_sub_f32_e32 v4, v4, v80
	v_mul_f32_e32 v3, v3, v122
	v_mul_f32_e32 v0, v0, v4
	v_mul_f32_e32 v1, v1, v7
	v_mul_f32_e32 v4, 0xbfb8aa3b, v2
	v_sub_f32_e32 v5, v5, v80
	v_exp_f32_e32 v4, v4
	v_mul_f32_e32 v1, v1, v5
	v_mul_f32_e32 v5, 0xbfb8aa3b, v3
	v_exp_f32_e32 v5, v5
	v_add_f32_e32 v4, 1.0, v4
	v_rcp_f32_e32 v4, v4
	v_lshlrev_b32_e32 v6, 16, v83
	v_add_f32_e32 v5, 1.0, v5
	v_rcp_f32_e32 v5, v5
	v_and_b32_e32 v8, 0xffff0000, v83
	v_mul_f32_e32 v2, v2, v4
	v_sub_f32_e32 v4, v6, v80
	v_mul_f32_e32 v2, v2, v4
	v_mul_f32_e32 v3, v3, v5
	v_sub_f32_e32 v4, v8, v80
	v_mul_f32_e32 v0, v81, v0
	v_mul_f32_e32 v1, v81, v1
	v_mul_f32_e32 v3, v3, v4
	v_mul_f32_e32 v0, v44, v0
	v_mul_f32_e32 v1, v45, v1
	v_mul_f32_e32 v2, v81, v2
	v_mul_f32_e32 v3, v81, v3
	v_mul_f32_e32 v2, v46, v2
	v_mul_f32_e32 v3, v47, v3
	v_cvt_pk_bf16_f32 v0, v0, v1
	v_cvt_pk_bf16_f32 v1, v2, v3
	global_store_dwordx2 v[16:17], v[0:1], off offset:96
	s_add_i32 s34, s34, s74
	s_cmpk_lt_i32 s34, 0x800
	s_cbranch_scc1 .LBB0_502

.LBB0_706:
	ds_read_b128 v[196:199], v171 offset:32768
	ds_read_b128 v[200:203], v171 offset:33792
	ds_read_b128 v[204:207], v171 offset:34816
	ds_read_b128 v[208:211], v171 offset:35840
	ds_read_b128 v[212:215], v169
	ds_read_b128 v[216:219], v169 offset:1024
	ds_read_b128 v[222:225], v169 offset:2048
	ds_read_b128 v[226:229], v169 offset:3072
	ds_read_b128 v[230:233], v169 offset:4096
	ds_read_b128 v[234:237], v169 offset:5120
	ds_read_b128 v[238:241], v169 offset:6144
	ds_read_b128 v[242:245], v169 offset:7168
	s_setprio 1
	s_waitcnt lgkmcnt(7)
	v_mfma_f32_16x16x32_bf16 v[148:151], v[196:199], v[212:215], v[148:151]
	v_mfma_f32_16x16x32_bf16 v[144:147], v[200:203], v[212:215], v[144:147]
	v_mfma_f32_16x16x32_bf16 v[140:143], v[204:207], v[212:215], v[140:143]
	v_mfma_f32_16x16x32_bf16 v[136:139], v[208:211], v[212:215], v[136:139]
	global_load_dwordx4 v[172:175], v[172:173], off
	global_load_dwordx4 v[176:179], v[176:177], off
	global_load_dwordx4 v[180:183], v[180:181], off
	global_load_dwordx4 v[184:187], v[184:185], off
	global_load_dwordx4 v[188:191], v[188:189], off
	global_load_dwordx4 v[192:195], v[192:193], off
	s_waitcnt vmcnt(11)
	ds_write_b128 v152, v[112:115] offset:16384
	s_waitcnt lgkmcnt(7)
	v_mfma_f32_16x16x32_bf16 v[108:111], v[196:199], v[216:219], v[108:111]
	v_mfma_f32_16x16x32_bf16 v[104:107], v[200:203], v[216:219], v[104:107]
	v_mfma_f32_16x16x32_bf16 v[100:103], v[204:207], v[216:219], v[100:103]
	v_mfma_f32_16x16x32_bf16 v[96:99], v[208:211], v[216:219], v[96:99]
	s_waitcnt vmcnt(9)
	ds_write_b128 v152, v[120:123] offset:20480
	s_waitcnt lgkmcnt(7)
	v_mfma_f32_16x16x32_bf16 v[92:95], v[196:199], v[222:225], v[92:95]
	v_mfma_f32_16x16x32_bf16 v[88:91], v[200:203], v[222:225], v[88:91]
	v_mfma_f32_16x16x32_bf16 v[84:87], v[204:207], v[222:225], v[84:87]
	v_mfma_f32_16x16x32_bf16 v[80:83], v[208:211], v[222:225], v[80:83]
	s_waitcnt vmcnt(8)
	ds_write_b128 v152, v[124:127] offset:24576
	s_waitcnt lgkmcnt(7)
	v_mfma_f32_16x16x32_bf16 v[76:79], v[196:199], v[226:229], v[76:79]
	v_mfma_f32_16x16x32_bf16 v[72:75], v[200:203], v[226:229], v[72:75]
	v_mfma_f32_16x16x32_bf16 v[68:71], v[204:207], v[226:229], v[68:71]
	v_mfma_f32_16x16x32_bf16 v[64:67], v[208:211], v[226:229], v[64:67]
	s_waitcnt vmcnt(7)
	ds_write_b128 v152, v[128:131] offset:28672
	s_waitcnt lgkmcnt(7)
	v_mfma_f32_16x16x32_bf16 v[60:63], v[196:199], v[230:233], v[60:63]
	v_mfma_f32_16x16x32_bf16 v[56:59], v[200:203], v[230:233], v[56:59]
	v_mfma_f32_16x16x32_bf16 v[52:55], v[204:207], v[230:233], v[52:55]
	v_mfma_f32_16x16x32_bf16 v[48:51], v[208:211], v[230:233], v[48:51]
	s_waitcnt vmcnt(7)
	ds_write_b128 v152, v[116:119] offset:40960
	s_waitcnt lgkmcnt(7)
	v_mfma_f32_16x16x32_bf16 v[44:47], v[196:199], v[234:237], v[44:47]
	v_mfma_f32_16x16x32_bf16 v[40:43], v[200:203], v[234:237], v[40:43]
	v_mfma_f32_16x16x32_bf16 v[36:39], v[204:207], v[234:237], v[36:39]
	v_mfma_f32_16x16x32_bf16 v[32:35], v[208:211], v[234:237], v[32:35]
	s_waitcnt vmcnt(6)
	ds_write_b128 v152, v[132:135] offset:45056
	s_waitcnt lgkmcnt(7)
	v_mfma_f32_16x16x32_bf16 v[28:31], v[196:199], v[238:241], v[28:31]
	v_mfma_f32_16x16x32_bf16 v[24:27], v[200:203], v[238:241], v[24:27]
	v_mfma_f32_16x16x32_bf16 v[20:23], v[204:207], v[238:241], v[20:23]
	v_mfma_f32_16x16x32_bf16 v[16:19], v[208:211], v[238:241], v[16:19]
	s_waitcnt lgkmcnt(6)
	v_mfma_f32_16x16x32_bf16 v[12:15], v[196:199], v[242:245], v[12:15]
	v_mfma_f32_16x16x32_bf16 v[8:11], v[200:203], v[242:245], v[8:11]
	v_mfma_f32_16x16x32_bf16 v[4:7], v[204:207], v[242:245], v[4:7]
	v_mfma_f32_16x16x32_bf16 v[0:3], v[208:211], v[242:245], v[0:3]
	s_setprio 0
	s_min_u32 s10, s10, 0x380
	s_lshl_b32 s16, s10, 1
	s_mov_b32 s27, s17
	s_add_i32 s26, s16, 0xc0
	v_lshl_add_u64 v[112:113], v[154:155], 0, s[16:17]
	v_lshl_add_u64 v[116:117], v[156:157], 0, s[16:17]
	v_lshl_add_u64 v[120:121], v[158:159], 0, s[26:27]
	v_lshl_add_u64 v[124:125], v[160:161], 0, s[26:27]
	v_lshl_add_u64 v[128:129], v[162:163], 0, s[26:27]
	v_lshl_add_u64 v[132:133], v[164:165], 0, s[26:27]
	s_waitcnt lgkmcnt(0)
	s_barrier
	ds_read_b128 v[196:199], v168 offset:40960
	ds_read_b128 v[200:203], v168 offset:41984
	ds_read_b128 v[204:207], v168 offset:43008
	ds_read_b128 v[208:211], v168 offset:44032
	ds_read_b128 v[212:215], v170
	ds_read_b128 v[216:219], v170 offset:1024
	ds_read_b128 v[222:225], v170 offset:2048
	ds_read_b128 v[226:229], v170 offset:3072
	ds_read_b128 v[230:233], v170 offset:4096
	ds_read_b128 v[234:237], v170 offset:5120
	ds_read_b128 v[238:241], v170 offset:6144
	ds_read_b128 v[242:245], v170 offset:7168
	s_setprio 1
	s_waitcnt lgkmcnt(7)
	v_mfma_f32_16x16x32_bf16 v[148:151], v[196:199], v[212:215], v[148:151]
	v_mfma_f32_16x16x32_bf16 v[144:147], v[200:203], v[212:215], v[144:147]
	v_mfma_f32_16x16x32_bf16 v[140:143], v[204:207], v[212:215], v[140:143]
	v_mfma_f32_16x16x32_bf16 v[136:139], v[208:211], v[212:215], v[136:139]
	global_load_dwordx4 v[112:115], v[112:113], off offset:192
	global_load_dwordx4 v[116:119], v[116:117], off offset:192
	global_load_dwordx4 v[120:123], v[120:121], off
	global_load_dwordx4 v[124:127], v[124:125], off
	global_load_dwordx4 v[128:131], v[128:129], off
	global_load_dwordx4 v[132:135], v[132:133], off
	s_waitcnt vmcnt(11)
	ds_write_b128 v152, v[172:175]
	s_waitcnt lgkmcnt(7)
	v_mfma_f32_16x16x32_bf16 v[108:111], v[196:199], v[216:219], v[108:111]
	v_mfma_f32_16x16x32_bf16 v[104:107], v[200:203], v[216:219], v[104:107]
	v_mfma_f32_16x16x32_bf16 v[100:103], v[204:207], v[216:219], v[100:103]
	v_mfma_f32_16x16x32_bf16 v[96:99], v[208:211], v[216:219], v[96:99]
	s_waitcnt vmcnt(10)
	ds_write_b128 v152, v[176:179] offset:4096
	s_waitcnt lgkmcnt(7)
	v_mfma_f32_16x16x32_bf16 v[92:95], v[196:199], v[222:225], v[92:95]
	v_mfma_f32_16x16x32_bf16 v[88:91], v[200:203], v[222:225], v[88:91]
	v_mfma_f32_16x16x32_bf16 v[84:87], v[204:207], v[222:225], v[84:87]
	v_mfma_f32_16x16x32_bf16 v[80:83], v[208:211], v[222:225], v[80:83]
	s_waitcnt vmcnt(9)
	ds_write_b128 v152, v[180:183] offset:8192
	s_waitcnt lgkmcnt(7)
	v_mfma_f32_16x16x32_bf16 v[76:79], v[196:199], v[226:229], v[76:79]
	v_mfma_f32_16x16x32_bf16 v[72:75], v[200:203], v[226:229], v[72:75]
	v_mfma_f32_16x16x32_bf16 v[68:71], v[204:207], v[226:229], v[68:71]
	v_mfma_f32_16x16x32_bf16 v[64:67], v[208:211], v[226:229], v[64:67]
	s_waitcnt vmcnt(8)
	ds_write_b128 v152, v[184:187] offset:12288
	s_waitcnt lgkmcnt(7)
	v_mfma_f32_16x16x32_bf16 v[60:63], v[196:199], v[230:233], v[60:63]
	v_mfma_f32_16x16x32_bf16 v[56:59], v[200:203], v[230:233], v[56:59]
	v_mfma_f32_16x16x32_bf16 v[52:55], v[204:207], v[230:233], v[52:55]
	v_mfma_f32_16x16x32_bf16 v[48:51], v[208:211], v[230:233], v[48:51]
	s_waitcnt vmcnt(7)
	ds_write_b128 v152, v[188:191] offset:32768
	s_waitcnt lgkmcnt(7)
	v_mfma_f32_16x16x32_bf16 v[44:47], v[196:199], v[234:237], v[44:47]
	v_mfma_f32_16x16x32_bf16 v[40:43], v[200:203], v[234:237], v[40:43]
	v_mfma_f32_16x16x32_bf16 v[36:39], v[204:207], v[234:237], v[36:39]
	v_mfma_f32_16x16x32_bf16 v[32:35], v[208:211], v[234:237], v[32:35]
	s_waitcnt vmcnt(6)
	ds_write_b128 v152, v[192:195] offset:36864
	s_waitcnt lgkmcnt(7)
	v_mfma_f32_16x16x32_bf16 v[28:31], v[196:199], v[238:241], v[28:31]
	v_mfma_f32_16x16x32_bf16 v[24:27], v[200:203], v[238:241], v[24:27]
	v_mfma_f32_16x16x32_bf16 v[20:23], v[204:207], v[238:241], v[20:23]
	v_mfma_f32_16x16x32_bf16 v[16:19], v[208:211], v[238:241], v[16:19]
	s_waitcnt lgkmcnt(6)
	v_mfma_f32_16x16x32_bf16 v[12:15], v[196:199], v[242:245], v[12:15]
	v_mfma_f32_16x16x32_bf16 v[8:11], v[200:203], v[242:245], v[8:11]
	v_mfma_f32_16x16x32_bf16 v[4:7], v[204:207], v[242:245], v[4:7]
	v_mfma_f32_16x16x32_bf16 v[0:3], v[208:211], v[242:245], v[0:3]
	s_setprio 0
	s_add_i32 s1, s1, 2
	s_mov_b32 s10, s11
	s_add_i32 s11, s10, 64
	s_min_u32 s13, s11, 0x3e0
	s_lshl_b32 s16, s13, 1
	v_lshl_add_u64 v[172:173], v[154:155], 0, s[16:17]
	v_lshl_add_u64 v[176:177], v[158:159], 0, s[16:17]
	v_lshl_add_u64 v[180:181], v[160:161], 0, s[16:17]
	v_lshl_add_u64 v[184:185], v[162:163], 0, s[16:17]
	v_lshl_add_u64 v[188:189], v[156:157], 0, s[16:17]
	v_lshl_add_u64 v[192:193], v[164:165], 0, s[16:17]
	s_cmp_lt_u32 s1, 30
	s_waitcnt lgkmcnt(0)
	s_cbranch_scc1 .Lrot_3
	s_barrier
	s_waitcnt vmcnt(4)
	v_mov_b32_e32 v116, v220
	s_nop 0
	v_and_b32_e32 v112, 0xffffff80, v116
	v_add_u32_e32 v117, s0, v112
	v_and_or_b32 v114, v116, 15, v117
	v_ashrrev_i32_e32 v115, 31, v114
	v_lshl_add_u64 v[112:113], v[114:115], 2, s[14:15]
	global_load_dword v246, v[112:113], off offset:64
	global_load_dword v247, v[112:113], off offset:128
	global_load_dword v248, v[112:113], off offset:192
	global_load_dword v249, v[112:113], off offset:256
	global_load_dword v250, v[112:113], off offset:320
	global_load_dword v251, v[112:113], off offset:384
	global_load_dword v252, v[112:113], off offset:448
	global_load_dword v122, v[112:113], off
	v_and_b32_e32 v112, 64, v116
	v_lshrrev_b32_e32 v115, 1, v116
	v_ashrrev_i32_e32 v116, 14, v117
	v_ashrrev_i32_e32 v117, 31, v116
	v_lshlrev_b32_e32 v152, 1, v112
	v_or_b32_e32 v118, 16, v114
	v_lshlrev_b64 v[116:117], 16, v[116:117]
	v_lshl_add_u64 v[112:113], s[38:39], 0, v[152:153]
	v_and_b32_e32 v152, 24, v115
	v_ashrrev_i32_e32 v119, 31, v118
	v_lshl_or_b32 v115, s12, 14, v116
	s_waitcnt vmcnt(4)
	v_lshl_add_u64 v[120:121], v[118:119], 2, s[14:15]
	v_lshl_add_u64 v[112:113], v[112:113], 0, v[152:153]
	s_waitcnt vmcnt(0)
	v_fmamk_f32 v116, v122, 0x3a800000, v166
	v_mul_f32_e32 v119, 0x4b800000, v116
	v_cmp_gt_f32_e32 vcc, s40, v116
	s_nop 1
	v_cndmask_b32_e32 v116, v116, v119, vcc
	v_rsq_f32_e32 v119, v116
	v_and_or_b32 v116, v114, s41, v115
	v_lshlrev_b64 v[122:123], 8, v[116:117]
	v_lshl_add_u64 v[122:123], v[112:113], 0, v[122:123]
	v_mul_f32_e32 v116, 0x45800000, v119
	v_cndmask_b32_e32 v116, v119, v116, vcc
	v_mul_f32_e32 v124, v149, v116
	v_mul_f32_e32 v125, v150, v116
	v_mul_f32_e32 v119, v148, v116
	v_mul_f32_e32 v126, v151, v116
	v_mul_f32_e32 v127, v144, v116
	v_mul_f32_e32 v128, v145, v116
	v_mul_f32_e32 v129, v146, v116
	v_mul_f32_e32 v130, v147, v116
	v_mul_f32_e32 v131, v140, v116
	v_cvt_pk_bf16_f32 v124, v119, v124
	v_cvt_pk_bf16_f32 v125, v125, v126
	v_mul_f32_e32 v132, v141, v116
	v_mul_f32_e32 v133, v142, v116
	v_mul_f32_e32 v134, v143, v116
	v_mul_f32_e32 v135, v136, v116
	v_mul_f32_e32 v136, v137, v116
	v_mul_f32_e32 v137, v138, v116
	v_mul_f32_e32 v116, v139, v116
	v_cvt_pk_bf16_f32 v126, v127, v128
	v_cvt_pk_bf16_f32 v127, v129, v130
	v_cvt_pk_bf16_f32 v128, v131, v132
	v_cvt_pk_bf16_f32 v129, v133, v134
	v_cvt_pk_bf16_f32 v130, v135, v136
	v_cvt_pk_bf16_f32 v131, v137, v116
	global_store_dwordx2 v[122:123], v[124:125], off
	global_store_dwordx2 v[122:123], v[126:127], off offset:32
	global_store_dwordx2 v[122:123], v[128:129], off offset:64
	global_store_dwordx2 v[122:123], v[130:131], off offset:96
	v_mov_b32_e32 v116, v246
	v_or_b32_e32 v120, 32, v114
	v_ashrrev_i32_e32 v121, 31, v120
	v_lshl_add_u64 v[122:123], v[120:121], 2, s[14:15]
	v_fmamk_f32 v116, v116, 0x3a800000, v166
	v_mul_f32_e32 v119, 0x4b800000, v116
	v_cmp_gt_f32_e32 vcc, s40, v116
	s_nop 1
	v_cndmask_b32_e32 v116, v116, v119, vcc
	v_rsq_f32_e32 v121, v116
	v_and_or_b32 v116, v118, s42, v115
	v_lshlrev_b64 v[118:119], 8, v[116:117]
	v_lshl_add_u64 v[118:119], v[112:113], 0, v[118:119]
	v_mul_f32_e32 v116, 0x45800000, v121
	v_cndmask_b32_e32 v116, v121, v116, vcc
	v_mul_f32_e32 v108, v108, v116
	v_mul_f32_e32 v109, v109, v116
	v_mul_f32_e32 v110, v110, v116
	v_mul_f32_e32 v111, v111, v116
	v_mul_f32_e32 v100, v100, v116
	v_mul_f32_e32 v101, v101, v116
	v_mul_f32_e32 v102, v102, v116
	v_mul_f32_e32 v103, v103, v116
	v_mul_f32_e32 v121, v96, v116
	v_mul_f32_e32 v124, v97, v116
	v_cvt_pk_bf16_f32 v96, v108, v109
	v_cvt_pk_bf16_f32 v97, v110, v111
	v_mul_f32_e32 v104, v104, v116
	v_mul_f32_e32 v105, v105, v116
	v_mul_f32_e32 v106, v106, v116
	v_mul_f32_e32 v107, v107, v116
	v_mul_f32_e32 v125, v98, v116
	v_mul_f32_e32 v116, v99, v116
	v_cvt_pk_bf16_f32 v98, v104, v105
	v_cvt_pk_bf16_f32 v99, v106, v107
	v_cvt_pk_bf16_f32 v100, v100, v101
	v_cvt_pk_bf16_f32 v101, v102, v103
	v_cvt_pk_bf16_f32 v102, v121, v124
	v_cvt_pk_bf16_f32 v103, v125, v116
	global_store_dwordx2 v[118:119], v[96:97], off
	global_store_dwordx2 v[118:119], v[98:99], off offset:32
	global_store_dwordx2 v[118:119], v[100:101], off offset:64
	global_store_dwordx2 v[118:119], v[102:103], off offset:96
	v_mov_b32_e32 v100, v247
	v_or_b32_e32 v96, 48, v114
	v_ashrrev_i32_e32 v97, 31, v96
	v_lshl_add_u64 v[98:99], v[96:97], 2, s[14:15]
	v_and_or_b32 v116, v120, s43, v115
	v_fmamk_f32 v97, v100, 0x3a800000, v166
	v_mul_f32_e32 v100, 0x4b800000, v97
	v_cmp_gt_f32_e32 vcc, s40, v97
	s_nop 1
	v_cndmask_b32_e32 v97, v97, v100, vcc
	v_rsq_f32_e32 v97, v97
	v_lshlrev_b64 v[100:101], 8, v[116:117]
	v_lshl_add_u64 v[100:101], v[112:113], 0, v[100:101]
	v_and_or_b32 v116, v96, s44, v115
	v_mul_f32_e32 v102, 0x45800000, v97
	v_cndmask_b32_e32 v97, v97, v102, vcc
	v_mul_f32_e32 v92, v92, v97
	v_mul_f32_e32 v93, v93, v97
	v_mul_f32_e32 v94, v94, v97
	v_mul_f32_e32 v95, v95, v97
	v_mul_f32_e32 v84, v84, v97
	v_mul_f32_e32 v85, v85, v97
	v_mul_f32_e32 v86, v86, v97
	v_mul_f32_e32 v87, v87, v97
	v_mul_f32_e32 v102, v80, v97
	v_mul_f32_e32 v103, v81, v97
	v_cvt_pk_bf16_f32 v80, v92, v93
	v_cvt_pk_bf16_f32 v81, v94, v95
	v_mul_f32_e32 v88, v88, v97
	v_mul_f32_e32 v89, v89, v97
	v_mul_f32_e32 v90, v90, v97
	v_mul_f32_e32 v91, v91, v97
	v_mul_f32_e32 v104, v82, v97
	v_mul_f32_e32 v97, v83, v97
	v_cvt_pk_bf16_f32 v82, v88, v89
	v_cvt_pk_bf16_f32 v83, v90, v91
	v_cvt_pk_bf16_f32 v84, v84, v85
	v_cvt_pk_bf16_f32 v85, v86, v87
	v_cvt_pk_bf16_f32 v86, v102, v103
	v_cvt_pk_bf16_f32 v87, v104, v97
	global_store_dwordx2 v[100:101], v[80:81], off
	global_store_dwordx2 v[100:101], v[82:83], off offset:32
	global_store_dwordx2 v[100:101], v[84:85], off offset:64
	global_store_dwordx2 v[100:101], v[86:87], off offset:96
	v_mov_b32_e32 v84, v248
	v_or_b32_e32 v80, 64, v114
	v_ashrrev_i32_e32 v81, 31, v80
	v_lshl_add_u64 v[82:83], v[80:81], 2, s[14:15]
	v_fmamk_f32 v81, v84, 0x3a800000, v166
	v_mul_f32_e32 v84, 0x4b800000, v81
	v_cmp_gt_f32_e32 vcc, s40, v81
	s_nop 1
	v_cndmask_b32_e32 v81, v81, v84, vcc
	v_rsq_f32_e32 v81, v81
	v_lshlrev_b64 v[84:85], 8, v[116:117]
	v_lshl_add_u64 v[84:85], v[112:113], 0, v[84:85]
	v_and_or_b32 v116, v80, s45, v115
	v_mul_f32_e32 v86, 0x45800000, v81
	v_cndmask_b32_e32 v81, v81, v86, vcc
	v_mul_f32_e32 v76, v76, v81
	v_mul_f32_e32 v77, v77, v81
	v_mul_f32_e32 v78, v78, v81
	v_mul_f32_e32 v79, v79, v81
	v_mul_f32_e32 v68, v68, v81
	v_mul_f32_e32 v69, v69, v81
	v_mul_f32_e32 v70, v70, v81
	v_mul_f32_e32 v71, v71, v81
	v_mul_f32_e32 v86, v64, v81
	v_mul_f32_e32 v87, v65, v81
	v_cvt_pk_bf16_f32 v64, v76, v77
	v_cvt_pk_bf16_f32 v65, v78, v79
	v_mul_f32_e32 v72, v72, v81
	v_mul_f32_e32 v73, v73, v81
	v_mul_f32_e32 v74, v74, v81
	v_mul_f32_e32 v75, v75, v81
	v_mul_f32_e32 v88, v66, v81
	v_mul_f32_e32 v81, v67, v81
	v_cvt_pk_bf16_f32 v66, v72, v73
	v_cvt_pk_bf16_f32 v67, v74, v75
	v_cvt_pk_bf16_f32 v68, v68, v69
	v_cvt_pk_bf16_f32 v69, v70, v71
	v_cvt_pk_bf16_f32 v70, v86, v87
	v_cvt_pk_bf16_f32 v71, v88, v81
	global_store_dwordx2 v[84:85], v[64:65], off
	global_store_dwordx2 v[84:85], v[66:67], off offset:32
	global_store_dwordx2 v[84:85], v[68:69], off offset:64
	global_store_dwordx2 v[84:85], v[70:71], off offset:96
	v_mov_b32_e32 v68, v249
	v_or_b32_e32 v64, 0x50, v114
	v_ashrrev_i32_e32 v65, 31, v64
	v_lshl_add_u64 v[66:67], v[64:65], 2, s[14:15]
	v_fmamk_f32 v65, v68, 0x3a800000, v166
	v_mul_f32_e32 v68, 0x4b800000, v65
	v_cmp_gt_f32_e32 vcc, s40, v65
	s_nop 1
	v_cndmask_b32_e32 v65, v65, v68, vcc
	v_rsq_f32_e32 v65, v65
	v_lshlrev_b64 v[68:69], 8, v[116:117]
	v_lshl_add_u64 v[68:69], v[112:113], 0, v[68:69]
	v_and_or_b32 v116, v64, s46, v115
	v_mul_f32_e32 v70, 0x45800000, v65
	v_cndmask_b32_e32 v65, v65, v70, vcc
	v_mul_f32_e32 v60, v60, v65
	v_mul_f32_e32 v61, v61, v65
	v_mul_f32_e32 v62, v62, v65
	v_mul_f32_e32 v63, v63, v65
	v_mul_f32_e32 v52, v52, v65
	v_mul_f32_e32 v53, v53, v65
	v_mul_f32_e32 v54, v54, v65
	v_mul_f32_e32 v55, v55, v65
	v_mul_f32_e32 v70, v48, v65
	v_mul_f32_e32 v71, v49, v65
	v_cvt_pk_bf16_f32 v48, v60, v61
	v_cvt_pk_bf16_f32 v49, v62, v63
	v_mul_f32_e32 v56, v56, v65
	v_mul_f32_e32 v57, v57, v65
	v_mul_f32_e32 v58, v58, v65
	v_mul_f32_e32 v59, v59, v65
	v_mul_f32_e32 v72, v50, v65
	v_mul_f32_e32 v65, v51, v65
	v_cvt_pk_bf16_f32 v50, v56, v57
	v_cvt_pk_bf16_f32 v51, v58, v59
	v_cvt_pk_bf16_f32 v52, v52, v53
	v_cvt_pk_bf16_f32 v53, v54, v55
	v_cvt_pk_bf16_f32 v54, v70, v71
	v_cvt_pk_bf16_f32 v55, v72, v65
	global_store_dwordx2 v[68:69], v[48:49], off
	global_store_dwordx2 v[68:69], v[50:51], off offset:32
	global_store_dwordx2 v[68:69], v[52:53], off offset:64
	global_store_dwordx2 v[68:69], v[54:55], off offset:96
	v_mov_b32_e32 v52, v250
	v_or_b32_e32 v48, 0x60, v114
	v_ashrrev_i32_e32 v49, 31, v48
	v_lshl_add_u64 v[50:51], v[48:49], 2, s[14:15]
	v_fmamk_f32 v49, v52, 0x3a800000, v166
	v_mul_f32_e32 v52, 0x4b800000, v49
	v_cmp_gt_f32_e32 vcc, s40, v49
	s_nop 1
	v_cndmask_b32_e32 v49, v49, v52, vcc
	v_rsq_f32_e32 v49, v49
	v_lshlrev_b64 v[52:53], 8, v[116:117]
	v_lshl_add_u64 v[52:53], v[112:113], 0, v[52:53]
	v_and_or_b32 v116, v48, s47, v115
	v_mul_f32_e32 v54, 0x45800000, v49
	v_cndmask_b32_e32 v49, v49, v54, vcc
	v_mul_f32_e32 v44, v44, v49
	v_mul_f32_e32 v45, v45, v49
	v_mul_f32_e32 v46, v46, v49
	v_mul_f32_e32 v47, v47, v49
	v_mul_f32_e32 v36, v36, v49
	v_mul_f32_e32 v37, v37, v49
	v_mul_f32_e32 v38, v38, v49
	v_mul_f32_e32 v39, v39, v49
	v_mul_f32_e32 v54, v32, v49
	v_mul_f32_e32 v55, v33, v49
	v_cvt_pk_bf16_f32 v32, v44, v45
	v_cvt_pk_bf16_f32 v33, v46, v47
	v_mul_f32_e32 v40, v40, v49
	v_mul_f32_e32 v41, v41, v49
	v_mul_f32_e32 v42, v42, v49
	v_mul_f32_e32 v43, v43, v49
	v_mul_f32_e32 v56, v34, v49
	v_mul_f32_e32 v49, v35, v49
	v_cvt_pk_bf16_f32 v34, v40, v41
	v_cvt_pk_bf16_f32 v35, v42, v43
	v_cvt_pk_bf16_f32 v36, v36, v37
	v_cvt_pk_bf16_f32 v37, v38, v39
	v_cvt_pk_bf16_f32 v38, v54, v55
	v_cvt_pk_bf16_f32 v39, v56, v49
	global_store_dwordx2 v[52:53], v[32:33], off
	global_store_dwordx2 v[52:53], v[34:35], off offset:32
	global_store_dwordx2 v[52:53], v[36:37], off offset:64
	global_store_dwordx2 v[52:53], v[38:39], off offset:96
	v_mov_b32_e32 v36, v251
	v_or_b32_e32 v32, 0x70, v114
	v_ashrrev_i32_e32 v33, 31, v32
	v_lshl_add_u64 v[34:35], v[32:33], 2, s[14:15]
	v_fmamk_f32 v33, v36, 0x3a800000, v166
	v_mul_f32_e32 v36, 0x4b800000, v33
	v_cmp_gt_f32_e32 vcc, s40, v33
	s_nop 1
	v_cndmask_b32_e32 v33, v33, v36, vcc
	v_rsq_f32_e32 v33, v33
	v_lshlrev_b64 v[36:37], 8, v[116:117]
	v_lshl_add_u64 v[36:37], v[112:113], 0, v[36:37]
	v_and_or_b32 v116, v32, s48, v115
	v_mul_f32_e32 v38, 0x45800000, v33
	v_cndmask_b32_e32 v33, v33, v38, vcc
	v_mul_f32_e32 v28, v28, v33
	v_mul_f32_e32 v29, v29, v33
	v_mul_f32_e32 v30, v30, v33
	v_mul_f32_e32 v31, v31, v33
	v_mul_f32_e32 v20, v20, v33
	v_mul_f32_e32 v21, v21, v33
	v_mul_f32_e32 v22, v22, v33
	v_mul_f32_e32 v23, v23, v33
	v_mul_f32_e32 v38, v16, v33
	v_mul_f32_e32 v39, v17, v33
	v_cvt_pk_bf16_f32 v16, v28, v29
	v_cvt_pk_bf16_f32 v17, v30, v31
	v_mul_f32_e32 v24, v24, v33
	v_mul_f32_e32 v25, v25, v33
	v_mul_f32_e32 v26, v26, v33
	v_mul_f32_e32 v27, v27, v33
	v_mul_f32_e32 v40, v18, v33
	v_mul_f32_e32 v33, v19, v33
	v_cvt_pk_bf16_f32 v18, v24, v25
	v_cvt_pk_bf16_f32 v19, v26, v27
	v_cvt_pk_bf16_f32 v20, v20, v21
	v_cvt_pk_bf16_f32 v21, v22, v23
	v_cvt_pk_bf16_f32 v22, v38, v39
	v_cvt_pk_bf16_f32 v23, v40, v33
	global_store_dwordx2 v[36:37], v[16:17], off
	global_store_dwordx2 v[36:37], v[18:19], off offset:32
	global_store_dwordx2 v[36:37], v[20:21], off offset:64
	global_store_dwordx2 v[36:37], v[22:23], off offset:96
	v_mov_b32_e32 v16, v252
	v_fmamk_f32 v16, v16, 0x3a800000, v166
	v_mul_f32_e32 v17, 0x4b800000, v16
	v_cmp_gt_f32_e32 vcc, s40, v16
	s_nop 1
	v_cndmask_b32_e32 v16, v16, v17, vcc
	v_rsq_f32_e32 v18, v16
	v_lshlrev_b64 v[16:17], 8, v[116:117]
	v_lshl_add_u64 v[16:17], v[112:113], 0, v[16:17]
	v_mul_f32_e32 v19, 0x45800000, v18
	v_cndmask_b32_e32 v18, v18, v19, vcc
	v_mul_f32_e32 v12, v12, v18
	v_mul_f32_e32 v13, v13, v18
	v_mul_f32_e32 v14, v14, v18
	v_mul_f32_e32 v15, v15, v18
	v_mul_f32_e32 v4, v4, v18
	v_mul_f32_e32 v5, v5, v18
	v_mul_f32_e32 v6, v6, v18
	v_mul_f32_e32 v7, v7, v18
	v_mul_f32_e32 v19, v0, v18
	v_mul_f32_e32 v20, v1, v18
	v_cvt_pk_bf16_f32 v0, v12, v13
	v_cvt_pk_bf16_f32 v1, v14, v15
	v_mul_f32_e32 v8, v8, v18
	v_mul_f32_e32 v9, v9, v18
	v_mul_f32_e32 v10, v10, v18
	v_mul_f32_e32 v11, v11, v18
	v_mul_f32_e32 v21, v2, v18
	v_mul_f32_e32 v18, v3, v18
	v_cvt_pk_bf16_f32 v2, v8, v9
	v_cvt_pk_bf16_f32 v3, v10, v11
	v_cvt_pk_bf16_f32 v4, v4, v5
	v_cvt_pk_bf16_f32 v5, v6, v7
	v_cvt_pk_bf16_f32 v6, v19, v20
	v_cvt_pk_bf16_f32 v7, v21, v18
	global_store_dwordx2 v[16:17], v[0:1], off
	global_store_dwordx2 v[16:17], v[2:3], off offset:32
	global_store_dwordx2 v[16:17], v[4:5], off offset:64
	global_store_dwordx2 v[16:17], v[6:7], off offset:96
	s_branch .LBB0_699

.LBB0_710:
	ds_read_b128 v[196:199], v171 offset:32768
	ds_read_b128 v[200:203], v171 offset:33792
	ds_read_b128 v[204:207], v171 offset:34816
	ds_read_b128 v[208:211], v171 offset:35840
	ds_read_b128 v[212:215], v169
	ds_read_b128 v[216:219], v169 offset:1024
	ds_read_b128 v[222:225], v169 offset:2048
	ds_read_b128 v[226:229], v169 offset:3072
	ds_read_b128 v[230:233], v169 offset:4096
	ds_read_b128 v[234:237], v169 offset:5120
	ds_read_b128 v[238:241], v169 offset:6144
	ds_read_b128 v[242:245], v169 offset:7168
	s_setprio 1
	s_waitcnt lgkmcnt(7)
	v_mfma_f32_16x16x32_bf16 v[148:151], v[212:215], v[196:199], v[148:151]
	v_mfma_f32_16x16x32_bf16 v[144:147], v[212:215], v[200:203], v[144:147]
	v_mfma_f32_16x16x32_bf16 v[140:143], v[212:215], v[204:207], v[140:143]
	v_mfma_f32_16x16x32_bf16 v[128:131], v[212:215], v[208:211], v[128:131]
	global_load_dwordx4 v[172:175], v[172:173], off
	global_load_dwordx4 v[176:179], v[176:177], off
	global_load_dwordx4 v[180:183], v[180:181], off
	global_load_dwordx4 v[184:187], v[184:185], off
	global_load_dwordx4 v[188:191], v[188:189], off
	global_load_dwordx4 v[192:195], v[192:193], off
	s_waitcnt vmcnt(11)
	ds_write_b128 v152, v[112:115] offset:16384
	s_waitcnt lgkmcnt(7)
	v_mfma_f32_16x16x32_bf16 v[108:111], v[216:219], v[196:199], v[108:111]
	v_mfma_f32_16x16x32_bf16 v[104:107], v[216:219], v[200:203], v[104:107]
	v_mfma_f32_16x16x32_bf16 v[100:103], v[216:219], v[204:207], v[100:103]
	v_mfma_f32_16x16x32_bf16 v[96:99], v[216:219], v[208:211], v[96:99]
	s_waitcnt vmcnt(9)
	ds_write_b128 v152, v[120:123] offset:20480
	s_waitcnt lgkmcnt(7)
	v_mfma_f32_16x16x32_bf16 v[92:95], v[222:225], v[196:199], v[92:95]
	v_mfma_f32_16x16x32_bf16 v[88:91], v[222:225], v[200:203], v[88:91]
	v_mfma_f32_16x16x32_bf16 v[84:87], v[222:225], v[204:207], v[84:87]
	v_mfma_f32_16x16x32_bf16 v[80:83], v[222:225], v[208:211], v[80:83]
	s_waitcnt vmcnt(8)
	ds_write_b128 v152, v[124:127] offset:24576
	s_waitcnt lgkmcnt(7)
	v_mfma_f32_16x16x32_bf16 v[76:79], v[226:229], v[196:199], v[76:79]
	v_mfma_f32_16x16x32_bf16 v[72:75], v[226:229], v[200:203], v[72:75]
	v_mfma_f32_16x16x32_bf16 v[68:71], v[226:229], v[204:207], v[68:71]
	v_mfma_f32_16x16x32_bf16 v[64:67], v[226:229], v[208:211], v[64:67]
	s_waitcnt vmcnt(7)
	ds_write_b128 v152, v[132:135] offset:28672
	s_waitcnt lgkmcnt(7)
	v_mfma_f32_16x16x32_bf16 v[60:63], v[230:233], v[196:199], v[60:63]
	v_mfma_f32_16x16x32_bf16 v[56:59], v[230:233], v[200:203], v[56:59]
	v_mfma_f32_16x16x32_bf16 v[52:55], v[230:233], v[204:207], v[52:55]
	v_mfma_f32_16x16x32_bf16 v[48:51], v[230:233], v[208:211], v[48:51]
	s_waitcnt vmcnt(7)
	ds_write_b128 v152, v[116:119] offset:40960
	s_waitcnt lgkmcnt(7)
	v_mfma_f32_16x16x32_bf16 v[44:47], v[234:237], v[196:199], v[44:47]
	v_mfma_f32_16x16x32_bf16 v[40:43], v[234:237], v[200:203], v[40:43]
	v_mfma_f32_16x16x32_bf16 v[36:39], v[234:237], v[204:207], v[36:39]
	v_mfma_f32_16x16x32_bf16 v[32:35], v[234:237], v[208:211], v[32:35]
	s_waitcnt vmcnt(6)
	ds_write_b128 v152, v[136:139] offset:45056
	s_waitcnt lgkmcnt(7)
	v_mfma_f32_16x16x32_bf16 v[28:31], v[238:241], v[196:199], v[28:31]
	v_mfma_f32_16x16x32_bf16 v[24:27], v[238:241], v[200:203], v[24:27]
	v_mfma_f32_16x16x32_bf16 v[20:23], v[238:241], v[204:207], v[20:23]
	v_mfma_f32_16x16x32_bf16 v[16:19], v[238:241], v[208:211], v[16:19]
	s_waitcnt lgkmcnt(6)
	v_mfma_f32_16x16x32_bf16 v[12:15], v[242:245], v[196:199], v[12:15]
	v_mfma_f32_16x16x32_bf16 v[8:11], v[242:245], v[200:203], v[8:11]
	v_mfma_f32_16x16x32_bf16 v[4:7], v[242:245], v[204:207], v[4:7]
	v_mfma_f32_16x16x32_bf16 v[0:3], v[242:245], v[208:211], v[0:3]
	s_setprio 0
	s_min_u32 s10, s10, 0x380
	s_lshl_b32 s16, s10, 1
	s_mov_b32 s27, s17
	s_add_i32 s26, s16, 0xc0
	v_lshl_add_u64 v[112:113], v[154:155], 0, s[16:17]
	v_lshl_add_u64 v[116:117], v[156:157], 0, s[16:17]
	v_lshl_add_u64 v[120:121], v[158:159], 0, s[26:27]
	v_lshl_add_u64 v[124:125], v[160:161], 0, s[26:27]
	v_lshl_add_u64 v[132:133], v[162:163], 0, s[26:27]
	v_lshl_add_u64 v[136:137], v[164:165], 0, s[26:27]
	s_waitcnt lgkmcnt(0)
	s_barrier
	ds_read_b128 v[196:199], v168 offset:40960
	ds_read_b128 v[200:203], v168 offset:41984
	ds_read_b128 v[204:207], v168 offset:43008
	ds_read_b128 v[208:211], v168 offset:44032
	ds_read_b128 v[212:215], v170
	ds_read_b128 v[216:219], v170 offset:1024
	ds_read_b128 v[222:225], v170 offset:2048
	ds_read_b128 v[226:229], v170 offset:3072
	ds_read_b128 v[230:233], v170 offset:4096
	ds_read_b128 v[234:237], v170 offset:5120
	ds_read_b128 v[238:241], v170 offset:6144
	ds_read_b128 v[242:245], v170 offset:7168
	s_setprio 1
	s_waitcnt lgkmcnt(7)
	v_mfma_f32_16x16x32_bf16 v[148:151], v[212:215], v[196:199], v[148:151]
	v_mfma_f32_16x16x32_bf16 v[144:147], v[212:215], v[200:203], v[144:147]
	v_mfma_f32_16x16x32_bf16 v[140:143], v[212:215], v[204:207], v[140:143]
	v_mfma_f32_16x16x32_bf16 v[128:131], v[212:215], v[208:211], v[128:131]
	global_load_dwordx4 v[112:115], v[112:113], off offset:192
	global_load_dwordx4 v[116:119], v[116:117], off offset:192
	global_load_dwordx4 v[120:123], v[120:121], off
	global_load_dwordx4 v[124:127], v[124:125], off
	global_load_dwordx4 v[132:135], v[132:133], off
	global_load_dwordx4 v[136:139], v[136:137], off
	s_waitcnt vmcnt(11)
	ds_write_b128 v152, v[172:175]
	s_waitcnt lgkmcnt(7)
	v_mfma_f32_16x16x32_bf16 v[108:111], v[216:219], v[196:199], v[108:111]
	v_mfma_f32_16x16x32_bf16 v[104:107], v[216:219], v[200:203], v[104:107]
	v_mfma_f32_16x16x32_bf16 v[100:103], v[216:219], v[204:207], v[100:103]
	v_mfma_f32_16x16x32_bf16 v[96:99], v[216:219], v[208:211], v[96:99]
	s_waitcnt vmcnt(10)
	ds_write_b128 v152, v[176:179] offset:4096
	s_waitcnt lgkmcnt(7)
	v_mfma_f32_16x16x32_bf16 v[92:95], v[222:225], v[196:199], v[92:95]
	v_mfma_f32_16x16x32_bf16 v[88:91], v[222:225], v[200:203], v[88:91]
	v_mfma_f32_16x16x32_bf16 v[84:87], v[222:225], v[204:207], v[84:87]
	v_mfma_f32_16x16x32_bf16 v[80:83], v[222:225], v[208:211], v[80:83]
	s_waitcnt vmcnt(9)
	ds_write_b128 v152, v[180:183] offset:8192
	s_waitcnt lgkmcnt(7)
	v_mfma_f32_16x16x32_bf16 v[76:79], v[226:229], v[196:199], v[76:79]
	v_mfma_f32_16x16x32_bf16 v[72:75], v[226:229], v[200:203], v[72:75]
	v_mfma_f32_16x16x32_bf16 v[68:71], v[226:229], v[204:207], v[68:71]
	v_mfma_f32_16x16x32_bf16 v[64:67], v[226:229], v[208:211], v[64:67]
	s_waitcnt vmcnt(8)
	ds_write_b128 v152, v[184:187] offset:12288
	s_waitcnt lgkmcnt(7)
	v_mfma_f32_16x16x32_bf16 v[60:63], v[230:233], v[196:199], v[60:63]
	v_mfma_f32_16x16x32_bf16 v[56:59], v[230:233], v[200:203], v[56:59]
	v_mfma_f32_16x16x32_bf16 v[52:55], v[230:233], v[204:207], v[52:55]
	v_mfma_f32_16x16x32_bf16 v[48:51], v[230:233], v[208:211], v[48:51]
	s_waitcnt vmcnt(7)
	ds_write_b128 v152, v[188:191] offset:32768
	s_waitcnt lgkmcnt(7)
	v_mfma_f32_16x16x32_bf16 v[44:47], v[234:237], v[196:199], v[44:47]
	v_mfma_f32_16x16x32_bf16 v[40:43], v[234:237], v[200:203], v[40:43]
	v_mfma_f32_16x16x32_bf16 v[36:39], v[234:237], v[204:207], v[36:39]
	v_mfma_f32_16x16x32_bf16 v[32:35], v[234:237], v[208:211], v[32:35]
	s_waitcnt vmcnt(6)
	ds_write_b128 v152, v[192:195] offset:36864
	s_waitcnt lgkmcnt(7)
	v_mfma_f32_16x16x32_bf16 v[28:31], v[238:241], v[196:199], v[28:31]
	v_mfma_f32_16x16x32_bf16 v[24:27], v[238:241], v[200:203], v[24:27]
	v_mfma_f32_16x16x32_bf16 v[20:23], v[238:241], v[204:207], v[20:23]
	v_mfma_f32_16x16x32_bf16 v[16:19], v[238:241], v[208:211], v[16:19]
	s_waitcnt lgkmcnt(6)
	v_mfma_f32_16x16x32_bf16 v[12:15], v[242:245], v[196:199], v[12:15]
	v_mfma_f32_16x16x32_bf16 v[8:11], v[242:245], v[200:203], v[8:11]
	v_mfma_f32_16x16x32_bf16 v[4:7], v[242:245], v[204:207], v[4:7]
	v_mfma_f32_16x16x32_bf16 v[0:3], v[242:245], v[208:211], v[0:3]
	s_setprio 0
	s_add_i32 s1, s1, 2
	s_mov_b32 s10, s11
	s_add_i32 s11, s10, 64
	s_min_u32 s13, s11, 0x3e0
	s_lshl_b32 s16, s13, 1
	v_lshl_add_u64 v[172:173], v[154:155], 0, s[16:17]
	v_lshl_add_u64 v[176:177], v[158:159], 0, s[16:17]
	v_lshl_add_u64 v[180:181], v[160:161], 0, s[16:17]
	v_lshl_add_u64 v[184:185], v[162:163], 0, s[16:17]
	v_lshl_add_u64 v[188:189], v[156:157], 0, s[16:17]
	v_lshl_add_u64 v[192:193], v[164:165], 0, s[16:17]
	s_cmp_lt_u32 s1, 30
	s_waitcnt lgkmcnt(0)
	s_cbranch_scc1 .Lrot_2
	s_barrier
	s_waitcnt vmcnt(5)
	v_mov_b32_e32 v114, v220
	v_mov_b32_e32 v115, v153
	v_and_b32_e32 v112, 0xffffff80, v114
	s_waitcnt vmcnt(4)
	v_add_u32_e32 v116, s0, v112
	v_lshrrev_b32_e32 v112, 2, v114
	v_and_b32_e32 v118, 12, v112
	s_waitcnt vmcnt(3)
	v_or_b32_e32 v120, v118, v116
	v_ashrrev_i32_e32 v121, 31, v120
	v_lshl_add_u64 v[112:113], v[120:121], 2, s[14:15]
	global_load_dwordx4 v[132:135], v[112:113], off
	v_ashrrev_i32_e32 v122, 14, v116
	v_ashrrev_i32_e32 v123, 31, v122
	v_lshlrev_b64 v[122:123], 10, v[122:123]
	v_mov_b64_e32 v[112:113], s[34:35]
	s_waitcnt vmcnt(3)
	v_lshrrev_b32_e32 v126, 6, v116
	v_or_b32_e32 v124, 16, v120
	v_lshl_or_b32 v121, s12, 8, v122
	v_ashrrev_i32_e32 v125, 31, v124
	v_and_or_b32 v122, v126, s49, v121
	s_waitcnt vmcnt(1)
	v_lshl_add_u64 v[136:137], v[124:125], 2, s[14:15]
	global_load_dwordx4 v[246:249], v[136:137], off
	v_lshlrev_b64 v[124:125], 14, v[122:123]
	v_lshlrev_b32_e32 v114, 7, v114
	v_lshlrev_b32_e32 v152, 1, v118
	v_lshl_add_u64 v[124:125], s[38:39], 0, v[124:125]
	v_and_b32_e32 v114, 0x2780, v114
	v_lshl_add_u64 v[126:127], v[124:125], 0, v[152:153]
	v_mov_b32_e32 v117, v153
	v_mov_b32_e32 v119, v153
	v_or_b32_e32 v116, 0x1000, v114
	v_or_b32_e32 v118, 0x1800, v114
	v_lshl_add_u64 v[124:125], v[126:127], 0, v[114:115]
	v_lshl_add_u64 v[138:139], v[126:127], 0, v[116:117]
	v_lshl_add_u64 v[154:155], v[126:127], 0, v[118:119]
	s_waitcnt vmcnt(1)
	v_pk_fma_f32 v[132:133], v[132:133], s[30:31], v[112:113] op_sel_hi:[1,0,0]
	v_pk_fma_f32 v[134:135], v[134:135], s[30:31], v[112:113] op_sel_hi:[1,0,0]
	v_mul_f32_e32 v122, 0x4b800000, v132
	v_mul_f32_e32 v156, 0x4b800000, v133
	v_mul_f32_e32 v157, 0x4b800000, v134
	v_mul_f32_e32 v158, 0x4b800000, v135
	v_cmp_gt_f32_e32 vcc, s40, v132
	v_cmp_gt_f32_e64 s[0:1], s40, v133
	v_cmp_gt_f32_e64 s[10:11], s40, v134
	v_cmp_gt_f32_e64 s[12:13], s40, v135
	v_cndmask_b32_e32 v122, v132, v122, vcc
	v_cndmask_b32_e64 v132, v133, v156, s[0:1]
	v_cndmask_b32_e64 v133, v134, v157, s[10:11]
	v_cndmask_b32_e64 v134, v135, v158, s[12:13]
	v_rsq_f32_e32 v122, v122
	v_rsq_f32_e32 v132, v132
	v_rsq_f32_e32 v133, v133
	v_rsq_f32_e32 v134, v134
	v_mul_f32_e32 v135, 0x45800000, v122
	v_mul_f32_e32 v156, 0x45800000, v132
	v_mul_f32_e32 v157, 0x45800000, v133
	v_mul_f32_e32 v158, 0x45800000, v134
	v_cndmask_b32_e32 v122, v122, v135, vcc
	v_cndmask_b32_e64 v132, v132, v156, s[0:1]
	v_cndmask_b32_e64 v133, v133, v157, s[10:11]
	v_cndmask_b32_e64 v134, v134, v158, s[12:13]
	v_mul_f32_e32 v135, v148, v122
	v_mul_f32_e32 v148, v149, v132
	v_mul_f32_e32 v149, v150, v133
	v_mul_f32_e32 v150, v151, v134
	v_mul_f32_e32 v144, v144, v122
	v_mul_f32_e32 v140, v140, v122
	v_mul_f32_e32 v122, v128, v122
	v_mul_f32_e32 v151, v129, v132
	v_cvt_pk_bf16_f32 v128, v135, v148
	v_cvt_pk_bf16_f32 v129, v149, v150
	v_mul_f32_e32 v145, v145, v132
	v_mul_f32_e32 v146, v146, v133
	v_mul_f32_e32 v147, v147, v134
	v_mul_f32_e32 v141, v141, v132
	v_mul_f32_e32 v142, v142, v133
	v_mul_f32_e32 v143, v143, v134
	v_mul_f32_e32 v156, v130, v133
	v_mul_f32_e32 v157, v131, v134
	v_cvt_pk_bf16_f32 v130, v144, v145
	v_cvt_pk_bf16_f32 v131, v146, v147
	v_cvt_pk_bf16_f32 v132, v140, v141
	v_cvt_pk_bf16_f32 v133, v142, v143
	v_cvt_pk_bf16_f32 v134, v122, v151
	v_cvt_pk_bf16_f32 v135, v156, v157
	global_store_dwordx2 v[124:125], v[128:129], off
	global_store_dwordx2 v[124:125], v[130:131], off offset:2048
	global_store_dwordx2 v[138:139], v[132:133], off
	global_store_dwordx2 v[154:155], v[134:135], off
	v_or_b32_e32 v132, 32, v120
	v_ashrrev_i32_e32 v133, 31, v132
	v_lshl_add_u64 v[134:135], v[126:127], 0, 32
	v_lshl_add_u64 v[132:133], v[132:133], 2, s[14:15]
	global_load_dwordx4 v[250:253], v[132:133], off
	v_lshl_add_u64 v[136:137], v[134:135], 0, v[116:117]
	v_lshl_add_u64 v[134:135], v[134:135], 0, v[118:119]
	s_waitcnt vmcnt(5)
	v_mov_b32_e32 v128, v246
	v_mov_b32_e32 v129, v247
	v_mov_b32_e32 v130, v248
	v_mov_b32_e32 v131, v249
	v_pk_fma_f32 v[128:129], v[128:129], s[30:31], v[112:113] op_sel_hi:[1,0,0]
	v_pk_fma_f32 v[130:131], v[130:131], s[30:31], v[112:113] op_sel_hi:[1,0,0]
	v_mul_f32_e32 v122, 0x4b800000, v128
	v_mul_f32_e32 v138, 0x4b800000, v129
	v_mul_f32_e32 v139, 0x4b800000, v130
	v_mul_f32_e32 v140, 0x4b800000, v131
	v_cmp_gt_f32_e32 vcc, s40, v128
	v_cmp_gt_f32_e64 s[0:1], s40, v129
	v_cmp_gt_f32_e64 s[10:11], s40, v130
	v_cmp_gt_f32_e64 s[12:13], s40, v131
	v_cndmask_b32_e32 v122, v128, v122, vcc
	v_cndmask_b32_e64 v128, v129, v138, s[0:1]
	v_cndmask_b32_e64 v129, v130, v139, s[10:11]
	v_cndmask_b32_e64 v130, v131, v140, s[12:13]
	v_rsq_f32_e32 v122, v122
	v_rsq_f32_e32 v128, v128
	v_rsq_f32_e32 v129, v129
	v_rsq_f32_e32 v130, v130
	v_mul_f32_e32 v131, 0x45800000, v122
	v_mul_f32_e32 v138, 0x45800000, v128
	v_mul_f32_e32 v139, 0x45800000, v129
	v_mul_f32_e32 v140, 0x45800000, v130
	v_cndmask_b32_e32 v122, v122, v131, vcc
	v_cndmask_b32_e64 v128, v128, v138, s[0:1]
	v_cndmask_b32_e64 v129, v129, v139, s[10:11]
	v_cndmask_b32_e64 v130, v130, v140, s[12:13]
	v_mul_f32_e32 v108, v108, v122
	v_mul_f32_e32 v109, v109, v128
	v_mul_f32_e32 v110, v110, v129
	v_mul_f32_e32 v111, v111, v130
	v_mul_f32_e32 v104, v104, v122
	v_mul_f32_e32 v105, v105, v128
	v_mul_f32_e32 v100, v100, v122
	v_mul_f32_e32 v101, v101, v128
	v_mul_f32_e32 v102, v102, v129
	v_mul_f32_e32 v103, v103, v130
	v_mul_f32_e32 v122, v96, v122
	v_mul_f32_e32 v128, v97, v128
	v_cvt_pk_bf16_f32 v96, v108, v109
	v_cvt_pk_bf16_f32 v97, v110, v111
	v_mul_f32_e32 v106, v106, v129
	v_mul_f32_e32 v107, v107, v130
	v_mul_f32_e32 v129, v98, v129
	v_mul_f32_e32 v130, v99, v130
	v_cvt_pk_bf16_f32 v98, v104, v105
	v_cvt_pk_bf16_f32 v99, v106, v107
	v_cvt_pk_bf16_f32 v100, v100, v101
	v_cvt_pk_bf16_f32 v101, v102, v103
	v_cvt_pk_bf16_f32 v102, v122, v128
	v_cvt_pk_bf16_f32 v103, v129, v130
	global_store_dwordx2 v[124:125], v[96:97], off offset:32
	global_store_dwordx2 v[124:125], v[98:99], off offset:2080
	global_store_dwordx2 v[136:137], v[100:101], off
	global_store_dwordx2 v[134:135], v[102:103], off
	v_or_b32_e32 v100, 48, v120
	v_ashrrev_i32_e32 v101, 31, v100
	v_lshl_add_u64 v[102:103], v[126:127], 0, 64
	v_lshl_add_u64 v[100:101], v[100:101], 2, s[14:15]
	global_load_dwordx4 v[246:249], v[100:101], off
	v_lshl_add_u64 v[104:105], v[102:103], 0, v[116:117]
	v_lshl_add_u64 v[102:103], v[102:103], 0, v[118:119]
	s_waitcnt vmcnt(5)
	v_mov_b32_e32 v96, v250
	v_mov_b32_e32 v97, v251
	v_mov_b32_e32 v98, v252
	v_mov_b32_e32 v99, v253
	v_pk_fma_f32 v[96:97], v[96:97], s[30:31], v[112:113] op_sel_hi:[1,0,0]
	v_pk_fma_f32 v[98:99], v[98:99], s[30:31], v[112:113] op_sel_hi:[1,0,0]
	v_mul_f32_e32 v106, 0x4b800000, v96
	v_mul_f32_e32 v107, 0x4b800000, v97
	v_mul_f32_e32 v108, 0x4b800000, v98
	v_mul_f32_e32 v109, 0x4b800000, v99
	v_cmp_gt_f32_e32 vcc, s40, v96
	v_cmp_gt_f32_e64 s[0:1], s40, v97
	v_cmp_gt_f32_e64 s[10:11], s40, v98
	v_cmp_gt_f32_e64 s[12:13], s40, v99
	v_cndmask_b32_e32 v96, v96, v106, vcc
	v_cndmask_b32_e64 v97, v97, v107, s[0:1]
	v_cndmask_b32_e64 v98, v98, v108, s[10:11]
	v_cndmask_b32_e64 v99, v99, v109, s[12:13]
	v_rsq_f32_e32 v96, v96
	v_rsq_f32_e32 v97, v97
	v_rsq_f32_e32 v98, v98
	v_rsq_f32_e32 v99, v99
	v_mul_f32_e32 v106, 0x45800000, v96
	v_mul_f32_e32 v107, 0x45800000, v97
	v_mul_f32_e32 v108, 0x45800000, v98
	v_mul_f32_e32 v109, 0x45800000, v99
	v_cndmask_b32_e32 v96, v96, v106, vcc
	v_cndmask_b32_e64 v97, v97, v107, s[0:1]
	v_cndmask_b32_e64 v98, v98, v108, s[10:11]
	v_cndmask_b32_e64 v99, v99, v109, s[12:13]
	v_mul_f32_e32 v92, v92, v96
	v_mul_f32_e32 v93, v93, v97
	v_mul_f32_e32 v94, v94, v98
	v_mul_f32_e32 v95, v95, v99
	v_mul_f32_e32 v88, v88, v96
	v_mul_f32_e32 v89, v89, v97
	v_mul_f32_e32 v84, v84, v96
	v_mul_f32_e32 v85, v85, v97
	v_mul_f32_e32 v86, v86, v98
	v_mul_f32_e32 v87, v87, v99
	v_mul_f32_e32 v96, v80, v96
	v_mul_f32_e32 v97, v81, v97
	v_cvt_pk_bf16_f32 v80, v92, v93
	v_cvt_pk_bf16_f32 v81, v94, v95
	v_mul_f32_e32 v90, v90, v98
	v_mul_f32_e32 v91, v91, v99
	v_mul_f32_e32 v98, v82, v98
	v_mul_f32_e32 v99, v83, v99
	v_cvt_pk_bf16_f32 v82, v88, v89
	v_cvt_pk_bf16_f32 v83, v90, v91
	v_cvt_pk_bf16_f32 v84, v84, v85
	v_cvt_pk_bf16_f32 v85, v86, v87
	v_cvt_pk_bf16_f32 v86, v96, v97
	v_cvt_pk_bf16_f32 v87, v98, v99
	global_store_dwordx2 v[124:125], v[80:81], off offset:64
	global_store_dwordx2 v[124:125], v[82:83], off offset:2112
	global_store_dwordx2 v[104:105], v[84:85], off
	global_store_dwordx2 v[102:103], v[86:87], off
	v_or_b32_e32 v84, 64, v120
	v_ashrrev_i32_e32 v85, 31, v84
	v_lshl_add_u64 v[86:87], v[84:85], 2, s[14:15]
	global_load_dwordx4 v[250:253], v[86:87], off
	v_lshl_add_u64 v[88:89], v[126:127], 0, s[36:37]
	v_lshl_add_u64 v[90:91], v[88:89], 0, v[116:117]
	v_lshl_add_u64 v[88:89], v[88:89], 0, v[118:119]
	s_waitcnt vmcnt(5)
	v_mov_b32_e32 v80, v246
	v_mov_b32_e32 v81, v247
	v_mov_b32_e32 v82, v248
	v_mov_b32_e32 v83, v249
	v_pk_fma_f32 v[80:81], v[80:81], s[30:31], v[112:113] op_sel_hi:[1,0,0]
	v_pk_fma_f32 v[82:83], v[82:83], s[30:31], v[112:113] op_sel_hi:[1,0,0]
	v_mul_f32_e32 v85, 0x4b800000, v80
	v_mul_f32_e32 v92, 0x4b800000, v81
	v_mul_f32_e32 v93, 0x4b800000, v82
	v_mul_f32_e32 v94, 0x4b800000, v83
	v_cmp_gt_f32_e32 vcc, s40, v80
	v_cmp_gt_f32_e64 s[0:1], s40, v81
	v_cmp_gt_f32_e64 s[10:11], s40, v82
	v_cmp_gt_f32_e64 s[12:13], s40, v83
	v_cndmask_b32_e32 v80, v80, v85, vcc
	v_cndmask_b32_e64 v81, v81, v92, s[0:1]
	v_cndmask_b32_e64 v82, v82, v93, s[10:11]
	v_cndmask_b32_e64 v83, v83, v94, s[12:13]
	v_rsq_f32_e32 v80, v80
	v_rsq_f32_e32 v81, v81
	v_rsq_f32_e32 v82, v82
	v_rsq_f32_e32 v83, v83
	v_mul_f32_e32 v85, 0x45800000, v80
	v_mul_f32_e32 v92, 0x45800000, v81
	v_mul_f32_e32 v93, 0x45800000, v82
	v_mul_f32_e32 v94, 0x45800000, v83
	v_cndmask_b32_e32 v80, v80, v85, vcc
	v_cndmask_b32_e64 v81, v81, v92, s[0:1]
	v_cndmask_b32_e64 v82, v82, v93, s[10:11]
	v_cndmask_b32_e64 v83, v83, v94, s[12:13]
	v_mul_f32_e32 v76, v76, v80
	v_mul_f32_e32 v77, v77, v81
	v_mul_f32_e32 v78, v78, v82
	v_mul_f32_e32 v79, v79, v83
	v_mul_f32_e32 v72, v72, v80
	v_mul_f32_e32 v73, v73, v81
	v_mul_f32_e32 v68, v68, v80
	v_mul_f32_e32 v69, v69, v81
	v_mul_f32_e32 v70, v70, v82
	v_mul_f32_e32 v71, v71, v83
	v_mul_f32_e32 v80, v64, v80
	v_mul_f32_e32 v81, v65, v81
	v_cvt_pk_bf16_f32 v64, v76, v77
	v_cvt_pk_bf16_f32 v65, v78, v79
	v_mul_f32_e32 v74, v74, v82
	v_mul_f32_e32 v75, v75, v83
	v_mul_f32_e32 v82, v66, v82
	v_mul_f32_e32 v83, v67, v83
	v_cvt_pk_bf16_f32 v66, v72, v73
	v_cvt_pk_bf16_f32 v67, v74, v75
	v_cvt_pk_bf16_f32 v68, v68, v69
	v_cvt_pk_bf16_f32 v69, v70, v71
	v_cvt_pk_bf16_f32 v70, v80, v81
	v_cvt_pk_bf16_f32 v71, v82, v83
	global_store_dwordx2 v[124:125], v[64:65], off offset:96
	global_store_dwordx2 v[124:125], v[66:67], off offset:2144
	global_store_dwordx2 v[90:91], v[68:69], off
	global_store_dwordx2 v[88:89], v[70:71], off
	v_or_b32_e32 v68, 0x50, v120
	v_ashrrev_i32_e32 v69, 31, v68
	v_lshl_add_u64 v[70:71], v[68:69], 2, s[14:15]
	global_load_dwordx4 v[246:249], v[70:71], off
	v_lshrrev_b32_e32 v72, 6, v84
	v_and_or_b32 v122, v72, s50, v121
	v_lshlrev_b64 v[72:73], 14, v[122:123]
	v_lshl_add_u64 v[72:73], s[38:39], 0, v[72:73]
	v_lshl_add_u64 v[72:73], v[72:73], 0, v[152:153]
	v_lshl_add_u64 v[74:75], v[72:73], 0, v[114:115]
	v_lshl_add_u64 v[76:77], v[72:73], 0, v[116:117]
	v_lshl_add_u64 v[72:73], v[72:73], 0, v[118:119]
	s_waitcnt vmcnt(5)
	v_mov_b32_e32 v64, v250
	v_mov_b32_e32 v65, v251
	v_mov_b32_e32 v66, v252
	v_mov_b32_e32 v67, v253
	v_pk_fma_f32 v[64:65], v[64:65], s[30:31], v[112:113] op_sel_hi:[1,0,0]
	v_pk_fma_f32 v[66:67], v[66:67], s[30:31], v[112:113] op_sel_hi:[1,0,0]
	v_mul_f32_e32 v69, 0x4b800000, v64
	v_mul_f32_e32 v78, 0x4b800000, v65
	v_mul_f32_e32 v79, 0x4b800000, v66
	v_mul_f32_e32 v80, 0x4b800000, v67
	v_cmp_gt_f32_e32 vcc, s40, v64
	v_cmp_gt_f32_e64 s[0:1], s40, v65
	v_cmp_gt_f32_e64 s[10:11], s40, v66
	v_cmp_gt_f32_e64 s[12:13], s40, v67
	v_cndmask_b32_e32 v64, v64, v69, vcc
	v_cndmask_b32_e64 v65, v65, v78, s[0:1]
	v_cndmask_b32_e64 v66, v66, v79, s[10:11]
	v_cndmask_b32_e64 v67, v67, v80, s[12:13]
	v_rsq_f32_e32 v64, v64
	v_rsq_f32_e32 v65, v65
	v_rsq_f32_e32 v66, v66
	v_rsq_f32_e32 v67, v67
	v_mul_f32_e32 v69, 0x45800000, v64
	v_mul_f32_e32 v78, 0x45800000, v65
	v_mul_f32_e32 v79, 0x45800000, v66
	v_mul_f32_e32 v80, 0x45800000, v67
	v_cndmask_b32_e32 v64, v64, v69, vcc
	v_cndmask_b32_e64 v65, v65, v78, s[0:1]
	v_cndmask_b32_e64 v66, v66, v79, s[10:11]
	v_cndmask_b32_e64 v67, v67, v80, s[12:13]
	v_mul_f32_e32 v60, v60, v64
	v_mul_f32_e32 v61, v61, v65
	v_mul_f32_e32 v62, v62, v66
	v_mul_f32_e32 v63, v63, v67
	v_mul_f32_e32 v56, v56, v64
	v_mul_f32_e32 v57, v57, v65
	v_mul_f32_e32 v52, v52, v64
	v_mul_f32_e32 v53, v53, v65
	v_mul_f32_e32 v54, v54, v66
	v_mul_f32_e32 v55, v55, v67
	v_mul_f32_e32 v64, v48, v64
	v_mul_f32_e32 v65, v49, v65
	v_cvt_pk_bf16_f32 v48, v60, v61
	v_cvt_pk_bf16_f32 v49, v62, v63
	v_mul_f32_e32 v58, v58, v66
	v_mul_f32_e32 v59, v59, v67
	v_mul_f32_e32 v66, v50, v66
	v_mul_f32_e32 v67, v51, v67
	v_cvt_pk_bf16_f32 v50, v56, v57
	v_cvt_pk_bf16_f32 v51, v58, v59
	v_cvt_pk_bf16_f32 v52, v52, v53
	v_cvt_pk_bf16_f32 v53, v54, v55
	v_cvt_pk_bf16_f32 v54, v64, v65
	v_cvt_pk_bf16_f32 v55, v66, v67
	global_store_dwordx2 v[74:75], v[48:49], off
	global_store_dwordx2 v[74:75], v[50:51], off offset:2048
	global_store_dwordx2 v[76:77], v[52:53], off
	global_store_dwordx2 v[72:73], v[54:55], off
	v_or_b32_e32 v52, 0x60, v120
	v_ashrrev_i32_e32 v53, 31, v52
	v_lshl_add_u64 v[54:55], v[52:53], 2, s[14:15]
	global_load_dwordx4 v[250:253], v[54:55], off
	v_lshrrev_b32_e32 v56, 6, v68
	v_and_or_b32 v122, v56, s50, v121
	v_lshlrev_b64 v[56:57], 14, v[122:123]
	v_lshl_add_u64 v[56:57], s[38:39], 0, v[56:57]
	v_lshl_add_u64 v[56:57], v[56:57], 0, v[152:153]
	v_lshl_add_u64 v[58:59], v[56:57], 0, 32
	v_lshl_add_u64 v[56:57], v[56:57], 0, v[114:115]
	v_lshl_add_u64 v[60:61], v[58:59], 0, v[116:117]
	v_lshl_add_u64 v[58:59], v[58:59], 0, v[118:119]
	s_waitcnt vmcnt(5)
	v_mov_b32_e32 v48, v246
	v_mov_b32_e32 v49, v247
	v_mov_b32_e32 v50, v248
	v_mov_b32_e32 v51, v249
	v_pk_fma_f32 v[48:49], v[48:49], s[30:31], v[112:113] op_sel_hi:[1,0,0]
	v_pk_fma_f32 v[50:51], v[50:51], s[30:31], v[112:113] op_sel_hi:[1,0,0]
	v_mul_f32_e32 v53, 0x4b800000, v48
	v_mul_f32_e32 v62, 0x4b800000, v49
	v_mul_f32_e32 v63, 0x4b800000, v50
	v_mul_f32_e32 v64, 0x4b800000, v51
	v_cmp_gt_f32_e32 vcc, s40, v48
	v_cmp_gt_f32_e64 s[0:1], s40, v49
	v_cmp_gt_f32_e64 s[10:11], s40, v50
	v_cmp_gt_f32_e64 s[12:13], s40, v51
	v_cndmask_b32_e32 v48, v48, v53, vcc
	v_cndmask_b32_e64 v49, v49, v62, s[0:1]
	v_cndmask_b32_e64 v50, v50, v63, s[10:11]
	v_cndmask_b32_e64 v51, v51, v64, s[12:13]
	v_rsq_f32_e32 v48, v48
	v_rsq_f32_e32 v49, v49
	v_rsq_f32_e32 v50, v50
	v_rsq_f32_e32 v51, v51
	v_mul_f32_e32 v53, 0x45800000, v48
	v_mul_f32_e32 v62, 0x45800000, v49
	v_mul_f32_e32 v63, 0x45800000, v50
	v_mul_f32_e32 v64, 0x45800000, v51
	v_cndmask_b32_e32 v48, v48, v53, vcc
	v_cndmask_b32_e64 v49, v49, v62, s[0:1]
	v_cndmask_b32_e64 v50, v50, v63, s[10:11]
	v_cndmask_b32_e64 v51, v51, v64, s[12:13]
	v_mul_f32_e32 v44, v44, v48
	v_mul_f32_e32 v45, v45, v49
	v_mul_f32_e32 v46, v46, v50
	v_mul_f32_e32 v47, v47, v51
	v_mul_f32_e32 v40, v40, v48
	v_mul_f32_e32 v41, v41, v49
	v_mul_f32_e32 v36, v36, v48
	v_mul_f32_e32 v37, v37, v49
	v_mul_f32_e32 v38, v38, v50
	v_mul_f32_e32 v39, v39, v51
	v_mul_f32_e32 v48, v32, v48
	v_mul_f32_e32 v49, v33, v49
	v_cvt_pk_bf16_f32 v32, v44, v45
	v_cvt_pk_bf16_f32 v33, v46, v47
	v_mul_f32_e32 v42, v42, v50
	v_mul_f32_e32 v43, v43, v51
	v_mul_f32_e32 v50, v34, v50
	v_mul_f32_e32 v51, v35, v51
	v_cvt_pk_bf16_f32 v34, v40, v41
	v_cvt_pk_bf16_f32 v35, v42, v43
	v_cvt_pk_bf16_f32 v36, v36, v37
	v_cvt_pk_bf16_f32 v37, v38, v39
	v_cvt_pk_bf16_f32 v38, v48, v49
	v_cvt_pk_bf16_f32 v39, v50, v51
	global_store_dwordx2 v[56:57], v[32:33], off offset:32
	global_store_dwordx2 v[56:57], v[34:35], off offset:2080
	global_store_dwordx2 v[60:61], v[36:37], off
	global_store_dwordx2 v[58:59], v[38:39], off
	v_or_b32_e32 v36, 0x70, v120
	v_ashrrev_i32_e32 v37, 31, v36
	v_lshl_add_u64 v[38:39], v[36:37], 2, s[14:15]
	global_load_dwordx4 v[246:249], v[38:39], off
	v_lshrrev_b32_e32 v40, 6, v52
	v_and_or_b32 v122, v40, s50, v121
	v_lshlrev_b64 v[40:41], 14, v[122:123]
	v_lshl_add_u64 v[40:41], s[38:39], 0, v[40:41]
	v_lshl_add_u64 v[40:41], v[40:41], 0, v[152:153]
	v_lshl_add_u64 v[42:43], v[40:41], 0, 64
	v_lshl_add_u64 v[40:41], v[40:41], 0, v[114:115]
	v_lshl_add_u64 v[44:45], v[42:43], 0, v[116:117]
	v_lshl_add_u64 v[42:43], v[42:43], 0, v[118:119]
	s_waitcnt vmcnt(5)
	v_mov_b32_e32 v32, v250
	v_mov_b32_e32 v33, v251
	v_mov_b32_e32 v34, v252
	v_mov_b32_e32 v35, v253
	v_pk_fma_f32 v[32:33], v[32:33], s[30:31], v[112:113] op_sel_hi:[1,0,0]
	v_pk_fma_f32 v[34:35], v[34:35], s[30:31], v[112:113] op_sel_hi:[1,0,0]
	v_mul_f32_e32 v37, 0x4b800000, v32
	v_mul_f32_e32 v46, 0x4b800000, v33
	v_mul_f32_e32 v47, 0x4b800000, v34
	v_mul_f32_e32 v48, 0x4b800000, v35
	v_cmp_gt_f32_e32 vcc, s40, v32
	v_cmp_gt_f32_e64 s[0:1], s40, v33
	v_cmp_gt_f32_e64 s[10:11], s40, v34
	v_cmp_gt_f32_e64 s[12:13], s40, v35
	v_cndmask_b32_e32 v32, v32, v37, vcc
	v_cndmask_b32_e64 v33, v33, v46, s[0:1]
	v_cndmask_b32_e64 v34, v34, v47, s[10:11]
	v_cndmask_b32_e64 v35, v35, v48, s[12:13]
	v_rsq_f32_e32 v32, v32
	v_rsq_f32_e32 v33, v33
	v_rsq_f32_e32 v34, v34
	v_rsq_f32_e32 v35, v35
	v_mul_f32_e32 v37, 0x45800000, v32
	v_mul_f32_e32 v46, 0x45800000, v33
	v_mul_f32_e32 v47, 0x45800000, v34
	v_mul_f32_e32 v48, 0x45800000, v35
	v_cndmask_b32_e32 v32, v32, v37, vcc
	v_cndmask_b32_e64 v33, v33, v46, s[0:1]
	v_cndmask_b32_e64 v34, v34, v47, s[10:11]
	v_cndmask_b32_e64 v35, v35, v48, s[12:13]
	v_mul_f32_e32 v28, v28, v32
	v_mul_f32_e32 v29, v29, v33
	v_mul_f32_e32 v30, v30, v34
	v_mul_f32_e32 v31, v31, v35
	v_mul_f32_e32 v24, v24, v32
	v_mul_f32_e32 v25, v25, v33
	v_mul_f32_e32 v20, v20, v32
	v_mul_f32_e32 v21, v21, v33
	v_mul_f32_e32 v22, v22, v34
	v_mul_f32_e32 v23, v23, v35
	v_mul_f32_e32 v32, v16, v32
	v_mul_f32_e32 v33, v17, v33
	v_cvt_pk_bf16_f32 v16, v28, v29
	v_cvt_pk_bf16_f32 v17, v30, v31
	v_mul_f32_e32 v26, v26, v34
	v_mul_f32_e32 v27, v27, v35
	v_mul_f32_e32 v34, v18, v34
	v_mul_f32_e32 v35, v19, v35
	v_cvt_pk_bf16_f32 v18, v24, v25
	v_cvt_pk_bf16_f32 v19, v26, v27
	v_cvt_pk_bf16_f32 v20, v20, v21
	v_cvt_pk_bf16_f32 v21, v22, v23
	v_cvt_pk_bf16_f32 v22, v32, v33
	v_cvt_pk_bf16_f32 v23, v34, v35
	global_store_dwordx2 v[40:41], v[16:17], off offset:64
	global_store_dwordx2 v[40:41], v[18:19], off offset:2112
	global_store_dwordx2 v[44:45], v[20:21], off
	global_store_dwordx2 v[42:43], v[22:23], off
	v_lshrrev_b32_e32 v20, 6, v36
	v_and_or_b32 v122, v20, s50, v121
	v_lshlrev_b64 v[20:21], 14, v[122:123]
	v_lshl_add_u64 v[20:21], s[38:39], 0, v[20:21]
	v_lshl_add_u64 v[20:21], v[20:21], 0, v[152:153]
	v_lshl_add_u64 v[22:23], v[20:21], 0, s[36:37]
	v_lshl_add_u64 v[20:21], v[20:21], 0, v[114:115]
	v_lshl_add_u64 v[24:25], v[22:23], 0, v[116:117]
	v_lshl_add_u64 v[22:23], v[22:23], 0, v[118:119]
	s_waitcnt vmcnt(4)
	v_mov_b32_e32 v16, v246
	v_mov_b32_e32 v17, v247
	v_mov_b32_e32 v18, v248
	v_mov_b32_e32 v19, v249
	v_pk_fma_f32 v[16:17], v[16:17], s[30:31], v[112:113] op_sel_hi:[1,0,0]
	v_pk_fma_f32 v[18:19], v[18:19], s[30:31], v[112:113] op_sel_hi:[1,0,0]
	v_mul_f32_e32 v26, 0x4b800000, v16
	v_mul_f32_e32 v27, 0x4b800000, v17
	v_mul_f32_e32 v28, 0x4b800000, v18
	v_mul_f32_e32 v29, 0x4b800000, v19
	v_cmp_gt_f32_e32 vcc, s40, v16
	v_cmp_gt_f32_e64 s[0:1], s40, v17
	v_cmp_gt_f32_e64 s[10:11], s40, v18
	v_cmp_gt_f32_e64 s[12:13], s40, v19
	v_cndmask_b32_e32 v16, v16, v26, vcc
	v_cndmask_b32_e64 v17, v17, v27, s[0:1]
	v_cndmask_b32_e64 v18, v18, v28, s[10:11]
	v_cndmask_b32_e64 v19, v19, v29, s[12:13]
	v_rsq_f32_e32 v16, v16
	v_rsq_f32_e32 v17, v17
	v_rsq_f32_e32 v18, v18
	v_rsq_f32_e32 v19, v19
	v_mul_f32_e32 v26, 0x45800000, v16
	v_mul_f32_e32 v27, 0x45800000, v17
	v_mul_f32_e32 v28, 0x45800000, v18
	v_mul_f32_e32 v29, 0x45800000, v19
	v_cndmask_b32_e32 v16, v16, v26, vcc
	v_cndmask_b32_e64 v17, v17, v27, s[0:1]
	v_cndmask_b32_e64 v18, v18, v28, s[10:11]
	v_cndmask_b32_e64 v19, v19, v29, s[12:13]
	v_mul_f32_e32 v12, v12, v16
	v_mul_f32_e32 v13, v13, v17
	v_mul_f32_e32 v14, v14, v18
	v_mul_f32_e32 v15, v15, v19
	v_mul_f32_e32 v8, v8, v16
	v_mul_f32_e32 v9, v9, v17
	v_mul_f32_e32 v4, v4, v16
	v_mul_f32_e32 v5, v5, v17
	v_mul_f32_e32 v6, v6, v18
	v_mul_f32_e32 v7, v7, v19
	v_mul_f32_e32 v16, v0, v16
	v_mul_f32_e32 v17, v1, v17
	v_cvt_pk_bf16_f32 v0, v12, v13
	v_cvt_pk_bf16_f32 v1, v14, v15
	v_mul_f32_e32 v10, v10, v18
	v_mul_f32_e32 v11, v11, v19
	v_mul_f32_e32 v18, v2, v18
	v_mul_f32_e32 v19, v3, v19
	v_cvt_pk_bf16_f32 v2, v8, v9
	v_cvt_pk_bf16_f32 v3, v10, v11
	v_cvt_pk_bf16_f32 v4, v4, v5
	v_cvt_pk_bf16_f32 v5, v6, v7
	v_cvt_pk_bf16_f32 v6, v16, v17
	v_cvt_pk_bf16_f32 v7, v18, v19
	global_store_dwordx2 v[20:21], v[0:1], off offset:96
	global_store_dwordx2 v[20:21], v[2:3], off offset:2144
	global_store_dwordx2 v[24:25], v[4:5], off
	global_store_dwordx2 v[22:23], v[6:7], off
	s_branch .LBB0_699

.LBB0_769:
	ds_read_b128 v[196:199], v171 offset:32768
	ds_read_b128 v[200:203], v171 offset:33792
	ds_read_b128 v[204:207], v171 offset:34816
	ds_read_b128 v[208:211], v171 offset:35840
	ds_read_b128 v[212:215], v169
	ds_read_b128 v[216:219], v169 offset:1024
	ds_read_b128 v[222:225], v169 offset:2048
	ds_read_b128 v[226:229], v169 offset:3072
	ds_read_b128 v[230:233], v169 offset:4096
	ds_read_b128 v[234:237], v169 offset:5120
	ds_read_b128 v[238:241], v169 offset:6144
	ds_read_b128 v[242:245], v169 offset:7168
	s_setprio 1
	s_waitcnt lgkmcnt(7)
	v_mfma_f32_16x16x32_bf16 v[148:151], v[196:199], v[212:215], v[148:151]
	v_mfma_f32_16x16x32_bf16 v[144:147], v[200:203], v[212:215], v[144:147]
	v_mfma_f32_16x16x32_bf16 v[116:119], v[204:207], v[212:215], v[116:119]
	v_mfma_f32_16x16x32_bf16 v[112:115], v[208:211], v[212:215], v[112:115]
	global_load_dwordx4 v[172:175], v[172:173], off
	global_load_dwordx4 v[176:179], v[176:177], off
	global_load_dwordx4 v[180:183], v[180:181], off
	global_load_dwordx4 v[184:187], v[184:185], off
	global_load_dwordx4 v[188:191], v[188:189], off
	global_load_dwordx4 v[192:195], v[192:193], off
	s_waitcnt vmcnt(11)
	ds_write_b128 v152, v[120:123] offset:16384
	s_waitcnt lgkmcnt(7)
	v_mfma_f32_16x16x32_bf16 v[108:111], v[196:199], v[216:219], v[108:111]
	v_mfma_f32_16x16x32_bf16 v[104:107], v[200:203], v[216:219], v[104:107]
	v_mfma_f32_16x16x32_bf16 v[100:103], v[204:207], v[216:219], v[100:103]
	v_mfma_f32_16x16x32_bf16 v[96:99], v[208:211], v[216:219], v[96:99]
	s_waitcnt vmcnt(9)
	ds_write_b128 v152, v[128:131] offset:20480
	s_waitcnt lgkmcnt(7)
	v_mfma_f32_16x16x32_bf16 v[92:95], v[196:199], v[222:225], v[92:95]
	v_mfma_f32_16x16x32_bf16 v[88:91], v[200:203], v[222:225], v[88:91]
	v_mfma_f32_16x16x32_bf16 v[84:87], v[204:207], v[222:225], v[84:87]
	v_mfma_f32_16x16x32_bf16 v[80:83], v[208:211], v[222:225], v[80:83]
	s_waitcnt vmcnt(8)
	ds_write_b128 v152, v[132:135] offset:24576
	s_waitcnt lgkmcnt(7)
	v_mfma_f32_16x16x32_bf16 v[76:79], v[196:199], v[226:229], v[76:79]
	v_mfma_f32_16x16x32_bf16 v[72:75], v[200:203], v[226:229], v[72:75]
	v_mfma_f32_16x16x32_bf16 v[68:71], v[204:207], v[226:229], v[68:71]
	v_mfma_f32_16x16x32_bf16 v[64:67], v[208:211], v[226:229], v[64:67]
	s_waitcnt vmcnt(7)
	ds_write_b128 v152, v[136:139] offset:28672
	s_waitcnt lgkmcnt(7)
	v_mfma_f32_16x16x32_bf16 v[60:63], v[196:199], v[230:233], v[60:63]
	v_mfma_f32_16x16x32_bf16 v[56:59], v[200:203], v[230:233], v[56:59]
	v_mfma_f32_16x16x32_bf16 v[52:55], v[204:207], v[230:233], v[52:55]
	v_mfma_f32_16x16x32_bf16 v[48:51], v[208:211], v[230:233], v[48:51]
	s_waitcnt vmcnt(7)
	ds_write_b128 v152, v[124:127] offset:40960
	s_waitcnt lgkmcnt(7)
	v_mfma_f32_16x16x32_bf16 v[44:47], v[196:199], v[234:237], v[44:47]
	v_mfma_f32_16x16x32_bf16 v[40:43], v[200:203], v[234:237], v[40:43]
	v_mfma_f32_16x16x32_bf16 v[36:39], v[204:207], v[234:237], v[36:39]
	v_mfma_f32_16x16x32_bf16 v[32:35], v[208:211], v[234:237], v[32:35]
	s_waitcnt vmcnt(6)
	ds_write_b128 v152, v[140:143] offset:45056
	s_waitcnt lgkmcnt(7)
	v_mfma_f32_16x16x32_bf16 v[28:31], v[196:199], v[238:241], v[28:31]
	v_mfma_f32_16x16x32_bf16 v[24:27], v[200:203], v[238:241], v[24:27]
	v_mfma_f32_16x16x32_bf16 v[20:23], v[204:207], v[238:241], v[20:23]
	v_mfma_f32_16x16x32_bf16 v[16:19], v[208:211], v[238:241], v[16:19]
	s_waitcnt lgkmcnt(6)
	v_mfma_f32_16x16x32_bf16 v[12:15], v[196:199], v[242:245], v[12:15]
	v_mfma_f32_16x16x32_bf16 v[8:11], v[200:203], v[242:245], v[8:11]
	v_mfma_f32_16x16x32_bf16 v[4:7], v[204:207], v[242:245], v[4:7]
	v_mfma_f32_16x16x32_bf16 v[0:3], v[208:211], v[242:245], v[0:3]
	s_setprio 0
	s_min_u32 s13, s13, 0x380
	s_lshl_b32 s34, s13, 1
	s_mov_b32 s17, s35
	s_add_i32 s16, s34, 0xc0
	v_lshl_add_u64 v[120:121], v[154:155], 0, s[34:35]
	v_lshl_add_u64 v[124:125], v[156:157], 0, s[34:35]
	v_lshl_add_u64 v[128:129], v[158:159], 0, s[16:17]
	v_lshl_add_u64 v[132:133], v[160:161], 0, s[16:17]
	v_lshl_add_u64 v[136:137], v[162:163], 0, s[16:17]
	v_lshl_add_u64 v[140:141], v[164:165], 0, s[16:17]
	s_waitcnt lgkmcnt(0)
	s_barrier
	ds_read_b128 v[196:199], v168 offset:40960
	ds_read_b128 v[200:203], v168 offset:41984
	ds_read_b128 v[204:207], v168 offset:43008
	ds_read_b128 v[208:211], v168 offset:44032
	ds_read_b128 v[212:215], v170
	ds_read_b128 v[216:219], v170 offset:1024
	ds_read_b128 v[222:225], v170 offset:2048
	ds_read_b128 v[226:229], v170 offset:3072
	ds_read_b128 v[230:233], v170 offset:4096
	ds_read_b128 v[234:237], v170 offset:5120
	ds_read_b128 v[238:241], v170 offset:6144
	ds_read_b128 v[242:245], v170 offset:7168
	s_setprio 1
	s_waitcnt lgkmcnt(7)
	v_mfma_f32_16x16x32_bf16 v[148:151], v[196:199], v[212:215], v[148:151]
	v_mfma_f32_16x16x32_bf16 v[144:147], v[200:203], v[212:215], v[144:147]
	v_mfma_f32_16x16x32_bf16 v[116:119], v[204:207], v[212:215], v[116:119]
	v_mfma_f32_16x16x32_bf16 v[112:115], v[208:211], v[212:215], v[112:115]
	global_load_dwordx4 v[120:123], v[120:121], off offset:192
	global_load_dwordx4 v[124:127], v[124:125], off offset:192
	global_load_dwordx4 v[128:131], v[128:129], off
	global_load_dwordx4 v[132:135], v[132:133], off
	global_load_dwordx4 v[136:139], v[136:137], off
	global_load_dwordx4 v[140:143], v[140:141], off
	s_waitcnt vmcnt(11)
	ds_write_b128 v152, v[172:175]
	s_waitcnt lgkmcnt(7)
	v_mfma_f32_16x16x32_bf16 v[108:111], v[196:199], v[216:219], v[108:111]
	v_mfma_f32_16x16x32_bf16 v[104:107], v[200:203], v[216:219], v[104:107]
	v_mfma_f32_16x16x32_bf16 v[100:103], v[204:207], v[216:219], v[100:103]
	v_mfma_f32_16x16x32_bf16 v[96:99], v[208:211], v[216:219], v[96:99]
	s_waitcnt vmcnt(10)
	ds_write_b128 v152, v[176:179] offset:4096
	s_waitcnt lgkmcnt(7)
	v_mfma_f32_16x16x32_bf16 v[92:95], v[196:199], v[222:225], v[92:95]
	v_mfma_f32_16x16x32_bf16 v[88:91], v[200:203], v[222:225], v[88:91]
	v_mfma_f32_16x16x32_bf16 v[84:87], v[204:207], v[222:225], v[84:87]
	v_mfma_f32_16x16x32_bf16 v[80:83], v[208:211], v[222:225], v[80:83]
	s_waitcnt vmcnt(9)
	ds_write_b128 v152, v[180:183] offset:8192
	s_waitcnt lgkmcnt(7)
	v_mfma_f32_16x16x32_bf16 v[76:79], v[196:199], v[226:229], v[76:79]
	v_mfma_f32_16x16x32_bf16 v[72:75], v[200:203], v[226:229], v[72:75]
	v_mfma_f32_16x16x32_bf16 v[68:71], v[204:207], v[226:229], v[68:71]
	v_mfma_f32_16x16x32_bf16 v[64:67], v[208:211], v[226:229], v[64:67]
	s_waitcnt vmcnt(8)
	ds_write_b128 v152, v[184:187] offset:12288
	s_waitcnt lgkmcnt(7)
	v_mfma_f32_16x16x32_bf16 v[60:63], v[196:199], v[230:233], v[60:63]
	v_mfma_f32_16x16x32_bf16 v[56:59], v[200:203], v[230:233], v[56:59]
	v_mfma_f32_16x16x32_bf16 v[52:55], v[204:207], v[230:233], v[52:55]
	v_mfma_f32_16x16x32_bf16 v[48:51], v[208:211], v[230:233], v[48:51]
	s_waitcnt vmcnt(7)
	ds_write_b128 v152, v[188:191] offset:32768
	s_waitcnt lgkmcnt(7)
	v_mfma_f32_16x16x32_bf16 v[44:47], v[196:199], v[234:237], v[44:47]
	v_mfma_f32_16x16x32_bf16 v[40:43], v[200:203], v[234:237], v[40:43]
	v_mfma_f32_16x16x32_bf16 v[36:39], v[204:207], v[234:237], v[36:39]
	v_mfma_f32_16x16x32_bf16 v[32:35], v[208:211], v[234:237], v[32:35]
	s_waitcnt vmcnt(6)
	ds_write_b128 v152, v[192:195] offset:36864
	s_waitcnt lgkmcnt(7)
	v_mfma_f32_16x16x32_bf16 v[28:31], v[196:199], v[238:241], v[28:31]
	v_mfma_f32_16x16x32_bf16 v[24:27], v[200:203], v[238:241], v[24:27]
	v_mfma_f32_16x16x32_bf16 v[20:23], v[204:207], v[238:241], v[20:23]
	v_mfma_f32_16x16x32_bf16 v[16:19], v[208:211], v[238:241], v[16:19]
	s_waitcnt lgkmcnt(6)
	v_mfma_f32_16x16x32_bf16 v[12:15], v[196:199], v[242:245], v[12:15]
	v_mfma_f32_16x16x32_bf16 v[8:11], v[200:203], v[242:245], v[8:11]
	v_mfma_f32_16x16x32_bf16 v[4:7], v[204:207], v[242:245], v[4:7]
	v_mfma_f32_16x16x32_bf16 v[0:3], v[208:211], v[242:245], v[0:3]
	s_setprio 0
	s_add_i32 s11, s11, 2
	s_mov_b32 s13, s14
	s_add_i32 s14, s13, 64
	s_min_u32 s15, s14, 0x3e0
	s_lshl_b32 s34, s15, 1
	v_lshl_add_u64 v[172:173], v[154:155], 0, s[34:35]
	v_lshl_add_u64 v[176:177], v[158:159], 0, s[34:35]
	v_lshl_add_u64 v[180:181], v[160:161], 0, s[34:35]
	v_lshl_add_u64 v[184:185], v[162:163], 0, s[34:35]
	v_lshl_add_u64 v[188:189], v[156:157], 0, s[34:35]
	v_lshl_add_u64 v[192:193], v[164:165], 0, s[34:35]
	s_cmp_lt_u32 s11, 30
	s_waitcnt lgkmcnt(0)
	s_cbranch_scc1 .Lrot_1
	s_barrier
	s_waitcnt vmcnt(4)
	v_mov_b32_e32 v126, v220
	v_mov_b64_e32 v[124:125], s[72:73]
	v_and_b32_e32 v120, 0xffffff80, v126
	v_add_u32_e32 v120, s12, v120
	v_and_or_b32 v122, v126, 15, v120
	v_ashrrev_i32_e32 v123, 31, v122
	v_lshl_add_u64 v[120:121], v[122:123], 2, s[0:1]
	global_load_dword v246, v[120:121], off offset:64
	global_load_dword v247, v[120:121], off offset:128
	global_load_dword v248, v[120:121], off offset:192
	global_load_dword v249, v[120:121], off offset:256
	global_load_dword v250, v[120:121], off offset:320
	global_load_dword v251, v[120:121], off offset:384
	global_load_dword v252, v[120:121], off offset:448
	global_load_dword v120, v[120:121], off
	v_and_b32_e32 v121, 64, v126
	v_lshrrev_b32_e32 v126, 2, v126
	v_and_b32_e32 v126, 12, v126
	s_waitcnt vmcnt(0)
	v_fmamk_f32 v120, v120, 0x3a800000, v167
	v_mul_f32_e32 v127, 0x4b800000, v120
	v_cmp_gt_f32_e32 vcc, s42, v120
	s_nop 1
	v_cndmask_b32_e32 v120, v120, v127, vcc
	v_rsq_f32_e32 v127, v120
	v_or3_b32 v120, v121, v126, s10
	v_mad_i64_i32 v[124:125], s[10:11], v122, s41, v[124:125]
	v_mul_f32_e32 v121, 0x45800000, v127
	v_cndmask_b32_e32 v129, v127, v121, vcc
	v_mul_f32_e32 v132, v148, v129
	v_mul_f32_e32 v131, v149, v129
	v_mul_f32_e32 v130, v150, v129
	v_mul_f32_e32 v128, v151, v129
	v_cmp_lt_i32_e64 s[10:11], s43, v120
	s_and_saveexec_b64 s[12:13], s[10:11]
	s_xor_b64 s[12:13], exec, s[12:13]
	s_cbranch_execz .LBB0_774
	v_cmp_gt_u32_e32 vcc, s44, v120
	s_and_saveexec_b64 s[14:15], vcc
	s_cbranch_execz .LBB0_773
	v_mul_f32_e32 v121, 0xbfb8aa3b, v132
	v_exp_f32_e32 v121, v121
	v_mul_f32_e32 v126, 0xbfb8aa3b, v131
	v_mul_f32_e32 v127, 0xbfb8aa3b, v128
	v_exp_f32_e32 v126, v126
	v_add_f32_e32 v121, 1.0, v121
	v_rcp_f32_e32 v132, v121
	v_mul_f32_e32 v121, 0xbfb8aa3b, v130
	v_exp_f32_e32 v121, v121
	v_exp_f32_e32 v127, v127
	v_add_f32_e32 v126, 1.0, v126
	v_rcp_f32_e32 v133, v126
	v_add_f32_e32 v121, 1.0, v121
	v_rcp_f32_e32 v134, v121
	v_add_f32_e32 v121, 1.0, v127
	v_rcp_f32_e32 v135, v121
	v_mov_b32_e32 v121, v153
	v_lshl_add_u64 v[126:127], v[120:121], 2, v[124:125]
	v_add_co_u32_e32 v126, vcc, 0x2ffe000, v126
	s_nop 1
	v_addc_co_u32_e32 v127, vcc, 0, v127, vcc
	global_store_dwordx4 v[126:127], v[132:135], off

.LBB0_1737:
	ds_read_b128 v[196:199], v171 offset:32768
	ds_read_b128 v[200:203], v171 offset:33792
	ds_read_b128 v[204:207], v171 offset:34816
	ds_read_b128 v[208:211], v171 offset:35840
	ds_read_b128 v[212:215], v169
	ds_read_b128 v[216:219], v169 offset:1024
	ds_read_b128 v[222:225], v169 offset:2048
	ds_read_b128 v[226:229], v169 offset:3072
	ds_read_b128 v[230:233], v169 offset:4096
	ds_read_b128 v[234:237], v169 offset:5120
	ds_read_b128 v[238:241], v169 offset:6144
	ds_read_b128 v[242:245], v169 offset:7168
	s_setprio 1
	s_waitcnt lgkmcnt(7)
	v_mfma_f32_16x16x32_bf16 v[148:151], v[196:199], v[212:215], v[148:151]
	v_mfma_f32_16x16x32_bf16 v[144:147], v[200:203], v[212:215], v[144:147]
	v_mfma_f32_16x16x32_bf16 v[116:119], v[204:207], v[212:215], v[116:119]
	v_mfma_f32_16x16x32_bf16 v[112:115], v[208:211], v[212:215], v[112:115]
	global_load_dwordx4 v[172:175], v[172:173], off
	global_load_dwordx4 v[176:179], v[176:177], off
	global_load_dwordx4 v[180:183], v[180:181], off
	global_load_dwordx4 v[184:187], v[184:185], off
	global_load_dwordx4 v[188:191], v[188:189], off
	global_load_dwordx4 v[192:195], v[192:193], off
	s_waitcnt vmcnt(11)
	ds_write_b128 v152, v[120:123] offset:16384
	s_waitcnt lgkmcnt(7)
	v_mfma_f32_16x16x32_bf16 v[108:111], v[196:199], v[216:219], v[108:111]
	v_mfma_f32_16x16x32_bf16 v[104:107], v[200:203], v[216:219], v[104:107]
	v_mfma_f32_16x16x32_bf16 v[100:103], v[204:207], v[216:219], v[100:103]
	v_mfma_f32_16x16x32_bf16 v[96:99], v[208:211], v[216:219], v[96:99]
	s_waitcnt vmcnt(9)
	ds_write_b128 v152, v[124:127] offset:20480
	s_waitcnt lgkmcnt(7)
	v_mfma_f32_16x16x32_bf16 v[92:95], v[196:199], v[222:225], v[92:95]
	v_mfma_f32_16x16x32_bf16 v[88:91], v[200:203], v[222:225], v[88:91]
	v_mfma_f32_16x16x32_bf16 v[84:87], v[204:207], v[222:225], v[84:87]
	v_mfma_f32_16x16x32_bf16 v[80:83], v[208:211], v[222:225], v[80:83]
	s_waitcnt vmcnt(8)
	ds_write_b128 v152, v[128:131] offset:24576
	s_waitcnt lgkmcnt(7)
	v_mfma_f32_16x16x32_bf16 v[76:79], v[196:199], v[226:229], v[76:79]
	v_mfma_f32_16x16x32_bf16 v[72:75], v[200:203], v[226:229], v[72:75]
	v_mfma_f32_16x16x32_bf16 v[68:71], v[204:207], v[226:229], v[68:71]
	v_mfma_f32_16x16x32_bf16 v[64:67], v[208:211], v[226:229], v[64:67]
	s_waitcnt vmcnt(7)
	ds_write_b128 v152, v[136:139] offset:28672
	s_waitcnt lgkmcnt(7)
	v_mfma_f32_16x16x32_bf16 v[60:63], v[196:199], v[230:233], v[60:63]
	v_mfma_f32_16x16x32_bf16 v[56:59], v[200:203], v[230:233], v[56:59]
	v_mfma_f32_16x16x32_bf16 v[52:55], v[204:207], v[230:233], v[52:55]
	v_mfma_f32_16x16x32_bf16 v[48:51], v[208:211], v[230:233], v[48:51]
	s_waitcnt vmcnt(6)
	ds_write_b128 v152, v[140:143] offset:45056
	s_waitcnt lgkmcnt(7)
	v_mfma_f32_16x16x32_bf16 v[44:47], v[196:199], v[234:237], v[44:47]
	v_mfma_f32_16x16x32_bf16 v[40:43], v[200:203], v[234:237], v[40:43]
	v_mfma_f32_16x16x32_bf16 v[36:39], v[204:207], v[234:237], v[36:39]
	v_mfma_f32_16x16x32_bf16 v[32:35], v[208:211], v[234:237], v[32:35]
	ds_write_b128 v152, v[132:135] offset:40960
	s_waitcnt lgkmcnt(7)
	v_mfma_f32_16x16x32_bf16 v[28:31], v[196:199], v[238:241], v[28:31]
	v_mfma_f32_16x16x32_bf16 v[24:27], v[200:203], v[238:241], v[24:27]
	v_mfma_f32_16x16x32_bf16 v[20:23], v[204:207], v[238:241], v[20:23]
	v_mfma_f32_16x16x32_bf16 v[16:19], v[208:211], v[238:241], v[16:19]
	s_waitcnt lgkmcnt(6)
	v_mfma_f32_16x16x32_bf16 v[12:15], v[196:199], v[242:245], v[12:15]
	v_mfma_f32_16x16x32_bf16 v[8:11], v[200:203], v[242:245], v[8:11]
	v_mfma_f32_16x16x32_bf16 v[4:7], v[204:207], v[242:245], v[4:7]
	v_mfma_f32_16x16x32_bf16 v[0:3], v[208:211], v[242:245], v[0:3]
	s_setprio 0
	s_min_u32 s12, s25, 0x380
	s_lshl_b32 s12, s12, 1
	s_mov_b32 s29, s13
	s_add_i32 s28, s12, 0xc0
	v_lshl_add_u64 v[120:121], v[154:155], 0, s[12:13]
	v_lshl_add_u64 v[124:125], v[156:157], 0, s[12:13]
	v_lshl_add_u64 v[126:127], v[158:159], 0, s[28:29]
	v_lshl_add_u64 v[128:129], v[160:161], 0, s[28:29]
	v_lshl_add_u64 v[136:137], v[162:163], 0, s[28:29]
	v_lshl_add_u64 v[140:141], v[164:165], 0, s[28:29]
	s_waitcnt lgkmcnt(0)
	s_barrier
	ds_read_b128 v[196:199], v168 offset:40960
	ds_read_b128 v[200:203], v168 offset:41984
	ds_read_b128 v[204:207], v168 offset:43008
	ds_read_b128 v[208:211], v168 offset:44032
	ds_read_b128 v[212:215], v170
	ds_read_b128 v[216:219], v170 offset:1024
	ds_read_b128 v[222:225], v170 offset:2048
	ds_read_b128 v[226:229], v170 offset:3072
	ds_read_b128 v[230:233], v170 offset:4096
	ds_read_b128 v[234:237], v170 offset:5120
	ds_read_b128 v[238:241], v170 offset:6144
	ds_read_b128 v[242:245], v170 offset:7168
	s_setprio 1
	s_waitcnt lgkmcnt(7)
	v_mfma_f32_16x16x32_bf16 v[148:151], v[196:199], v[212:215], v[148:151]
	v_mfma_f32_16x16x32_bf16 v[144:147], v[200:203], v[212:215], v[144:147]
	v_mfma_f32_16x16x32_bf16 v[116:119], v[204:207], v[212:215], v[116:119]
	v_mfma_f32_16x16x32_bf16 v[112:115], v[208:211], v[212:215], v[112:115]
	global_load_dwordx4 v[120:123], v[120:121], off offset:192
	global_load_dwordx4 v[132:135], v[124:125], off offset:192
	global_load_dwordx4 v[124:127], v[126:127], off
	global_load_dwordx4 v[128:131], v[128:129], off
	global_load_dwordx4 v[136:139], v[136:137], off
	global_load_dwordx4 v[140:143], v[140:141], off
	s_waitcnt vmcnt(11)
	ds_write_b128 v152, v[172:175]
	s_waitcnt lgkmcnt(7)
	v_mfma_f32_16x16x32_bf16 v[108:111], v[196:199], v[216:219], v[108:111]
	v_mfma_f32_16x16x32_bf16 v[104:107], v[200:203], v[216:219], v[104:107]
	v_mfma_f32_16x16x32_bf16 v[100:103], v[204:207], v[216:219], v[100:103]
	v_mfma_f32_16x16x32_bf16 v[96:99], v[208:211], v[216:219], v[96:99]
	s_waitcnt vmcnt(10)
	ds_write_b128 v152, v[176:179] offset:4096
	s_waitcnt lgkmcnt(7)
	v_mfma_f32_16x16x32_bf16 v[92:95], v[196:199], v[222:225], v[92:95]
	v_mfma_f32_16x16x32_bf16 v[88:91], v[200:203], v[222:225], v[88:91]
	v_mfma_f32_16x16x32_bf16 v[84:87], v[204:207], v[222:225], v[84:87]
	v_mfma_f32_16x16x32_bf16 v[80:83], v[208:211], v[222:225], v[80:83]
	s_waitcnt vmcnt(9)
	ds_write_b128 v152, v[180:183] offset:8192
	s_waitcnt lgkmcnt(7)
	v_mfma_f32_16x16x32_bf16 v[76:79], v[196:199], v[226:229], v[76:79]
	v_mfma_f32_16x16x32_bf16 v[72:75], v[200:203], v[226:229], v[72:75]
	v_mfma_f32_16x16x32_bf16 v[68:71], v[204:207], v[226:229], v[68:71]
	v_mfma_f32_16x16x32_bf16 v[64:67], v[208:211], v[226:229], v[64:67]
	s_waitcnt vmcnt(8)
	ds_write_b128 v152, v[184:187] offset:12288
	s_waitcnt lgkmcnt(7)
	v_mfma_f32_16x16x32_bf16 v[60:63], v[196:199], v[230:233], v[60:63]
	v_mfma_f32_16x16x32_bf16 v[56:59], v[200:203], v[230:233], v[56:59]
	v_mfma_f32_16x16x32_bf16 v[52:55], v[204:207], v[230:233], v[52:55]
	v_mfma_f32_16x16x32_bf16 v[48:51], v[208:211], v[230:233], v[48:51]
	s_waitcnt vmcnt(7)
	ds_write_b128 v152, v[188:191] offset:32768
	s_waitcnt lgkmcnt(7)
	v_mfma_f32_16x16x32_bf16 v[44:47], v[196:199], v[234:237], v[44:47]
	v_mfma_f32_16x16x32_bf16 v[40:43], v[200:203], v[234:237], v[40:43]
	v_mfma_f32_16x16x32_bf16 v[36:39], v[204:207], v[234:237], v[36:39]
	v_mfma_f32_16x16x32_bf16 v[32:35], v[208:211], v[234:237], v[32:35]
	s_waitcnt vmcnt(6)
	ds_write_b128 v152, v[192:195] offset:36864
	s_waitcnt lgkmcnt(7)
	v_mfma_f32_16x16x32_bf16 v[28:31], v[196:199], v[238:241], v[28:31]
	v_mfma_f32_16x16x32_bf16 v[24:27], v[200:203], v[238:241], v[24:27]
	v_mfma_f32_16x16x32_bf16 v[20:23], v[204:207], v[238:241], v[20:23]
	v_mfma_f32_16x16x32_bf16 v[16:19], v[208:211], v[238:241], v[16:19]
	s_waitcnt lgkmcnt(6)
	v_mfma_f32_16x16x32_bf16 v[12:15], v[196:199], v[242:245], v[12:15]
	v_mfma_f32_16x16x32_bf16 v[8:11], v[200:203], v[242:245], v[8:11]
	v_mfma_f32_16x16x32_bf16 v[4:7], v[204:207], v[242:245], v[4:7]
	v_mfma_f32_16x16x32_bf16 v[0:3], v[208:211], v[242:245], v[0:3]
	s_setprio 0
	s_add_i32 s21, s21, 2
	s_mov_b32 s25, s26
	s_add_i32 s26, s25, 64
	s_min_u32 s12, s26, 0x3e0
	s_lshl_b32 s12, s12, 1
	v_lshl_add_u64 v[172:173], v[154:155], 0, s[12:13]
	v_lshl_add_u64 v[176:177], v[158:159], 0, s[12:13]
	v_lshl_add_u64 v[180:181], v[160:161], 0, s[12:13]
	v_lshl_add_u64 v[184:185], v[162:163], 0, s[12:13]
	v_lshl_add_u64 v[188:189], v[156:157], 0, s[12:13]
	v_lshl_add_u64 v[192:193], v[164:165], 0, s[12:13]
	s_cmp_lt_u32 s21, 30
	s_waitcnt lgkmcnt(0)
	s_cbranch_scc1 .Lrot_0
	s_barrier
	s_waitcnt vmcnt(5)
	v_mov_b32_e32 v120, v220
	s_nop 0
	v_and_b32_e32 v122, 0xffffff80, v120
	v_add_u32_e32 v122, s20, v122
	v_and_b32_e32 v121, 64, v120
	v_and_or_b32 v122, v120, 15, v122
	v_lshrrev_b32_e32 v120, 2, v120
	v_and_b32_e32 v120, 12, v120
	v_or3_b32 v120, v121, v120, s24
	v_ashrrev_i32_e32 v121, 31, v120
	v_ashrrev_i32_e32 v123, 31, v122
	v_lshl_add_u64 v[120:121], v[120:121], 1, s[10:11]
	s_waitcnt vmcnt(3)
	v_lshl_add_u64 v[124:125], v[122:123], 2, s[0:1]
	v_lshlrev_b64 v[126:127], 12, v[122:123]
	v_lshl_add_u64 v[162:163], v[120:121], 0, v[126:127]
	global_load_dword v152, v[124:125], off
	global_load_dwordx2 v[168:169], v[162:163], off
	global_load_dwordx2 v[170:171], v[162:163], off offset:32
	global_load_dwordx2 v[172:173], v[162:163], off offset:64
	v_or_b32_e32 v124, 16, v122
	v_ashrrev_i32_e32 v125, 31, v124
	v_lshl_add_u64 v[126:127], v[124:125], 2, s[0:1]
	v_lshlrev_b64 v[124:125], 12, v[124:125]
	s_waitcnt vmcnt(4)
	v_lshl_add_u64 v[142:143], v[120:121], 0, v[124:125]
	v_or_b32_e32 v124, 32, v122
	v_ashrrev_i32_e32 v125, 31, v124
	global_load_dwordx2 v[174:175], v[162:163], off offset:96
	global_load_dword v176, v[126:127], off
	global_load_dwordx2 v[164:165], v[142:143], off
	global_load_dwordx2 v[160:161], v[142:143], off offset:32
	v_lshl_add_u64 v[126:127], v[124:125], 2, s[0:1]
	v_lshlrev_b64 v[124:125], 12, v[124:125]
	v_lshl_add_u64 v[132:133], v[120:121], 0, v[124:125]
	v_or_b32_e32 v124, 48, v122
	v_ashrrev_i32_e32 v125, 31, v124
	global_load_dwordx2 v[158:159], v[142:143], off offset:64
	global_load_dwordx2 v[156:157], v[142:143], off offset:96
	global_load_dword v177, v[126:127], off
	global_load_dwordx2 v[154:155], v[132:133], off
	v_lshl_add_u64 v[126:127], v[124:125], 2, s[0:1]
	v_lshlrev_b64 v[124:125], 12, v[124:125]
	v_lshl_add_u64 v[124:125], v[120:121], 0, v[124:125]
	global_load_dwordx2 v[140:141], v[132:133], off offset:32
	global_load_dwordx2 v[138:139], v[132:133], off offset:64
	global_load_dwordx2 v[136:137], v[132:133], off offset:96
	global_load_dword v123, v[126:127], off
	global_load_dwordx2 v[134:135], v[124:125], off
	global_load_dwordx2 v[130:131], v[124:125], off offset:32
	global_load_dwordx2 v[128:129], v[124:125], off offset:64
	s_nop 0
	global_load_dwordx2 v[126:127], v[124:125], off offset:96
	s_waitcnt vmcnt(19)
	v_fmamk_f32 v152, v152, 0x3a800000, v167
	v_mul_f32_e32 v178, 0x4b800000, v152
	v_cmp_gt_f32_e32 vcc, s22, v152
	s_nop 1
	v_cndmask_b32_e32 v152, v152, v178, vcc
	v_rsq_f32_e32 v152, v152
	s_waitcnt vmcnt(18)
	v_lshlrev_b32_e32 v178, 16, v168
	v_and_b32_e32 v168, 0xffff0000, v168
	v_mul_f32_e32 v179, 0x45800000, v152
	v_cndmask_b32_e32 v152, v152, v179, vcc
	v_mul_f32_e32 v148, v148, v152
	v_mul_f32_e32 v180, 0xbfb8aa3b, v148
	v_exp_f32_e32 v180, v180
	v_mul_f32_e32 v149, v149, v152
	v_mul_f32_e32 v181, 0xbfb8aa3b, v149
	v_exp_f32_e32 v181, v181
	v_add_f32_e32 v180, 1.0, v180
	v_rcp_f32_e32 v180, v180
	v_mul_f32_e32 v150, v150, v152
	v_mul_f32_e32 v151, v151, v152
	v_lshlrev_b32_e32 v179, 16, v169
	v_mul_f32_e32 v148, v148, v180
	v_mul_f32_e32 v148, v148, v178
	v_add_f32_e32 v178, 1.0, v181
	v_mul_f32_e32 v180, 0xbfb8aa3b, v150
	v_mul_f32_e32 v181, 0xbfb8aa3b, v151
	v_rcp_f32_e32 v178, v178
	v_exp_f32_e32 v180, v180
	v_exp_f32_e32 v181, v181
	v_and_b32_e32 v169, 0xffff0000, v169
	v_mul_f32_e32 v149, v149, v178
	v_add_f32_e32 v178, 1.0, v180
	v_add_f32_e32 v180, 1.0, v181
	v_rcp_f32_e32 v180, v180
	v_rcp_f32_e32 v178, v178
	v_mul_f32_e32 v149, v149, v168
	v_mul_f32_e32 v144, v144, v152
	v_mul_f32_e32 v151, v151, v180
	v_mul_f32_e32 v150, v150, v178
	v_mul_f32_e32 v151, v151, v169
	v_mul_f32_e32 v150, v150, v179
	v_cvt_pk_bf16_f32 v148, v148, v149
	v_cvt_pk_bf16_f32 v149, v150, v151
	v_mul_f32_e32 v151, 0xbfb8aa3b, v144
	v_exp_f32_e32 v151, v151
	v_mul_f32_e32 v145, v145, v152
	v_mul_f32_e32 v169, 0xbfb8aa3b, v145
	v_exp_f32_e32 v169, v169
	v_add_f32_e32 v151, 1.0, v151
	v_rcp_f32_e32 v151, v151
	global_store_dwordx2 v[162:163], v[148:149], off
	s_waitcnt vmcnt(18)
	v_lshlrev_b32_e32 v148, 16, v170
	v_mul_f32_e32 v146, v146, v152
	v_mul_f32_e32 v147, v147, v152
	v_mul_f32_e32 v144, v144, v151
	v_mul_f32_e32 v144, v144, v148
	v_add_f32_e32 v148, 1.0, v169
	v_mul_f32_e32 v151, 0xbfb8aa3b, v146
	v_mul_f32_e32 v169, 0xbfb8aa3b, v147
	v_rcp_f32_e32 v148, v148
	v_exp_f32_e32 v151, v151
	v_exp_f32_e32 v169, v169
	v_and_b32_e32 v149, 0xffff0000, v170
	v_mul_f32_e32 v145, v145, v148
	v_add_f32_e32 v148, 1.0, v151
	v_add_f32_e32 v151, 1.0, v169
	v_rcp_f32_e32 v151, v151
	v_rcp_f32_e32 v148, v148
	v_and_b32_e32 v168, 0xffff0000, v171
	v_lshlrev_b32_e32 v150, 16, v171
	v_mul_f32_e32 v147, v147, v151
	v_mul_f32_e32 v145, v145, v149
	v_mul_f32_e32 v146, v146, v148
	v_mul_f32_e32 v147, v147, v168
	v_mul_f32_e32 v116, v116, v152
	v_mul_f32_e32 v146, v146, v150
	v_cvt_pk_bf16_f32 v144, v144, v145
	v_cvt_pk_bf16_f32 v145, v146, v147
	v_mul_f32_e32 v147, 0xbfb8aa3b, v116
	v_exp_f32_e32 v147, v147
	v_mul_f32_e32 v117, v117, v152
	v_mul_f32_e32 v149, 0xbfb8aa3b, v117
	v_exp_f32_e32 v149, v149
	v_add_f32_e32 v147, 1.0, v147
	v_rcp_f32_e32 v147, v147
	global_store_dwordx2 v[162:163], v[144:145], off offset:32
	s_waitcnt vmcnt(18)
	v_lshlrev_b32_e32 v144, 16, v172
	v_mul_f32_e32 v118, v118, v152
	v_mul_f32_e32 v119, v119, v152
	v_mul_f32_e32 v116, v116, v147
	v_mul_f32_e32 v116, v116, v144
	v_add_f32_e32 v144, 1.0, v149
	v_mul_f32_e32 v147, 0xbfb8aa3b, v118
	v_mul_f32_e32 v149, 0xbfb8aa3b, v119
	v_rcp_f32_e32 v144, v144
	v_exp_f32_e32 v147, v147
	v_exp_f32_e32 v149, v149
	v_and_b32_e32 v145, 0xffff0000, v172
	v_mul_f32_e32 v117, v117, v144
	v_add_f32_e32 v144, 1.0, v147
	v_add_f32_e32 v147, 1.0, v149
	v_rcp_f32_e32 v147, v147
	v_rcp_f32_e32 v144, v144
	v_and_b32_e32 v148, 0xffff0000, v173
	v_lshlrev_b32_e32 v146, 16, v173
	v_mul_f32_e32 v119, v119, v147
	v_mul_f32_e32 v117, v117, v145
	v_mul_f32_e32 v118, v118, v144
	v_mul_f32_e32 v119, v119, v148
	v_mul_f32_e32 v112, v112, v152
	v_mul_f32_e32 v118, v118, v146
	v_cvt_pk_bf16_f32 v116, v116, v117
	v_cvt_pk_bf16_f32 v117, v118, v119
	v_mul_f32_e32 v119, 0xbfb8aa3b, v112
	v_exp_f32_e32 v119, v119
	v_mul_f32_e32 v113, v113, v152
	v_mul_f32_e32 v145, 0xbfb8aa3b, v113
	v_exp_f32_e32 v145, v145
	v_add_f32_e32 v119, 1.0, v119
	v_rcp_f32_e32 v119, v119
	global_store_dwordx2 v[162:163], v[116:117], off offset:64
	s_waitcnt vmcnt(18)
	v_lshlrev_b32_e32 v116, 16, v174
	v_mul_f32_e32 v114, v114, v152
	v_mul_f32_e32 v112, v112, v119
	v_mul_f32_e32 v112, v112, v116
	v_add_f32_e32 v116, 1.0, v145
	v_mul_f32_e32 v119, 0xbfb8aa3b, v114
	v_rcp_f32_e32 v116, v116
	v_exp_f32_e32 v119, v119
	v_mul_f32_e32 v115, v115, v152
	v_mul_f32_e32 v145, 0xbfb8aa3b, v115
	v_mul_f32_e32 v113, v113, v116
	v_add_f32_e32 v116, 1.0, v119
	v_rcp_f32_e32 v116, v116
	v_exp_f32_e32 v145, v145
	v_and_b32_e32 v117, 0xffff0000, v174
	v_mul_f32_e32 v113, v113, v117
	v_mul_f32_e32 v114, v114, v116
	s_waitcnt vmcnt(17)
	v_fmamk_f32 v116, v176, 0x3a800000, v167
	v_add_f32_e32 v119, 1.0, v145
	v_mul_f32_e32 v117, 0x4b800000, v116
	v_cmp_gt_f32_e32 vcc, s22, v116
	v_rcp_f32_e32 v119, v119
	v_lshlrev_b32_e32 v118, 16, v175
	v_cndmask_b32_e32 v116, v116, v117, vcc
	v_rsq_f32_e32 v116, v116
	v_and_b32_e32 v144, 0xffff0000, v175
	v_mul_f32_e32 v115, v115, v119
	v_cvt_pk_bf16_f32 v112, v112, v113
	v_mul_f32_e32 v114, v114, v118
	v_mul_f32_e32 v115, v115, v144
	v_cvt_pk_bf16_f32 v113, v114, v115
	global_store_dwordx2 v[162:163], v[112:113], off offset:96
	v_mul_f32_e32 v112, 0x45800000, v116
	v_cndmask_b32_e32 v112, v116, v112, vcc
	v_mul_f32_e32 v108, v108, v112
	v_mul_f32_e32 v116, 0xbfb8aa3b, v108
	v_exp_f32_e32 v116, v116
	v_mul_f32_e32 v109, v109, v112
	v_mul_f32_e32 v118, 0xbfb8aa3b, v109
	v_exp_f32_e32 v118, v118
	v_add_f32_e32 v116, 1.0, v116
	v_rcp_f32_e32 v116, v116
	s_waitcnt vmcnt(17)
	v_lshlrev_b32_e32 v113, 16, v164
	v_mul_f32_e32 v110, v110, v112
	v_mul_f32_e32 v111, v111, v112
	v_mul_f32_e32 v108, v108, v116
	v_mul_f32_e32 v108, v108, v113
	v_add_f32_e32 v113, 1.0, v118
	v_mul_f32_e32 v116, 0xbfb8aa3b, v110
	v_mul_f32_e32 v118, 0xbfb8aa3b, v111
	v_rcp_f32_e32 v113, v113
	v_exp_f32_e32 v116, v116
	v_exp_f32_e32 v118, v118
	v_and_b32_e32 v114, 0xffff0000, v164
	v_mul_f32_e32 v109, v109, v113
	v_add_f32_e32 v113, 1.0, v116
	v_add_f32_e32 v116, 1.0, v118
	v_rcp_f32_e32 v116, v116
	v_rcp_f32_e32 v113, v113
	v_and_b32_e32 v117, 0xffff0000, v165
	v_lshlrev_b32_e32 v115, 16, v165
	v_mul_f32_e32 v111, v111, v116
	v_mul_f32_e32 v109, v109, v114
	v_mul_f32_e32 v110, v110, v113
	v_mul_f32_e32 v111, v111, v117
	v_mul_f32_e32 v104, v104, v112
	v_mul_f32_e32 v110, v110, v115
	v_cvt_pk_bf16_f32 v108, v108, v109
	v_cvt_pk_bf16_f32 v109, v110, v111
	v_mul_f32_e32 v111, 0xbfb8aa3b, v104
	v_exp_f32_e32 v111, v111
	v_mul_f32_e32 v105, v105, v112
	v_mul_f32_e32 v114, 0xbfb8aa3b, v105
	v_exp_f32_e32 v114, v114
	v_add_f32_e32 v111, 1.0, v111
	v_rcp_f32_e32 v111, v111
	global_store_dwordx2 v[142:143], v[108:109], off
	s_waitcnt vmcnt(17)
	v_lshlrev_b32_e32 v108, 16, v160
	v_mul_f32_e32 v106, v106, v112
	v_mul_f32_e32 v107, v107, v112
	v_mul_f32_e32 v104, v104, v111
	v_mul_f32_e32 v104, v104, v108
	v_add_f32_e32 v108, 1.0, v114
	v_mul_f32_e32 v111, 0xbfb8aa3b, v106
	v_mul_f32_e32 v114, 0xbfb8aa3b, v107
	v_rcp_f32_e32 v108, v108
	v_exp_f32_e32 v111, v111
	v_exp_f32_e32 v114, v114
	v_and_b32_e32 v109, 0xffff0000, v160
	v_mul_f32_e32 v105, v105, v108
	v_add_f32_e32 v108, 1.0, v111
	v_add_f32_e32 v111, 1.0, v114
	v_rcp_f32_e32 v111, v111
	v_rcp_f32_e32 v108, v108
	v_and_b32_e32 v113, 0xffff0000, v161
	v_lshlrev_b32_e32 v110, 16, v161
	v_mul_f32_e32 v107, v107, v111
	v_mul_f32_e32 v105, v105, v109
	v_mul_f32_e32 v106, v106, v108
	v_mul_f32_e32 v107, v107, v113
	v_mul_f32_e32 v100, v100, v112
	v_mul_f32_e32 v106, v106, v110
	v_cvt_pk_bf16_f32 v104, v104, v105
	v_cvt_pk_bf16_f32 v105, v106, v107
	v_mul_f32_e32 v107, 0xbfb8aa3b, v100
	v_exp_f32_e32 v107, v107
	v_mul_f32_e32 v101, v101, v112
	v_mul_f32_e32 v109, 0xbfb8aa3b, v101
	v_exp_f32_e32 v109, v109
	v_add_f32_e32 v107, 1.0, v107
	v_rcp_f32_e32 v107, v107
	global_store_dwordx2 v[142:143], v[104:105], off offset:32
	s_waitcnt vmcnt(17)
	v_lshlrev_b32_e32 v104, 16, v158
	v_mul_f32_e32 v102, v102, v112
	v_mul_f32_e32 v103, v103, v112
	v_mul_f32_e32 v100, v100, v107
	v_mul_f32_e32 v100, v100, v104
	v_add_f32_e32 v104, 1.0, v109
	v_mul_f32_e32 v107, 0xbfb8aa3b, v102
	v_mul_f32_e32 v109, 0xbfb8aa3b, v103
	v_rcp_f32_e32 v104, v104
	v_exp_f32_e32 v107, v107
	v_exp_f32_e32 v109, v109
	v_and_b32_e32 v105, 0xffff0000, v158
	v_mul_f32_e32 v101, v101, v104
	v_add_f32_e32 v104, 1.0, v107
	v_add_f32_e32 v107, 1.0, v109
	v_rcp_f32_e32 v107, v107
	v_rcp_f32_e32 v104, v104
	v_and_b32_e32 v108, 0xffff0000, v159
	v_lshlrev_b32_e32 v106, 16, v159
	v_mul_f32_e32 v103, v103, v107
	v_mul_f32_e32 v101, v101, v105
	v_mul_f32_e32 v102, v102, v104
	v_mul_f32_e32 v103, v103, v108
	v_mul_f32_e32 v96, v96, v112
	v_mul_f32_e32 v102, v102, v106
	v_cvt_pk_bf16_f32 v100, v100, v101
	v_cvt_pk_bf16_f32 v101, v102, v103
	v_mul_f32_e32 v103, 0xbfb8aa3b, v96
	v_exp_f32_e32 v103, v103
	v_mul_f32_e32 v97, v97, v112
	v_mul_f32_e32 v105, 0xbfb8aa3b, v97
	v_exp_f32_e32 v105, v105
	v_add_f32_e32 v103, 1.0, v103
	v_rcp_f32_e32 v103, v103
	global_store_dwordx2 v[142:143], v[100:101], off offset:64
	s_waitcnt vmcnt(17)
	v_lshlrev_b32_e32 v100, 16, v156
	v_mul_f32_e32 v98, v98, v112
	v_mul_f32_e32 v96, v96, v103
	v_mul_f32_e32 v96, v96, v100
	v_add_f32_e32 v100, 1.0, v105
	v_mul_f32_e32 v103, 0xbfb8aa3b, v98
	v_rcp_f32_e32 v100, v100
	v_exp_f32_e32 v103, v103
	v_mul_f32_e32 v99, v99, v112
	v_mul_f32_e32 v105, 0xbfb8aa3b, v99
	v_mul_f32_e32 v97, v97, v100
	v_add_f32_e32 v100, 1.0, v103
	v_rcp_f32_e32 v100, v100
	v_exp_f32_e32 v105, v105
	v_and_b32_e32 v101, 0xffff0000, v156
	v_mul_f32_e32 v97, v97, v101
	v_mul_f32_e32 v98, v98, v100
	s_waitcnt vmcnt(16)
	v_fmamk_f32 v100, v177, 0x3a800000, v167
	v_add_f32_e32 v103, 1.0, v105
	v_mul_f32_e32 v101, 0x4b800000, v100
	v_cmp_gt_f32_e32 vcc, s22, v100
	v_rcp_f32_e32 v103, v103
	v_lshlrev_b32_e32 v102, 16, v157
	v_cndmask_b32_e32 v100, v100, v101, vcc
	v_rsq_f32_e32 v100, v100
	v_and_b32_e32 v104, 0xffff0000, v157
	v_mul_f32_e32 v99, v99, v103
	v_cvt_pk_bf16_f32 v96, v96, v97
	v_mul_f32_e32 v98, v98, v102
	v_mul_f32_e32 v99, v99, v104
	v_cvt_pk_bf16_f32 v97, v98, v99
	global_store_dwordx2 v[142:143], v[96:97], off offset:96
	v_mul_f32_e32 v96, 0x45800000, v100
	v_cndmask_b32_e32 v96, v100, v96, vcc
	v_mul_f32_e32 v92, v92, v96
	v_mul_f32_e32 v100, 0xbfb8aa3b, v92
	v_exp_f32_e32 v100, v100
	v_mul_f32_e32 v93, v93, v96
	v_mul_f32_e32 v102, 0xbfb8aa3b, v93
	v_exp_f32_e32 v102, v102
	v_add_f32_e32 v100, 1.0, v100
	v_rcp_f32_e32 v100, v100
	s_waitcnt vmcnt(16)
	v_lshlrev_b32_e32 v97, 16, v154
	v_mul_f32_e32 v94, v94, v96
	v_mul_f32_e32 v95, v95, v96
	v_mul_f32_e32 v92, v92, v100
	v_mul_f32_e32 v92, v92, v97
	v_add_f32_e32 v97, 1.0, v102
	v_mul_f32_e32 v100, 0xbfb8aa3b, v94
	v_mul_f32_e32 v102, 0xbfb8aa3b, v95
	v_rcp_f32_e32 v97, v97
	v_exp_f32_e32 v100, v100
	v_exp_f32_e32 v102, v102
	v_and_b32_e32 v98, 0xffff0000, v154
	v_mul_f32_e32 v93, v93, v97
	v_add_f32_e32 v97, 1.0, v100
	v_add_f32_e32 v100, 1.0, v102
	v_rcp_f32_e32 v100, v100
	v_rcp_f32_e32 v97, v97
	v_and_b32_e32 v101, 0xffff0000, v155
	v_lshlrev_b32_e32 v99, 16, v155
	v_mul_f32_e32 v95, v95, v100
	v_mul_f32_e32 v93, v93, v98
	v_mul_f32_e32 v94, v94, v97
	v_mul_f32_e32 v95, v95, v101
	v_mul_f32_e32 v88, v88, v96
	v_mul_f32_e32 v94, v94, v99
	v_cvt_pk_bf16_f32 v92, v92, v93
	v_cvt_pk_bf16_f32 v93, v94, v95
	v_mul_f32_e32 v95, 0xbfb8aa3b, v88
	v_exp_f32_e32 v95, v95
	v_mul_f32_e32 v89, v89, v96
	v_mul_f32_e32 v98, 0xbfb8aa3b, v89
	v_exp_f32_e32 v98, v98
	v_add_f32_e32 v95, 1.0, v95
	v_rcp_f32_e32 v95, v95
	global_store_dwordx2 v[132:133], v[92:93], off
	s_waitcnt vmcnt(16)
	v_lshlrev_b32_e32 v92, 16, v140
	v_mul_f32_e32 v90, v90, v96
	v_mul_f32_e32 v91, v91, v96
	v_mul_f32_e32 v88, v88, v95
	v_mul_f32_e32 v88, v88, v92
	v_add_f32_e32 v92, 1.0, v98
	v_mul_f32_e32 v95, 0xbfb8aa3b, v90
	v_mul_f32_e32 v98, 0xbfb8aa3b, v91
	v_rcp_f32_e32 v92, v92
	v_exp_f32_e32 v95, v95
	v_exp_f32_e32 v98, v98
	v_and_b32_e32 v93, 0xffff0000, v140
	v_mul_f32_e32 v89, v89, v92
	v_add_f32_e32 v92, 1.0, v95
	v_add_f32_e32 v95, 1.0, v98
	v_rcp_f32_e32 v95, v95
	v_rcp_f32_e32 v92, v92
	v_and_b32_e32 v97, 0xffff0000, v141
	v_lshlrev_b32_e32 v94, 16, v141
	v_mul_f32_e32 v91, v91, v95
	v_mul_f32_e32 v89, v89, v93
	v_mul_f32_e32 v90, v90, v92
	v_mul_f32_e32 v91, v91, v97
	v_mul_f32_e32 v84, v84, v96
	v_mul_f32_e32 v90, v90, v94
	v_cvt_pk_bf16_f32 v88, v88, v89
	v_cvt_pk_bf16_f32 v89, v90, v91
	v_mul_f32_e32 v91, 0xbfb8aa3b, v84
	v_exp_f32_e32 v91, v91
	v_mul_f32_e32 v85, v85, v96
	v_mul_f32_e32 v93, 0xbfb8aa3b, v85
	v_exp_f32_e32 v93, v93
	v_add_f32_e32 v91, 1.0, v91
	v_rcp_f32_e32 v91, v91
	global_store_dwordx2 v[132:133], v[88:89], off offset:32
	s_waitcnt vmcnt(16)
	v_lshlrev_b32_e32 v88, 16, v138
	v_mul_f32_e32 v86, v86, v96
	v_mul_f32_e32 v87, v87, v96
	v_mul_f32_e32 v84, v84, v91
	v_mul_f32_e32 v84, v84, v88
	v_add_f32_e32 v88, 1.0, v93
	v_mul_f32_e32 v91, 0xbfb8aa3b, v86
	v_mul_f32_e32 v93, 0xbfb8aa3b, v87
	v_rcp_f32_e32 v88, v88
	v_exp_f32_e32 v91, v91
	v_exp_f32_e32 v93, v93
	v_and_b32_e32 v89, 0xffff0000, v138
	v_mul_f32_e32 v85, v85, v88
	v_add_f32_e32 v88, 1.0, v91
	v_add_f32_e32 v91, 1.0, v93
	v_rcp_f32_e32 v91, v91
	v_rcp_f32_e32 v88, v88
	v_and_b32_e32 v92, 0xffff0000, v139
	v_lshlrev_b32_e32 v90, 16, v139
	v_mul_f32_e32 v87, v87, v91
	v_mul_f32_e32 v85, v85, v89
	v_mul_f32_e32 v86, v86, v88
	v_mul_f32_e32 v87, v87, v92
	v_mul_f32_e32 v80, v80, v96
	v_mul_f32_e32 v86, v86, v90
	v_cvt_pk_bf16_f32 v84, v84, v85
	v_cvt_pk_bf16_f32 v85, v86, v87
	v_mul_f32_e32 v87, 0xbfb8aa3b, v80
	v_exp_f32_e32 v87, v87
	v_mul_f32_e32 v81, v81, v96
	v_mul_f32_e32 v89, 0xbfb8aa3b, v81
	v_exp_f32_e32 v89, v89
	v_add_f32_e32 v87, 1.0, v87
	v_rcp_f32_e32 v87, v87
	global_store_dwordx2 v[132:133], v[84:85], off offset:64
	s_waitcnt vmcnt(16)
	v_lshlrev_b32_e32 v84, 16, v136
	v_mul_f32_e32 v82, v82, v96
	v_mul_f32_e32 v80, v80, v87
	v_mul_f32_e32 v80, v80, v84
	v_add_f32_e32 v84, 1.0, v89
	v_mul_f32_e32 v87, 0xbfb8aa3b, v82
	v_rcp_f32_e32 v84, v84
	v_exp_f32_e32 v87, v87
	v_mul_f32_e32 v83, v83, v96
	v_mul_f32_e32 v89, 0xbfb8aa3b, v83
	v_mul_f32_e32 v81, v81, v84
	v_add_f32_e32 v84, 1.0, v87
	v_rcp_f32_e32 v84, v84
	v_exp_f32_e32 v89, v89
	v_and_b32_e32 v85, 0xffff0000, v136
	v_mul_f32_e32 v81, v81, v85
	v_mul_f32_e32 v82, v82, v84
	s_waitcnt vmcnt(15)
	v_fmamk_f32 v84, v123, 0x3a800000, v167
	v_add_f32_e32 v87, 1.0, v89
	v_mul_f32_e32 v85, 0x4b800000, v84
	v_cmp_gt_f32_e32 vcc, s22, v84
	v_rcp_f32_e32 v87, v87
	v_lshlrev_b32_e32 v86, 16, v137
	v_cndmask_b32_e32 v84, v84, v85, vcc
	v_rsq_f32_e32 v84, v84
	v_and_b32_e32 v88, 0xffff0000, v137
	v_mul_f32_e32 v83, v83, v87
	v_cvt_pk_bf16_f32 v80, v80, v81
	v_mul_f32_e32 v82, v82, v86
	v_mul_f32_e32 v83, v83, v88
	v_cvt_pk_bf16_f32 v81, v82, v83
	global_store_dwordx2 v[132:133], v[80:81], off offset:96
	v_mul_f32_e32 v80, 0x45800000, v84
	v_cndmask_b32_e32 v80, v84, v80, vcc
	v_mul_f32_e32 v76, v76, v80
	v_mul_f32_e32 v84, 0xbfb8aa3b, v76
	v_exp_f32_e32 v84, v84
	v_mul_f32_e32 v77, v77, v80
	v_mul_f32_e32 v86, 0xbfb8aa3b, v77
	v_exp_f32_e32 v86, v86
	v_add_f32_e32 v84, 1.0, v84
	v_rcp_f32_e32 v84, v84
	s_waitcnt vmcnt(15)
	v_lshlrev_b32_e32 v81, 16, v134
	v_mul_f32_e32 v78, v78, v80
	v_mul_f32_e32 v79, v79, v80
	v_mul_f32_e32 v76, v76, v84
	v_mul_f32_e32 v76, v76, v81
	v_add_f32_e32 v81, 1.0, v86
	v_mul_f32_e32 v84, 0xbfb8aa3b, v78
	v_mul_f32_e32 v86, 0xbfb8aa3b, v79
	v_rcp_f32_e32 v81, v81
	v_exp_f32_e32 v84, v84
	v_exp_f32_e32 v86, v86
	v_and_b32_e32 v82, 0xffff0000, v134
	v_mul_f32_e32 v77, v77, v81
	v_add_f32_e32 v81, 1.0, v84
	v_add_f32_e32 v84, 1.0, v86
	v_rcp_f32_e32 v84, v84
	v_rcp_f32_e32 v81, v81
	v_and_b32_e32 v85, 0xffff0000, v135
	v_lshlrev_b32_e32 v83, 16, v135
	v_mul_f32_e32 v79, v79, v84
	v_mul_f32_e32 v77, v77, v82
	v_mul_f32_e32 v78, v78, v81
	v_mul_f32_e32 v79, v79, v85
	v_mul_f32_e32 v72, v72, v80
	v_mul_f32_e32 v78, v78, v83
	v_cvt_pk_bf16_f32 v76, v76, v77
	v_cvt_pk_bf16_f32 v77, v78, v79
	v_mul_f32_e32 v79, 0xbfb8aa3b, v72
	v_exp_f32_e32 v79, v79
	v_mul_f32_e32 v73, v73, v80
	v_mul_f32_e32 v82, 0xbfb8aa3b, v73
	v_exp_f32_e32 v82, v82
	v_add_f32_e32 v79, 1.0, v79
	v_rcp_f32_e32 v79, v79
	global_store_dwordx2 v[124:125], v[76:77], off
	s_waitcnt vmcnt(15)
	v_lshlrev_b32_e32 v76, 16, v130
	v_mul_f32_e32 v74, v74, v80
	v_mul_f32_e32 v75, v75, v80
	v_mul_f32_e32 v72, v72, v79
	v_mul_f32_e32 v72, v72, v76
	v_add_f32_e32 v76, 1.0, v82
	v_mul_f32_e32 v79, 0xbfb8aa3b, v74
	v_mul_f32_e32 v82, 0xbfb8aa3b, v75
	v_rcp_f32_e32 v76, v76
	v_exp_f32_e32 v79, v79
	v_exp_f32_e32 v82, v82
	v_and_b32_e32 v77, 0xffff0000, v130
	v_mul_f32_e32 v73, v73, v76
	v_add_f32_e32 v76, 1.0, v79
	v_add_f32_e32 v79, 1.0, v82
	v_rcp_f32_e32 v79, v79
	v_rcp_f32_e32 v76, v76
	v_and_b32_e32 v81, 0xffff0000, v131
	v_lshlrev_b32_e32 v78, 16, v131
	v_mul_f32_e32 v75, v75, v79
	v_mul_f32_e32 v73, v73, v77
	v_mul_f32_e32 v74, v74, v76
	v_mul_f32_e32 v75, v75, v81
	v_mul_f32_e32 v68, v68, v80
	v_mul_f32_e32 v74, v74, v78
	v_cvt_pk_bf16_f32 v72, v72, v73
	v_cvt_pk_bf16_f32 v73, v74, v75
	v_mul_f32_e32 v75, 0xbfb8aa3b, v68
	v_exp_f32_e32 v75, v75
	v_mul_f32_e32 v69, v69, v80
	v_mul_f32_e32 v77, 0xbfb8aa3b, v69
	v_exp_f32_e32 v77, v77
	v_add_f32_e32 v75, 1.0, v75
	v_rcp_f32_e32 v75, v75
	global_store_dwordx2 v[124:125], v[72:73], off offset:32
	s_waitcnt vmcnt(15)
	v_lshlrev_b32_e32 v72, 16, v128
	v_mul_f32_e32 v70, v70, v80
	v_mul_f32_e32 v71, v71, v80
	v_mul_f32_e32 v68, v68, v75
	v_mul_f32_e32 v68, v68, v72
	v_add_f32_e32 v72, 1.0, v77
	v_mul_f32_e32 v75, 0xbfb8aa3b, v70
	v_mul_f32_e32 v77, 0xbfb8aa3b, v71
	v_rcp_f32_e32 v72, v72
	v_exp_f32_e32 v75, v75
	v_exp_f32_e32 v77, v77
	v_and_b32_e32 v73, 0xffff0000, v128
	v_mul_f32_e32 v69, v69, v72
	v_add_f32_e32 v72, 1.0, v75
	v_add_f32_e32 v75, 1.0, v77
	v_rcp_f32_e32 v75, v75
	v_rcp_f32_e32 v72, v72
	v_and_b32_e32 v76, 0xffff0000, v129
	v_lshlrev_b32_e32 v74, 16, v129
	v_mul_f32_e32 v71, v71, v75
	v_mul_f32_e32 v69, v69, v73
	v_mul_f32_e32 v70, v70, v72
	v_mul_f32_e32 v71, v71, v76
	v_mul_f32_e32 v64, v64, v80
	v_mul_f32_e32 v70, v70, v74
	v_cvt_pk_bf16_f32 v68, v68, v69
	v_cvt_pk_bf16_f32 v69, v70, v71
	v_mul_f32_e32 v71, 0xbfb8aa3b, v64
	v_exp_f32_e32 v71, v71
	v_mul_f32_e32 v65, v65, v80
	v_mul_f32_e32 v73, 0xbfb8aa3b, v65
	v_exp_f32_e32 v73, v73
	v_add_f32_e32 v71, 1.0, v71
	v_rcp_f32_e32 v71, v71
	global_store_dwordx2 v[124:125], v[68:69], off offset:64
	s_waitcnt vmcnt(15)
	v_lshlrev_b32_e32 v68, 16, v126
	v_mul_f32_e32 v66, v66, v80
	v_mul_f32_e32 v67, v67, v80
	v_mul_f32_e32 v64, v64, v71
	v_mul_f32_e32 v64, v64, v68
	v_add_f32_e32 v68, 1.0, v73
	v_mul_f32_e32 v71, 0xbfb8aa3b, v66
	v_mul_f32_e32 v73, 0xbfb8aa3b, v67
	v_rcp_f32_e32 v68, v68
	v_exp_f32_e32 v71, v71
	v_exp_f32_e32 v73, v73
	v_and_b32_e32 v69, 0xffff0000, v126
	v_mul_f32_e32 v65, v65, v68
	v_add_f32_e32 v68, 1.0, v71
	v_add_f32_e32 v71, 1.0, v73
	v_rcp_f32_e32 v68, v68
	v_rcp_f32_e32 v71, v71
	v_lshlrev_b32_e32 v70, 16, v127
	v_and_b32_e32 v72, 0xffff0000, v127
	v_mul_f32_e32 v65, v65, v69
	v_mul_f32_e32 v66, v66, v68
	v_mul_f32_e32 v67, v67, v71
	v_mul_f32_e32 v66, v66, v70
	v_mul_f32_e32 v67, v67, v72
	v_cvt_pk_bf16_f32 v64, v64, v65
	v_cvt_pk_bf16_f32 v65, v66, v67
	global_store_dwordx2 v[124:125], v[64:65], off offset:96
	v_or_b32_e32 v64, 64, v122
	v_ashrrev_i32_e32 v65, 31, v64
	v_lshl_add_u64 v[66:67], v[64:65], 2, s[0:1]
	v_lshlrev_b64 v[64:65], 12, v[64:65]
	v_lshl_add_u64 v[92:93], v[120:121], 0, v[64:65]
	v_or_b32_e32 v64, 0x50, v122
	v_ashrrev_i32_e32 v65, 31, v64
	global_load_dword v97, v[66:67], off
	global_load_dwordx2 v[98:99], v[92:93], off
	global_load_dwordx2 v[100:101], v[92:93], off offset:32
	global_load_dwordx2 v[102:103], v[92:93], off offset:64
	v_lshl_add_u64 v[66:67], v[64:65], 2, s[0:1]
	v_lshlrev_b64 v[64:65], 12, v[64:65]
	v_lshl_add_u64 v[82:83], v[120:121], 0, v[64:65]
	v_or_b32_e32 v64, 0x60, v122
	v_ashrrev_i32_e32 v65, 31, v64
	global_load_dwordx2 v[104:105], v[92:93], off offset:96
	global_load_dword v106, v[66:67], off
	global_load_dwordx2 v[94:95], v[82:83], off
	global_load_dwordx2 v[90:91], v[82:83], off offset:32
	v_lshl_add_u64 v[66:67], v[64:65], 2, s[0:1]
	v_lshlrev_b64 v[64:65], 12, v[64:65]
	v_lshl_add_u64 v[72:73], v[120:121], 0, v[64:65]
	v_or_b32_e32 v64, 0x70, v122
	v_ashrrev_i32_e32 v65, 31, v64
	global_load_dwordx2 v[88:89], v[82:83], off offset:64
	global_load_dwordx2 v[86:87], v[82:83], off offset:96
	global_load_dword v107, v[66:67], off
	global_load_dwordx2 v[84:85], v[72:73], off
	v_lshl_add_u64 v[66:67], v[64:65], 2, s[0:1]
	v_lshlrev_b64 v[64:65], 12, v[64:65]
	v_lshl_add_u64 v[64:65], v[120:121], 0, v[64:65]
	global_load_dwordx2 v[80:81], v[72:73], off offset:32
	global_load_dwordx2 v[78:79], v[72:73], off offset:64
	global_load_dwordx2 v[76:77], v[72:73], off offset:96
	global_load_dword v96, v[66:67], off
	global_load_dwordx2 v[74:75], v[64:65], off
	global_load_dwordx2 v[70:71], v[64:65], off offset:32
	global_load_dwordx2 v[68:69], v[64:65], off offset:64
	s_nop 0
	global_load_dwordx2 v[66:67], v[64:65], off offset:96
	s_waitcnt vmcnt(19)
	v_fmamk_f32 v97, v97, 0x3a800000, v167
	v_mul_f32_e32 v108, 0x4b800000, v97
	v_cmp_gt_f32_e32 vcc, s22, v97
	s_nop 1
	v_cndmask_b32_e32 v97, v97, v108, vcc
	v_rsq_f32_e32 v97, v97
	s_waitcnt vmcnt(18)
	v_lshlrev_b32_e32 v108, 16, v98
	v_and_b32_e32 v98, 0xffff0000, v98
	v_mul_f32_e32 v109, 0x45800000, v97
	v_cndmask_b32_e32 v97, v97, v109, vcc
	v_mul_f32_e32 v60, v60, v97
	v_mul_f32_e32 v110, 0xbfb8aa3b, v60
	v_exp_f32_e32 v110, v110
	v_mul_f32_e32 v61, v61, v97
	v_mul_f32_e32 v111, 0xbfb8aa3b, v61
	v_exp_f32_e32 v111, v111
	v_add_f32_e32 v110, 1.0, v110
	v_rcp_f32_e32 v110, v110
	v_mul_f32_e32 v62, v62, v97
	v_mul_f32_e32 v63, v63, v97
	v_lshlrev_b32_e32 v109, 16, v99
	v_mul_f32_e32 v60, v60, v110
	v_mul_f32_e32 v60, v60, v108
	v_add_f32_e32 v108, 1.0, v111
	v_mul_f32_e32 v110, 0xbfb8aa3b, v62
	v_mul_f32_e32 v111, 0xbfb8aa3b, v63
	v_rcp_f32_e32 v108, v108
	v_exp_f32_e32 v110, v110
	v_exp_f32_e32 v111, v111
	v_and_b32_e32 v99, 0xffff0000, v99
	v_mul_f32_e32 v61, v61, v108
	v_add_f32_e32 v108, 1.0, v110
	v_add_f32_e32 v110, 1.0, v111
	v_rcp_f32_e32 v110, v110
	v_rcp_f32_e32 v108, v108
	v_mul_f32_e32 v61, v61, v98
	v_mul_f32_e32 v56, v56, v97
	v_mul_f32_e32 v63, v63, v110
	v_mul_f32_e32 v62, v62, v108
	v_mul_f32_e32 v63, v63, v99
	v_mul_f32_e32 v62, v62, v109
	v_cvt_pk_bf16_f32 v60, v60, v61
	v_cvt_pk_bf16_f32 v61, v62, v63
	v_mul_f32_e32 v63, 0xbfb8aa3b, v56
	v_exp_f32_e32 v63, v63
	v_mul_f32_e32 v57, v57, v97
	v_mul_f32_e32 v99, 0xbfb8aa3b, v57
	v_exp_f32_e32 v99, v99
	v_add_f32_e32 v63, 1.0, v63
	v_rcp_f32_e32 v63, v63
	global_store_dwordx2 v[92:93], v[60:61], off
	s_waitcnt vmcnt(18)
	v_lshlrev_b32_e32 v60, 16, v100
	v_mul_f32_e32 v58, v58, v97
	v_mul_f32_e32 v59, v59, v97
	v_mul_f32_e32 v56, v56, v63
	v_mul_f32_e32 v56, v56, v60
	v_add_f32_e32 v60, 1.0, v99
	v_mul_f32_e32 v63, 0xbfb8aa3b, v58
	v_mul_f32_e32 v99, 0xbfb8aa3b, v59
	v_rcp_f32_e32 v60, v60
	v_exp_f32_e32 v63, v63
	v_exp_f32_e32 v99, v99
	v_and_b32_e32 v61, 0xffff0000, v100
	v_mul_f32_e32 v57, v57, v60
	v_add_f32_e32 v60, 1.0, v63
	v_add_f32_e32 v63, 1.0, v99
	v_rcp_f32_e32 v63, v63
	v_rcp_f32_e32 v60, v60
	v_and_b32_e32 v98, 0xffff0000, v101
	v_lshlrev_b32_e32 v62, 16, v101
	v_mul_f32_e32 v59, v59, v63
	v_mul_f32_e32 v57, v57, v61
	v_mul_f32_e32 v58, v58, v60
	v_mul_f32_e32 v59, v59, v98
	v_mul_f32_e32 v52, v52, v97
	v_mul_f32_e32 v58, v58, v62
	v_cvt_pk_bf16_f32 v56, v56, v57
	v_cvt_pk_bf16_f32 v57, v58, v59
	v_mul_f32_e32 v59, 0xbfb8aa3b, v52
	v_exp_f32_e32 v59, v59
	v_mul_f32_e32 v53, v53, v97
	v_mul_f32_e32 v61, 0xbfb8aa3b, v53
	v_exp_f32_e32 v61, v61
	v_add_f32_e32 v59, 1.0, v59
	v_rcp_f32_e32 v59, v59
	global_store_dwordx2 v[92:93], v[56:57], off offset:32
	s_waitcnt vmcnt(18)
	v_lshlrev_b32_e32 v56, 16, v102
	v_mul_f32_e32 v54, v54, v97
	v_mul_f32_e32 v55, v55, v97
	v_mul_f32_e32 v52, v52, v59
	v_mul_f32_e32 v52, v52, v56
	v_add_f32_e32 v56, 1.0, v61
	v_mul_f32_e32 v59, 0xbfb8aa3b, v54
	v_mul_f32_e32 v61, 0xbfb8aa3b, v55
	v_rcp_f32_e32 v56, v56
	v_exp_f32_e32 v59, v59
	v_exp_f32_e32 v61, v61
	v_and_b32_e32 v57, 0xffff0000, v102
	v_mul_f32_e32 v53, v53, v56
	v_add_f32_e32 v56, 1.0, v59
	v_add_f32_e32 v59, 1.0, v61
	v_rcp_f32_e32 v59, v59
	v_rcp_f32_e32 v56, v56
	v_and_b32_e32 v60, 0xffff0000, v103
	v_lshlrev_b32_e32 v58, 16, v103
	v_mul_f32_e32 v55, v55, v59
	v_mul_f32_e32 v53, v53, v57
	v_mul_f32_e32 v54, v54, v56
	v_mul_f32_e32 v55, v55, v60
	v_mul_f32_e32 v48, v48, v97
	v_mul_f32_e32 v54, v54, v58
	v_cvt_pk_bf16_f32 v52, v52, v53
	v_cvt_pk_bf16_f32 v53, v54, v55
	v_mul_f32_e32 v55, 0xbfb8aa3b, v48
	v_exp_f32_e32 v55, v55
	v_mul_f32_e32 v49, v49, v97
	v_mul_f32_e32 v57, 0xbfb8aa3b, v49
	v_exp_f32_e32 v57, v57
	v_add_f32_e32 v55, 1.0, v55
	v_rcp_f32_e32 v55, v55
	global_store_dwordx2 v[92:93], v[52:53], off offset:64
	s_waitcnt vmcnt(18)
	v_lshlrev_b32_e32 v52, 16, v104
	v_mul_f32_e32 v50, v50, v97
	v_mul_f32_e32 v48, v48, v55
	v_mul_f32_e32 v48, v48, v52
	v_add_f32_e32 v52, 1.0, v57
	v_mul_f32_e32 v55, 0xbfb8aa3b, v50
	v_rcp_f32_e32 v52, v52
	v_exp_f32_e32 v55, v55
	v_mul_f32_e32 v51, v51, v97
	v_mul_f32_e32 v57, 0xbfb8aa3b, v51
	v_mul_f32_e32 v49, v49, v52
	v_add_f32_e32 v52, 1.0, v55
	v_rcp_f32_e32 v52, v52
	v_exp_f32_e32 v57, v57
	v_and_b32_e32 v53, 0xffff0000, v104
	v_mul_f32_e32 v49, v49, v53
	v_mul_f32_e32 v50, v50, v52
	s_waitcnt vmcnt(17)
	v_fmamk_f32 v52, v106, 0x3a800000, v167
	v_add_f32_e32 v55, 1.0, v57
	v_mul_f32_e32 v53, 0x4b800000, v52
	v_cmp_gt_f32_e32 vcc, s22, v52
	v_rcp_f32_e32 v55, v55
	v_lshlrev_b32_e32 v54, 16, v105
	v_cndmask_b32_e32 v52, v52, v53, vcc
	v_rsq_f32_e32 v52, v52
	v_and_b32_e32 v56, 0xffff0000, v105
	v_mul_f32_e32 v51, v51, v55
	v_cvt_pk_bf16_f32 v48, v48, v49
	v_mul_f32_e32 v50, v50, v54
	v_mul_f32_e32 v51, v51, v56
	v_cvt_pk_bf16_f32 v49, v50, v51
	global_store_dwordx2 v[92:93], v[48:49], off offset:96
	v_mul_f32_e32 v48, 0x45800000, v52
	v_cndmask_b32_e32 v48, v52, v48, vcc
	v_mul_f32_e32 v44, v44, v48
	v_mul_f32_e32 v52, 0xbfb8aa3b, v44
	v_exp_f32_e32 v52, v52
	v_mul_f32_e32 v45, v45, v48
	v_mul_f32_e32 v54, 0xbfb8aa3b, v45
	v_exp_f32_e32 v54, v54
	v_add_f32_e32 v52, 1.0, v52
	v_rcp_f32_e32 v52, v52
	s_waitcnt vmcnt(17)
	v_lshlrev_b32_e32 v49, 16, v94
	v_mul_f32_e32 v46, v46, v48
	v_mul_f32_e32 v47, v47, v48
	v_mul_f32_e32 v44, v44, v52
	v_mul_f32_e32 v44, v44, v49
	v_add_f32_e32 v49, 1.0, v54
	v_mul_f32_e32 v52, 0xbfb8aa3b, v46
	v_mul_f32_e32 v54, 0xbfb8aa3b, v47
	v_rcp_f32_e32 v49, v49
	v_exp_f32_e32 v52, v52
	v_exp_f32_e32 v54, v54
	v_and_b32_e32 v50, 0xffff0000, v94
	v_mul_f32_e32 v45, v45, v49
	v_add_f32_e32 v49, 1.0, v52
	v_add_f32_e32 v52, 1.0, v54
	v_rcp_f32_e32 v52, v52
	v_rcp_f32_e32 v49, v49
	v_and_b32_e32 v53, 0xffff0000, v95
	v_lshlrev_b32_e32 v51, 16, v95
	v_mul_f32_e32 v47, v47, v52
	v_mul_f32_e32 v45, v45, v50
	v_mul_f32_e32 v46, v46, v49
	v_mul_f32_e32 v47, v47, v53
	v_mul_f32_e32 v40, v40, v48
	v_mul_f32_e32 v46, v46, v51
	v_cvt_pk_bf16_f32 v44, v44, v45
	v_cvt_pk_bf16_f32 v45, v46, v47
	v_mul_f32_e32 v47, 0xbfb8aa3b, v40
	v_exp_f32_e32 v47, v47
	v_mul_f32_e32 v41, v41, v48
	v_mul_f32_e32 v50, 0xbfb8aa3b, v41
	v_exp_f32_e32 v50, v50
	v_add_f32_e32 v47, 1.0, v47
	v_rcp_f32_e32 v47, v47
	global_store_dwordx2 v[82:83], v[44:45], off
	s_waitcnt vmcnt(17)
	v_lshlrev_b32_e32 v44, 16, v90
	v_mul_f32_e32 v42, v42, v48
	v_mul_f32_e32 v43, v43, v48
	v_mul_f32_e32 v40, v40, v47
	v_mul_f32_e32 v40, v40, v44
	v_add_f32_e32 v44, 1.0, v50
	v_mul_f32_e32 v47, 0xbfb8aa3b, v42
	v_mul_f32_e32 v50, 0xbfb8aa3b, v43
	v_rcp_f32_e32 v44, v44
	v_exp_f32_e32 v47, v47
	v_exp_f32_e32 v50, v50
	v_and_b32_e32 v45, 0xffff0000, v90
	v_mul_f32_e32 v41, v41, v44
	v_add_f32_e32 v44, 1.0, v47
	v_add_f32_e32 v47, 1.0, v50
	v_rcp_f32_e32 v47, v47
	v_rcp_f32_e32 v44, v44
	v_and_b32_e32 v49, 0xffff0000, v91
	v_lshlrev_b32_e32 v46, 16, v91
	v_mul_f32_e32 v43, v43, v47
	v_mul_f32_e32 v41, v41, v45
	v_mul_f32_e32 v42, v42, v44
	v_mul_f32_e32 v43, v43, v49
	v_mul_f32_e32 v36, v36, v48
	v_mul_f32_e32 v42, v42, v46
	v_cvt_pk_bf16_f32 v40, v40, v41
	v_cvt_pk_bf16_f32 v41, v42, v43
	v_mul_f32_e32 v43, 0xbfb8aa3b, v36
	v_exp_f32_e32 v43, v43
	v_mul_f32_e32 v37, v37, v48
	v_mul_f32_e32 v45, 0xbfb8aa3b, v37
	v_exp_f32_e32 v45, v45
	v_add_f32_e32 v43, 1.0, v43
	v_rcp_f32_e32 v43, v43
	global_store_dwordx2 v[82:83], v[40:41], off offset:32
	s_waitcnt vmcnt(17)
	v_lshlrev_b32_e32 v40, 16, v88
	v_mul_f32_e32 v38, v38, v48
	v_mul_f32_e32 v39, v39, v48
	v_mul_f32_e32 v36, v36, v43
	v_mul_f32_e32 v36, v36, v40
	v_add_f32_e32 v40, 1.0, v45
	v_mul_f32_e32 v43, 0xbfb8aa3b, v38
	v_mul_f32_e32 v45, 0xbfb8aa3b, v39
	v_rcp_f32_e32 v40, v40
	v_exp_f32_e32 v43, v43
	v_exp_f32_e32 v45, v45
	v_and_b32_e32 v41, 0xffff0000, v88
	v_mul_f32_e32 v37, v37, v40
	v_add_f32_e32 v40, 1.0, v43
	v_add_f32_e32 v43, 1.0, v45
	v_rcp_f32_e32 v43, v43
	v_rcp_f32_e32 v40, v40
	v_and_b32_e32 v44, 0xffff0000, v89
	v_lshlrev_b32_e32 v42, 16, v89
	v_mul_f32_e32 v39, v39, v43
	v_mul_f32_e32 v37, v37, v41
	v_mul_f32_e32 v38, v38, v40
	v_mul_f32_e32 v39, v39, v44
	v_mul_f32_e32 v32, v32, v48
	v_mul_f32_e32 v38, v38, v42
	v_cvt_pk_bf16_f32 v36, v36, v37
	v_cvt_pk_bf16_f32 v37, v38, v39
	v_mul_f32_e32 v39, 0xbfb8aa3b, v32
	v_exp_f32_e32 v39, v39
	v_mul_f32_e32 v33, v33, v48
	v_mul_f32_e32 v41, 0xbfb8aa3b, v33
	v_exp_f32_e32 v41, v41
	v_add_f32_e32 v39, 1.0, v39
	v_rcp_f32_e32 v39, v39
	global_store_dwordx2 v[82:83], v[36:37], off offset:64
	s_waitcnt vmcnt(17)
	v_lshlrev_b32_e32 v36, 16, v86
	v_mul_f32_e32 v34, v34, v48
	v_mul_f32_e32 v32, v32, v39
	v_mul_f32_e32 v32, v32, v36
	v_add_f32_e32 v36, 1.0, v41
	v_mul_f32_e32 v39, 0xbfb8aa3b, v34
	v_rcp_f32_e32 v36, v36
	v_exp_f32_e32 v39, v39
	v_mul_f32_e32 v35, v35, v48
	v_mul_f32_e32 v41, 0xbfb8aa3b, v35
	v_mul_f32_e32 v33, v33, v36
	v_add_f32_e32 v36, 1.0, v39
	v_rcp_f32_e32 v36, v36
	v_exp_f32_e32 v41, v41
	v_and_b32_e32 v37, 0xffff0000, v86
	v_mul_f32_e32 v33, v33, v37
	v_mul_f32_e32 v34, v34, v36
	s_waitcnt vmcnt(16)
	v_fmamk_f32 v36, v107, 0x3a800000, v167
	v_add_f32_e32 v39, 1.0, v41
	v_mul_f32_e32 v37, 0x4b800000, v36
	v_cmp_gt_f32_e32 vcc, s22, v36
	v_rcp_f32_e32 v39, v39
	v_lshlrev_b32_e32 v38, 16, v87
	v_cndmask_b32_e32 v36, v36, v37, vcc
	v_rsq_f32_e32 v36, v36
	v_and_b32_e32 v40, 0xffff0000, v87
	v_mul_f32_e32 v35, v35, v39
	v_cvt_pk_bf16_f32 v32, v32, v33
	v_mul_f32_e32 v34, v34, v38
	v_mul_f32_e32 v35, v35, v40
	v_cvt_pk_bf16_f32 v33, v34, v35
	global_store_dwordx2 v[82:83], v[32:33], off offset:96
	v_mul_f32_e32 v32, 0x45800000, v36
	v_cndmask_b32_e32 v32, v36, v32, vcc
	v_mul_f32_e32 v28, v28, v32
	v_mul_f32_e32 v36, 0xbfb8aa3b, v28
	v_exp_f32_e32 v36, v36
	v_mul_f32_e32 v29, v29, v32
	v_mul_f32_e32 v38, 0xbfb8aa3b, v29
	v_exp_f32_e32 v38, v38
	v_add_f32_e32 v36, 1.0, v36
	v_rcp_f32_e32 v36, v36
	s_waitcnt vmcnt(16)
	v_lshlrev_b32_e32 v33, 16, v84
	v_mul_f32_e32 v30, v30, v32
	v_mul_f32_e32 v31, v31, v32
	v_mul_f32_e32 v28, v28, v36
	v_mul_f32_e32 v28, v28, v33
	v_add_f32_e32 v33, 1.0, v38
	v_mul_f32_e32 v36, 0xbfb8aa3b, v30
	v_mul_f32_e32 v38, 0xbfb8aa3b, v31
	v_rcp_f32_e32 v33, v33
	v_exp_f32_e32 v36, v36
	v_exp_f32_e32 v38, v38
	v_and_b32_e32 v34, 0xffff0000, v84
	v_mul_f32_e32 v29, v29, v33
	v_add_f32_e32 v33, 1.0, v36
	v_add_f32_e32 v36, 1.0, v38
	v_rcp_f32_e32 v36, v36
	v_rcp_f32_e32 v33, v33
	v_and_b32_e32 v37, 0xffff0000, v85
	v_lshlrev_b32_e32 v35, 16, v85
	v_mul_f32_e32 v31, v31, v36
	v_mul_f32_e32 v29, v29, v34
	v_mul_f32_e32 v30, v30, v33
	v_mul_f32_e32 v31, v31, v37
	v_mul_f32_e32 v24, v24, v32
	v_mul_f32_e32 v30, v30, v35
	v_cvt_pk_bf16_f32 v28, v28, v29
	v_cvt_pk_bf16_f32 v29, v30, v31
	v_mul_f32_e32 v31, 0xbfb8aa3b, v24
	v_exp_f32_e32 v31, v31
	v_mul_f32_e32 v25, v25, v32
	v_mul_f32_e32 v34, 0xbfb8aa3b, v25
	v_exp_f32_e32 v34, v34
	v_add_f32_e32 v31, 1.0, v31
	v_rcp_f32_e32 v31, v31
	global_store_dwordx2 v[72:73], v[28:29], off
	s_waitcnt vmcnt(16)
	v_lshlrev_b32_e32 v28, 16, v80
	v_mul_f32_e32 v26, v26, v32
	v_mul_f32_e32 v27, v27, v32
	v_mul_f32_e32 v24, v24, v31
	v_mul_f32_e32 v24, v24, v28
	v_add_f32_e32 v28, 1.0, v34
	v_mul_f32_e32 v31, 0xbfb8aa3b, v26
	v_mul_f32_e32 v34, 0xbfb8aa3b, v27
	v_rcp_f32_e32 v28, v28
	v_exp_f32_e32 v31, v31
	v_exp_f32_e32 v34, v34
	v_and_b32_e32 v29, 0xffff0000, v80
	v_mul_f32_e32 v25, v25, v28
	v_add_f32_e32 v28, 1.0, v31
	v_add_f32_e32 v31, 1.0, v34
	v_rcp_f32_e32 v31, v31
	v_rcp_f32_e32 v28, v28
	v_and_b32_e32 v33, 0xffff0000, v81
	v_lshlrev_b32_e32 v30, 16, v81
	v_mul_f32_e32 v27, v27, v31
	v_mul_f32_e32 v25, v25, v29
	v_mul_f32_e32 v26, v26, v28
	v_mul_f32_e32 v27, v27, v33
	v_mul_f32_e32 v20, v20, v32
	v_mul_f32_e32 v26, v26, v30
	v_cvt_pk_bf16_f32 v24, v24, v25
	v_cvt_pk_bf16_f32 v25, v26, v27
	v_mul_f32_e32 v27, 0xbfb8aa3b, v20
	v_exp_f32_e32 v27, v27
	v_mul_f32_e32 v21, v21, v32
	v_mul_f32_e32 v29, 0xbfb8aa3b, v21
	v_exp_f32_e32 v29, v29
	v_add_f32_e32 v27, 1.0, v27
	v_rcp_f32_e32 v27, v27
	global_store_dwordx2 v[72:73], v[24:25], off offset:32
	s_waitcnt vmcnt(16)
	v_lshlrev_b32_e32 v24, 16, v78
	v_mul_f32_e32 v22, v22, v32
	v_mul_f32_e32 v23, v23, v32
	v_mul_f32_e32 v20, v20, v27
	v_mul_f32_e32 v20, v20, v24
	v_add_f32_e32 v24, 1.0, v29
	v_mul_f32_e32 v27, 0xbfb8aa3b, v22
	v_mul_f32_e32 v29, 0xbfb8aa3b, v23
	v_rcp_f32_e32 v24, v24
	v_exp_f32_e32 v27, v27
	v_exp_f32_e32 v29, v29
	v_and_b32_e32 v25, 0xffff0000, v78
	v_mul_f32_e32 v21, v21, v24
	v_add_f32_e32 v24, 1.0, v27
	v_add_f32_e32 v27, 1.0, v29
	v_rcp_f32_e32 v27, v27
	v_rcp_f32_e32 v24, v24
	v_and_b32_e32 v28, 0xffff0000, v79
	v_lshlrev_b32_e32 v26, 16, v79
	v_mul_f32_e32 v23, v23, v27
	v_mul_f32_e32 v21, v21, v25
	v_mul_f32_e32 v22, v22, v24
	v_mul_f32_e32 v23, v23, v28
	v_mul_f32_e32 v16, v16, v32
	v_mul_f32_e32 v22, v22, v26
	v_cvt_pk_bf16_f32 v20, v20, v21
	v_cvt_pk_bf16_f32 v21, v22, v23
	v_mul_f32_e32 v23, 0xbfb8aa3b, v16
	v_exp_f32_e32 v23, v23
	v_mul_f32_e32 v17, v17, v32
	v_mul_f32_e32 v25, 0xbfb8aa3b, v17
	v_exp_f32_e32 v25, v25
	v_add_f32_e32 v23, 1.0, v23
	v_rcp_f32_e32 v23, v23
	global_store_dwordx2 v[72:73], v[20:21], off offset:64
	s_waitcnt vmcnt(16)
	v_lshlrev_b32_e32 v20, 16, v76
	v_mul_f32_e32 v18, v18, v32
	v_mul_f32_e32 v16, v16, v23
	v_mul_f32_e32 v16, v16, v20
	v_add_f32_e32 v20, 1.0, v25
	v_mul_f32_e32 v23, 0xbfb8aa3b, v18
	v_rcp_f32_e32 v20, v20
	v_exp_f32_e32 v23, v23
	v_mul_f32_e32 v19, v19, v32
	v_mul_f32_e32 v25, 0xbfb8aa3b, v19
	v_mul_f32_e32 v17, v17, v20
	v_add_f32_e32 v20, 1.0, v23
	v_rcp_f32_e32 v20, v20
	v_exp_f32_e32 v25, v25
	v_and_b32_e32 v21, 0xffff0000, v76
	v_mul_f32_e32 v17, v17, v21
	v_mul_f32_e32 v18, v18, v20
	s_waitcnt vmcnt(15)
	v_fmamk_f32 v20, v96, 0x3a800000, v167
	v_add_f32_e32 v23, 1.0, v25
	v_mul_f32_e32 v21, 0x4b800000, v20
	v_cmp_gt_f32_e32 vcc, s22, v20
	v_rcp_f32_e32 v23, v23
	v_lshlrev_b32_e32 v22, 16, v77
	v_cndmask_b32_e32 v20, v20, v21, vcc
	v_rsq_f32_e32 v20, v20
	v_and_b32_e32 v24, 0xffff0000, v77
	v_mul_f32_e32 v19, v19, v23
	v_cvt_pk_bf16_f32 v16, v16, v17
	v_mul_f32_e32 v18, v18, v22
	v_mul_f32_e32 v19, v19, v24
	v_cvt_pk_bf16_f32 v17, v18, v19
	global_store_dwordx2 v[72:73], v[16:17], off offset:96
	v_mul_f32_e32 v16, 0x45800000, v20
	v_cndmask_b32_e32 v16, v20, v16, vcc
	v_mul_f32_e32 v12, v12, v16
	v_mul_f32_e32 v20, 0xbfb8aa3b, v12
	v_exp_f32_e32 v20, v20
	v_mul_f32_e32 v13, v13, v16
	v_mul_f32_e32 v22, 0xbfb8aa3b, v13
	v_exp_f32_e32 v22, v22
	v_add_f32_e32 v20, 1.0, v20
	v_rcp_f32_e32 v20, v20
	s_waitcnt vmcnt(15)
	v_lshlrev_b32_e32 v17, 16, v74
	v_mul_f32_e32 v14, v14, v16
	v_mul_f32_e32 v15, v15, v16
	v_mul_f32_e32 v12, v12, v20
	v_mul_f32_e32 v12, v12, v17
	v_add_f32_e32 v17, 1.0, v22
	v_mul_f32_e32 v20, 0xbfb8aa3b, v14
	v_mul_f32_e32 v22, 0xbfb8aa3b, v15
	v_rcp_f32_e32 v17, v17
	v_exp_f32_e32 v20, v20
	v_exp_f32_e32 v22, v22
	v_and_b32_e32 v18, 0xffff0000, v74
	v_mul_f32_e32 v13, v13, v17
	v_add_f32_e32 v17, 1.0, v20
	v_add_f32_e32 v20, 1.0, v22
	v_rcp_f32_e32 v20, v20
	v_rcp_f32_e32 v17, v17
	v_and_b32_e32 v21, 0xffff0000, v75
	v_lshlrev_b32_e32 v19, 16, v75
	v_mul_f32_e32 v15, v15, v20
	v_mul_f32_e32 v13, v13, v18
	v_mul_f32_e32 v14, v14, v17
	v_mul_f32_e32 v15, v15, v21
	v_mul_f32_e32 v8, v8, v16
	v_mul_f32_e32 v14, v14, v19
	v_cvt_pk_bf16_f32 v12, v12, v13
	v_cvt_pk_bf16_f32 v13, v14, v15
	v_mul_f32_e32 v15, 0xbfb8aa3b, v8
	v_exp_f32_e32 v15, v15
	v_mul_f32_e32 v9, v9, v16
	v_mul_f32_e32 v18, 0xbfb8aa3b, v9
	v_exp_f32_e32 v18, v18
	v_add_f32_e32 v15, 1.0, v15
	v_rcp_f32_e32 v15, v15
	global_store_dwordx2 v[64:65], v[12:13], off
	s_waitcnt vmcnt(15)
	v_lshlrev_b32_e32 v12, 16, v70
	v_mul_f32_e32 v10, v10, v16
	v_mul_f32_e32 v11, v11, v16
	v_mul_f32_e32 v8, v8, v15
	v_mul_f32_e32 v8, v8, v12
	v_add_f32_e32 v12, 1.0, v18
	v_mul_f32_e32 v15, 0xbfb8aa3b, v10
	v_mul_f32_e32 v18, 0xbfb8aa3b, v11
	v_rcp_f32_e32 v12, v12
	v_exp_f32_e32 v15, v15
	v_exp_f32_e32 v18, v18
	v_and_b32_e32 v13, 0xffff0000, v70
	v_mul_f32_e32 v9, v9, v12
	v_add_f32_e32 v12, 1.0, v15
	v_add_f32_e32 v15, 1.0, v18
	v_rcp_f32_e32 v15, v15
	v_rcp_f32_e32 v12, v12
	v_and_b32_e32 v17, 0xffff0000, v71
	v_lshlrev_b32_e32 v14, 16, v71
	v_mul_f32_e32 v11, v11, v15
	v_mul_f32_e32 v9, v9, v13
	v_mul_f32_e32 v10, v10, v12
	v_mul_f32_e32 v11, v11, v17
	v_mul_f32_e32 v4, v4, v16
	v_mul_f32_e32 v10, v10, v14
	v_cvt_pk_bf16_f32 v8, v8, v9
	v_cvt_pk_bf16_f32 v9, v10, v11
	v_mul_f32_e32 v11, 0xbfb8aa3b, v4
	v_exp_f32_e32 v11, v11
	v_mul_f32_e32 v5, v5, v16
	v_mul_f32_e32 v13, 0xbfb8aa3b, v5
	v_exp_f32_e32 v13, v13
	v_add_f32_e32 v11, 1.0, v11
	v_rcp_f32_e32 v11, v11
	global_store_dwordx2 v[64:65], v[8:9], off offset:32
	s_waitcnt vmcnt(15)
	v_lshlrev_b32_e32 v8, 16, v68
	v_mul_f32_e32 v6, v6, v16
	v_mul_f32_e32 v7, v7, v16
	v_mul_f32_e32 v4, v4, v11
	v_mul_f32_e32 v4, v4, v8
	v_add_f32_e32 v8, 1.0, v13
	v_mul_f32_e32 v11, 0xbfb8aa3b, v6
	v_mul_f32_e32 v13, 0xbfb8aa3b, v7
	v_rcp_f32_e32 v8, v8
	v_exp_f32_e32 v11, v11
	v_exp_f32_e32 v13, v13
	v_and_b32_e32 v9, 0xffff0000, v68
	v_mul_f32_e32 v5, v5, v8
	v_add_f32_e32 v8, 1.0, v11
	v_add_f32_e32 v11, 1.0, v13
	v_rcp_f32_e32 v11, v11
	v_rcp_f32_e32 v8, v8
	v_and_b32_e32 v12, 0xffff0000, v69
	v_lshlrev_b32_e32 v10, 16, v69
	v_mul_f32_e32 v7, v7, v11
	v_mul_f32_e32 v5, v5, v9
	v_mul_f32_e32 v6, v6, v8
	v_mul_f32_e32 v7, v7, v12
	v_mul_f32_e32 v0, v0, v16
	v_mul_f32_e32 v6, v6, v10
	v_cvt_pk_bf16_f32 v4, v4, v5
	v_cvt_pk_bf16_f32 v5, v6, v7
	v_mul_f32_e32 v7, 0xbfb8aa3b, v0
	v_exp_f32_e32 v7, v7
	v_mul_f32_e32 v1, v1, v16
	v_mul_f32_e32 v9, 0xbfb8aa3b, v1
	v_exp_f32_e32 v9, v9
	v_add_f32_e32 v7, 1.0, v7
	v_rcp_f32_e32 v7, v7
	global_store_dwordx2 v[64:65], v[4:5], off offset:64
	s_waitcnt vmcnt(15)
	v_lshlrev_b32_e32 v4, 16, v66
	v_mul_f32_e32 v2, v2, v16
	v_mul_f32_e32 v3, v3, v16
	v_mul_f32_e32 v0, v0, v7
	v_mul_f32_e32 v0, v0, v4
	v_add_f32_e32 v4, 1.0, v9
	v_mul_f32_e32 v7, 0xbfb8aa3b, v2
	v_mul_f32_e32 v9, 0xbfb8aa3b, v3
	v_rcp_f32_e32 v4, v4
	v_exp_f32_e32 v7, v7
	v_exp_f32_e32 v9, v9
	v_and_b32_e32 v5, 0xffff0000, v66
	v_mul_f32_e32 v1, v1, v4
	v_add_f32_e32 v4, 1.0, v7
	v_add_f32_e32 v7, 1.0, v9
	v_rcp_f32_e32 v4, v4
	v_rcp_f32_e32 v7, v7
	v_lshlrev_b32_e32 v6, 16, v67
	v_and_b32_e32 v8, 0xffff0000, v67
	v_mul_f32_e32 v1, v1, v5
	v_mul_f32_e32 v2, v2, v4
	v_mul_f32_e32 v3, v3, v7
	v_mul_f32_e32 v2, v2, v6
	v_mul_f32_e32 v3, v3, v8
	v_cvt_pk_bf16_f32 v0, v0, v1
	v_cvt_pk_bf16_f32 v1, v2, v3
	global_store_dwordx2 v[64:65], v[0:1], off offset:96
	s_add_i32 s23, s23, s74
	s_cmpk_lt_i32 s23, 0x800
	s_cbranch_scc1 .LBB0_1736
